# plus: CA QK/PV pipelined, NA early K prefetch and no store wait, peeled first K-iteration with relaxed vmcnt, nt on swiglu stores, in-GEMM column-tile rotation
# speedup vs baseline: 1.0087x; 1.0087x over previous
;     __device__ bool next(int i, int& pm, int& pn) const {
;     ...
;         int wgid = (int)L; { const int q = nwg / NXCD, r = nwg % NXCD, xcd = wgid % NXCD, off = wgid / NXCD; wgid = (xcd < r ? xcd * (q + 1) : r * (q + 1) + (xcd - r) * q) + off; }
;         const int nig = WGM * nN, gid = wgid / nig, t = wgid - gid * nig, fm = gid * WGM, gsz = (nM - fm) < WGM ? (nM - fm) : WGM;
;         int pm_, pn_;
;         if (gsz == WGM) { pm_ = fm + (t & (WGM - 1)); pn_ = t >> 3; }
;         else { pm_ = fm + t % gsz; pn_ = t / gsz; }
;         pm = __builtin_amdgcn_readfirstlane(pm_); pn = __builtin_amdgcn_readfirstlane(pn_); return true;
;     __device__ __forceinline__ bool next(int i, pg8::Unit& u) const {
;     ...
;             u.A = A + (size_t)pm * 256 * lda; u.B = B + (size_t)pn * 256 * ldb; u.lda = lda; u.ldb = ldb; u.nt = nt; u.pm = pm; u.pn = pn; u.sub = 0; return true;
.LBB0_139:
	s_andn2_b64 vcc, exec, s[2:3]
	s_cbranch_vccnz .LBB0_141
	s_and_b32 s2, s6, 7
	s_or_b32 s72, s14, s2
	s_ashr_i32 s70, s7, 3
	v_readlane_b32 s2, v244, 42
	s_nop 0
	s_cmp_eq_u32 s2, 0x60
	s_cbranch_scc0 .Lpnrot_skipa
	s_lshr_b32 s2, s14, 3
	s_add_i32 s70, s70, s2
	s_mul_i32 s2, s70, 0xaaab
	s_lshr_b32 s2, s2, 19
	s_mul_i32 s2, s2, 12
	s_sub_i32 s70, s70, s2
.Lpnrot_skipa:
.LBB0_141:
	v_readlane_b32 s2, v244, 39
	s_lshl_b32 s2, s2, 8
	s_mul_hi_i32 s3, s2, s72
	s_mul_i32 s2, s2, s72
	v_readlane_b32 s6, v244, 22
	v_readlane_b32 s7, v244, 23
	s_add_u32 s74, s6, s2
	v_readlane_b32 s2, v244, 37
	s_addc_u32 s75, s7, s3
	s_lshl_b32 s2, s2, 8
	s_mul_hi_i32 s3, s2, s70
	s_mul_i32 s2, s2, s70
	v_readlane_b32 s6, v244, 40
	v_readlane_b32 s7, v244, 41
	s_add_u32 s86, s6, s2
	s_addc_u32 s87, s7, s3
	s_mov_b64 s[2:3], -1

;     __device__ bool next(int i, int& pm, int& pn) const {
;     ...
;         int wgid = (int)L; { const int q = nwg / NXCD, r = nwg % NXCD, xcd = wgid % NXCD, off = wgid / NXCD; wgid = (xcd < r ? xcd * (q + 1) : r * (q + 1) + (xcd - r) * q) + off; }
;         const int nig = WGM * nN, gid = wgid / nig, t = wgid - gid * nig, fm = gid * WGM, gsz = (nM - fm) < WGM ? (nM - fm) : WGM;
;         int pm_, pn_;
;         if (gsz == WGM) { pm_ = fm + (t & (WGM - 1)); pn_ = t >> 3; }
;         else { pm_ = fm + t % gsz; pn_ = t / gsz; }
;         pm = __builtin_amdgcn_readfirstlane(pm_); pn = __builtin_amdgcn_readfirstlane(pn_); return true;
;     __device__ __forceinline__ bool next(int i, pg8::Unit& u) const {
;     ...
;             u.A = A + (size_t)pm * 256 * lda; u.B = B + (size_t)pn * 256 * ldb; u.lda = lda; u.ldb = ldb; u.nt = nt; u.pm = pm; u.pn = pn; u.sub = 0; return true;
.LBB0_167:
	s_andn2_b64 vcc, exec, s[2:3]
	s_cbranch_vccnz .LBB0_169
	s_and_b32 s2, s6, 7
	s_or_b32 s48, s14, s2
	s_ashr_i32 s20, s7, 3
	v_readlane_b32 s2, v244, 42
	s_nop 0
	s_cmp_eq_u32 s2, 0x60
	s_cbranch_scc0 .Lpnrot_skipb
	s_lshr_b32 s2, s14, 3
	s_add_i32 s20, s20, s2
	s_mul_i32 s2, s20, 0xaaab
	s_lshr_b32 s2, s2, 19
	s_mul_i32 s2, s2, 12
	s_sub_i32 s20, s20, s2
.Lpnrot_skipb:
.LBB0_169:
	v_readlane_b32 s3, v244, 56
	s_mul_hi_i32 s2, s3, s48
	s_mul_i32 s3, s3, s48
	v_readlane_b32 s6, v244, 22
	v_readlane_b32 s7, v244, 23
	s_add_u32 s28, s6, s3
	v_readlane_b32 s3, v244, 57
	s_addc_u32 s29, s7, s2
	s_mul_hi_i32 s2, s3, s20
	s_mul_i32 s3, s3, s20
	v_readlane_b32 s6, v244, 40
	v_readlane_b32 s7, v244, 41
	s_add_u32 s58, s6, s3
	s_addc_u32 s59, s7, s2
	s_mov_b32 s63, 0
	s_mov_b64 s[60:61], -1
	v_readlane_b32 s49, v244, 39
	v_readlane_b32 s62, v244, 37
	v_readlane_b32 s64, v244, 38

; template <class Epi, class Sched>
; __device__ __forceinline__ void gemm_phase(LAS unsigned char* lds, const int tid, const Sched& S, const Epi& E) {
;     ...
;         { int t3 = tid; asm volatile("" : "+v"(t3));
;           int R0n, C0n; stage_rc(t3 * 16, R0n, C0n); const int RBn = Epi::PERM ? ((R0n & ~31) + perm32(R0n & 31)) : R0n;
;           noffA = (unsigned)R0n * (unsigned)nlda + (unsigned)C0n * 2u; noffB = (unsigned)RBn * (unsigned)nldb + (unsigned)C0n * 2u; }
;         const int nqA = 64 * nlda, nqB = 64 * nldb, nhA = 128 * nlda, nhB = 128 * nldb;
;         const int nt = cur.nt;
;         for (int t = 0; t < nt; t += 2) {
;     ...
; #pragma unroll
;         for (int a = 0; a < 2; ++a)
; #pragma unroll
;             for (int b = 0; b < 2; ++b)
; #pragma unroll
;                 for (int m = 0; m < 4; ++m)
; #pragma unroll
;                     for (int n = 0; n < 2; ++n) acc[a][b][m][n] = (f32x4){0.f, 0.f, 0.f, 0.f};
.LBB0_171:
	v_mov_b32_e32 v0, v183
	s_and_b64 s[2:3], s[60:61], exec
	v_ashrrev_i32_e32 v3, 31, v0
	v_lshrrev_b32_e32 v3, 26, v3
	v_lshlrev_b32_e32 v2, 4, v0
	v_add_u32_e32 v3, v0, v3
	v_bfe_i32 v0, v0, 27, 1
	v_lshrrev_b32_e32 v0, 22, v0
	v_add_u32_e32 v0, v2, v0
	v_and_b32_e32 v0, 0xfffffc00, v0
	v_sub_u32_e32 v0, v2, v0
	v_lshrrev_b32_e32 v2, 4, v0
	v_bitop3_b32 v0, v2, v0, 32 bitop3:0x6c
	v_ashrrev_i32_e32 v4, 31, v0
	v_ashrrev_i32_e32 v3, 6, v3
	v_lshrrev_b32_e32 v4, 26, v4
	v_lshlrev_b32_e32 v2, 3, v3
	v_add_u32_e32 v4, v0, v4
	v_and_b32_e32 v2, -16, v2
	v_ashrrev_i32_e32 v5, 6, v4
	v_and_b32_e32 v4, 0xc0, v4
	v_add_u32_e32 v2, v5, v2
	v_sub_u32_e32 v0, v0, v4
	v_lshlrev_b32_e32 v3, 5, v3
	v_ashrrev_i16_sdwa v0, v165, sext(v0) dst_sel:DWORD dst_unused:UNUSED_PAD src0_sel:DWORD src1_sel:BYTE_0
	v_lshlrev_b32_e32 v4, 1, v2
	v_lshrrev_b32_e32 v6, 2, v2
	v_and_b32_e32 v5, 3, v5
	s_movk_i32 s2, 0xffe0
	v_and_b32_e32 v3, 32, v3
	v_bfe_i32 v0, v0, 0, 16
	v_and_b32_e32 v4, 24, v4
	v_and_b32_e32 v6, 4, v6
	v_and_or_b32 v5, v2, s2, v5
	s_cselect_b32 s6, s90, s17
	s_cselect_b32 s7, s92, s16
	v_or3_b32 v4, v5, v6, v4
	v_add_lshl_u32 v0, v3, v0, 1
	v_mad_u64_u32 v[130:131], s[2:3], v2, s6, v[0:1]
	v_mad_u64_u32 v[132:133], s[2:3], v4, s7, v[0:1]
	s_lshl_b32 s2, s6, 6
	s_lshl_b32 s18, s7, 6
	s_lshl_b32 s84, s6, 7
	s_lshl_b32 s69, s7, 7
	s_cmp_lt_i32 s37, 1
	s_cbranch_scc1 .LBB0_178
	s_and_b64 s[6:7], s[60:61], exec
	s_cselect_b32 s82, s75, s41
	s_cselect_b32 s48, s74, s40
	s_cselect_b32 s15, s87, s43
	s_cselect_b32 s14, s86, s42
	s_add_i32 s49, s37, -2
	s_ashr_i32 s97, s96, 31
	s_mov_b32 s4, s68
	s_add_u32 s68, s40, s96
	v_mov_b32_e32 v2, 0
	s_addc_u32 s16, s41, s97
	v_mov_b32_e32 v135, v1
	s_ashr_i32 s67, s66, 31
	v_mov_b32_e32 v131, v1
	s_ashr_i32 s3, s2, 31
	s_ashr_i32 s85, s84, 31
	s_mov_b32 s17, 0
	v_mov_b32_e32 v3, v2
	v_mov_b32_e32 v4, v2
	v_mov_b32_e32 v5, v2
	v_mov_b32_e32 v6, v2
	v_mov_b32_e32 v7, v2
	v_mov_b32_e32 v8, v2
	v_mov_b32_e32 v9, v2
	v_mov_b32_e32 v18, v2
	v_mov_b32_e32 v19, v2
	v_mov_b32_e32 v20, v2
	v_mov_b32_e32 v21, v2
	v_mov_b32_e32 v22, v2
	v_mov_b32_e32 v23, v2
	v_mov_b32_e32 v24, v2
	v_mov_b32_e32 v25, v2
	v_mov_b32_e32 v34, v2
	v_mov_b32_e32 v35, v2
	v_mov_b32_e32 v36, v2
	v_mov_b32_e32 v37, v2
	v_mov_b32_e32 v38, v2
	v_mov_b32_e32 v39, v2
	v_mov_b32_e32 v40, v2
	v_mov_b32_e32 v41, v2
	v_mov_b32_e32 v50, v2
	v_mov_b32_e32 v51, v2
	v_mov_b32_e32 v52, v2
	v_mov_b32_e32 v53, v2
	v_mov_b32_e32 v54, v2
	v_mov_b32_e32 v55, v2
	v_mov_b32_e32 v56, v2
	v_mov_b32_e32 v57, v2
	v_mov_b32_e32 v10, v2
	v_mov_b32_e32 v11, v2
	v_mov_b32_e32 v12, v2
	v_mov_b32_e32 v13, v2
	v_mov_b32_e32 v14, v2
	v_mov_b32_e32 v15, v2
	v_mov_b32_e32 v16, v2
	v_mov_b32_e32 v17, v2
	v_mov_b32_e32 v26, v2
	v_mov_b32_e32 v27, v2
	v_mov_b32_e32 v28, v2
	v_mov_b32_e32 v29, v2
	v_mov_b32_e32 v30, v2
	v_mov_b32_e32 v31, v2
	v_mov_b32_e32 v32, v2
	v_mov_b32_e32 v33, v2
	v_mov_b32_e32 v42, v2
	v_mov_b32_e32 v43, v2
	v_mov_b32_e32 v44, v2
	v_mov_b32_e32 v45, v2
	v_mov_b32_e32 v46, v2
	v_mov_b32_e32 v47, v2
	v_mov_b32_e32 v48, v2
	v_mov_b32_e32 v49, v2
	v_mov_b32_e32 v58, v2
	v_mov_b32_e32 v59, v2
	v_mov_b32_e32 v60, v2
	v_mov_b32_e32 v61, v2
	v_mov_b32_e32 v62, v2
	v_mov_b32_e32 v63, v2
	v_mov_b32_e32 v64, v2
	v_mov_b32_e32 v65, v2
	v_mov_b32_e32 v66, v2
	v_mov_b32_e32 v67, v2
	v_mov_b32_e32 v68, v2
	v_mov_b32_e32 v69, v2
	v_mov_b32_e32 v70, v2
	v_mov_b32_e32 v71, v2
	v_mov_b32_e32 v72, v2
	v_mov_b32_e32 v73, v2
	v_mov_b32_e32 v82, v2
	v_mov_b32_e32 v83, v2
	v_mov_b32_e32 v84, v2
	v_mov_b32_e32 v85, v2
	v_mov_b32_e32 v86, v2
	v_mov_b32_e32 v87, v2
	v_mov_b32_e32 v88, v2
	v_mov_b32_e32 v89, v2
	v_mov_b32_e32 v98, v2
	v_mov_b32_e32 v99, v2
	v_mov_b32_e32 v100, v2
	v_mov_b32_e32 v101, v2
	v_mov_b32_e32 v102, v2
	v_mov_b32_e32 v103, v2
	v_mov_b32_e32 v104, v2
	v_mov_b32_e32 v105, v2
	v_mov_b32_e32 v114, v2
	v_mov_b32_e32 v115, v2
	v_mov_b32_e32 v116, v2
	v_mov_b32_e32 v117, v2
	v_mov_b32_e32 v118, v2
	v_mov_b32_e32 v119, v2
	v_mov_b32_e32 v120, v2
	v_mov_b32_e32 v121, v2
	v_mov_b32_e32 v74, v2
	v_mov_b32_e32 v75, v2
	v_mov_b32_e32 v76, v2
	v_mov_b32_e32 v77, v2
	v_mov_b32_e32 v78, v2
	v_mov_b32_e32 v79, v2
	v_mov_b32_e32 v80, v2
	v_mov_b32_e32 v81, v2
	v_mov_b32_e32 v90, v2
	v_mov_b32_e32 v91, v2
	v_mov_b32_e32 v92, v2
	v_mov_b32_e32 v93, v2
	v_mov_b32_e32 v94, v2
	v_mov_b32_e32 v95, v2
	v_mov_b32_e32 v96, v2
	v_mov_b32_e32 v97, v2
	v_mov_b32_e32 v106, v2
	v_mov_b32_e32 v107, v2
	v_mov_b32_e32 v108, v2
	v_mov_b32_e32 v109, v2
	v_mov_b32_e32 v110, v2
	v_mov_b32_e32 v111, v2
	v_mov_b32_e32 v112, v2
	v_mov_b32_e32 v113, v2
	v_mov_b32_e32 v122, v2
	v_mov_b32_e32 v123, v2
	v_mov_b32_e32 v124, v2
	v_mov_b32_e32 v125, v2
	v_mov_b32_e32 v126, v2
	v_mov_b32_e32 v127, v2
	v_mov_b32_e32 v128, v2
	v_mov_b32_e32 v129, v2
	s_cmp_lt_u32 s89, 2
	s_cbranch_scc1 .LBB0_173
	s_cmp_eq_u32 s5, 1
	s_cbranch_scc1 .Lk0a_head
	s_branch .Lk0b_head

; #define PG8_STAGE(bufoff, gbase, off, q) do { \
;         __builtin_amdgcn_global_load_lds((const unsigned*)((const char*)(gbase) + (off)), (LAS unsigned*)(lds + (bufoff) + ldsw), 16, 0, 0); \
;         __builtin_amdgcn_global_load_lds((const unsigned*)((const char*)(gbase) + (q) + (off)), (LAS unsigned*)(lds + (bufoff) + ldsw + 8192), 16, 0, 0); } while (0)
; #define PG8_LDA(dst, b, h) do { _Pragma("unroll") for (int m = 0; m < 4; ++m) _Pragma("unroll") for (int k = 0; k < 2; ++k) dst[m][k] = *(const LAS bf16x8*)(lds + PG8_SA(b, h) + aoff + m * 2048 + k * 1024); } while (0)
; #define PG8_LDB(dst, b, h) do { _Pragma("unroll") for (int n = 0; n < 2; ++n) _Pragma("unroll") for (int k = 0; k < 2; ++k) dst[n][k] = *(const LAS bf16x8*)(lds + PG8_SB(b, h) + boff + n * 2048 + k * 1024); } while (0)
; #define PG8_MMA(ai, bj, At, Bt) do { __builtin_amdgcn_s_setprio(1); _Pragma("unroll") for (int m = 0; m < 4; ++m) _Pragma("unroll") for (int n = 0; n < 2; ++n) _Pragma("unroll") for (int k = 0; k < 2; ++k) \
;         acc[ai][bj][m][n] = __builtin_amdgcn_mfma_f32_16x16x32_bf16(Bt[n][k], At[m][k], acc[ai][bj][m][n], 0, 0, 0); __builtin_amdgcn_s_setprio(0); } while (0)
; template <class Epi, class Sched>
; __device__ __forceinline__ void gemm_phase(LAS unsigned char* lds, const int tid, const Sched& S, const Epi& E) {
;     ...
;             const bool last = (t == nt - 2);
;             const char* a1 = cA + (size_t)(t + 1) * kstep;
;             const char* a2 = last ? nA : cA + (size_t)(t + 2) * kstep; const char* b2 = last ? nB : cB + (size_t)(t + 2) * kstep;
;             const char* a3 = a2 + kstep; const char* b3 = b2 + kstep;
;             const unsigned oA2 = last ? noffA : offA, oB2 = last ? noffB : offB;
;             const int qA2 = last ? nqA : qA, qB2 = last ? nqB : qB, hA2 = last ? nhA : hA, hB2 = last ? nhB : hB;
;             PG8_LDB(B0, 0, 0); PG8_LDB(B1, 0, 1); PG8_SCHED; PG8_LDA(At, 0, 0); PG8_STAGE(PG8_SA(1, 1), a1 + hA, offA, qA);
;             PG8_WAIT_V(8); PG8_WAIT_L(0); PG8_BAR; PG8_MMA(0, 0, At, B0); PG8_MMA(0, 1, At, B1); PG8_BAR; PG8_SCHED;
;             PG8_LDA(At, 0, 1); PG8_STAGE(PG8_SB(0, 0), b2, oB2, qB2); PG8_STAGE(PG8_SB(0, 1), b2 + hB2, oB2, qB2); PG8_STAGE(PG8_SA(0, 0), a2, oA2, qA2);
;             PG8_WAIT_V(8); PG8_WAIT_L(0); PG8_BAR; PG8_MMA(1, 0, At, B0); PG8_MMA(1, 1, At, B1); PG8_BAR; PG8_SCHED;
.LBB0_177:
	s_mov_b32 s65, 0x13fff
	s_mov_b32 s97, 0x800000
	s_mov_b32 s68, s4
	s_branch .LBB0_179
.Lk0a_head:
	s_cmp_eq_u32 s17, s49
	s_cselect_b64 s[62:63], -1, 0
	s_add_i32 s20, s17, 2
	s_lshl_b64 s[6:7], s[20:21], 7
	s_and_b64 vcc, exec, s[62:63]
	s_mov_b64 s[58:59], s[84:85]
	s_mov_b64 s[64:65], s[2:3]
	v_mov_b64_e32 v[136:137], v[130:131]
	s_mov_b32 s19, s69
	s_mov_b32 s73, s18
	v_mov_b32_e32 v0, v132
	s_mov_b64 s[28:29], s[14:15]
	s_cbranch_vccnz .Lk0a_175
	s_add_u32 s28, s42, s6
	s_addc_u32 s29, s43, s7
	s_mov_b64 s[58:59], s[96:97]
	s_mov_b64 s[64:65], s[66:67]
	v_mov_b64_e32 v[136:137], v[134:135]
	s_mov_b32 s19, s36
	s_mov_b32 s73, s35
	v_mov_b32_e32 v0, v138
.Lk0a_175:
	s_or_b32 vcc_lo, s17, 1
	s_mov_b32 vcc_hi, s21
	s_lshl_b64 s[10:11], vcc, 7
	s_add_u32 s17, s40, s6
	s_addc_u32 vcc_lo, s41, s7
	s_and_b64 s[6:7], exec, s[62:63]
	s_cselect_b32 vcc_hi, s82, vcc_lo
	s_cselect_b32 vcc_lo, s48, s17
	s_add_i32 s17, 0, 0x10000
	v_add_u32_e32 v133, s17, v147
	s_add_i32 s62, 0, 0x14000
	ds_read_b128 v[140:143], v133
	ds_read_b128 v[150:153], v133 offset:1024
	ds_read_b128 v[154:157], v133 offset:2048
	ds_read_b128 v[158:161], v133 offset:3072
	v_add_u32_e32 v133, s62, v147
	ds_read_b128 v[186:189], v133
	ds_read_b128 v[190:193], v133 offset:1024
	ds_read_b128 v[194:197], v133 offset:2048
	ds_read_b128 v[198:201], v133 offset:3072
	s_add_u32 s6, s68, s10
	s_addc_u32 s7, s16, s11
	s_add_i32 m0, s54, 0xc000
	v_lshl_add_u64 v[144:145], s[6:7], 0, v[134:135]
	s_add_u32 s6, s6, s66
	s_addc_u32 s7, s7, s67
	ds_read_b128 v[202:205], v184
	ds_read_b128 v[206:209], v184 offset:1024
	ds_read_b128 v[210:213], v184 offset:2048
	ds_read_b128 v[214:217], v184 offset:3072
	ds_read_b128 v[218:221], v184 offset:4096
	ds_read_b128 v[222:225], v184 offset:5120
	ds_read_b128 v[226:229], v184 offset:6144
	ds_read_b128 v[230:233], v184 offset:7168
	global_load_lds_dwordx4 v[144:145], off
	v_lshl_add_u64 v[144:145], s[6:7], 0, v[134:135]
	s_add_i32 m0, s54, 0xe000
	s_nop 0
	global_load_lds_dwordx4 v[144:145], off
	s_waitcnt vmcnt(16)
	s_waitcnt lgkmcnt(0)
	s_barrier
	s_setprio 1
	s_waitcnt lgkmcnt(0)
	v_mfma_f32_16x16x32_bf16 v[126:129], v[140:143], v[202:205], v[126:129]
	v_mfma_f32_16x16x32_bf16 v[122:125], v[154:157], v[202:205], v[122:125]
	v_mfma_f32_16x16x32_bf16 v[110:113], v[140:143], v[210:213], v[110:113]
	v_mfma_f32_16x16x32_bf16 v[106:109], v[154:157], v[210:213], v[106:109]
	v_mfma_f32_16x16x32_bf16 v[94:97], v[140:143], v[218:221], v[94:97]
	v_mfma_f32_16x16x32_bf16 v[90:93], v[154:157], v[218:221], v[90:93]
	v_mfma_f32_16x16x32_bf16 v[78:81], v[140:143], v[226:229], v[78:81]
	v_mfma_f32_16x16x32_bf16 v[74:77], v[154:157], v[226:229], v[74:77]
	v_mfma_f32_16x16x32_bf16 v[126:129], v[150:153], v[206:209], v[126:129]
	v_mfma_f32_16x16x32_bf16 v[122:125], v[158:161], v[206:209], v[122:125]
	v_mfma_f32_16x16x32_bf16 v[110:113], v[150:153], v[214:217], v[110:113]
	v_mfma_f32_16x16x32_bf16 v[106:109], v[158:161], v[214:217], v[106:109]
	v_mfma_f32_16x16x32_bf16 v[94:97], v[150:153], v[222:225], v[94:97]
	v_mfma_f32_16x16x32_bf16 v[90:93], v[158:161], v[222:225], v[90:93]
	v_mfma_f32_16x16x32_bf16 v[78:81], v[150:153], v[230:233], v[78:81]
	v_mfma_f32_16x16x32_bf16 v[74:77], v[158:161], v[230:233], v[74:77]
	s_setprio 0
	s_setprio 1
	v_mfma_f32_16x16x32_bf16 v[118:121], v[186:189], v[202:205], v[118:121]
	v_mfma_f32_16x16x32_bf16 v[114:117], v[194:197], v[202:205], v[114:117]
	v_mfma_f32_16x16x32_bf16 v[102:105], v[186:189], v[210:213], v[102:105]
	v_mfma_f32_16x16x32_bf16 v[98:101], v[194:197], v[210:213], v[98:101]
	v_mfma_f32_16x16x32_bf16 v[86:89], v[186:189], v[218:221], v[86:89]
	v_mfma_f32_16x16x32_bf16 v[82:85], v[194:197], v[218:221], v[82:85]
	v_mfma_f32_16x16x32_bf16 v[70:73], v[186:189], v[226:229], v[70:73]
	v_mfma_f32_16x16x32_bf16 v[66:69], v[194:197], v[226:229], v[66:69]
	v_mfma_f32_16x16x32_bf16 v[118:121], v[190:193], v[206:209], v[118:121]
	v_mfma_f32_16x16x32_bf16 v[114:117], v[198:201], v[206:209], v[114:117]
	v_mfma_f32_16x16x32_bf16 v[102:105], v[190:193], v[214:217], v[102:105]
	v_mfma_f32_16x16x32_bf16 v[98:101], v[198:201], v[214:217], v[98:101]
	v_mfma_f32_16x16x32_bf16 v[86:89], v[190:193], v[222:225], v[86:89]
	v_mfma_f32_16x16x32_bf16 v[82:85], v[198:201], v[222:225], v[82:85]
	v_mfma_f32_16x16x32_bf16 v[70:73], v[190:193], v[230:233], v[70:73]
	v_mfma_f32_16x16x32_bf16 v[66:69], v[198:201], v[230:233], v[66:69]
	s_setprio 0
	s_barrier
	s_add_i32 s10, s17, s47
	s_ashr_i32 s11, s73, 31
	s_mov_b32 m0, s10
	s_add_u32 s6, s28, s73
	ds_read_b128 v[202:205], v184 offset:16384
	ds_read_b128 v[206:209], v184 offset:17408
	ds_read_b128 v[210:213], v184 offset:18432
	ds_read_b128 v[214:217], v184 offset:19456
	ds_read_b128 v[218:221], v184 offset:20480
	ds_read_b128 v[222:225], v184 offset:21504
	ds_read_b128 v[226:229], v184 offset:22528
	ds_read_b128 v[230:233], v184 offset:23552
	global_load_lds_dwordx4 v0, s[28:29]
	s_addc_u32 s7, s29, s11
	s_add_i32 m0, s10, 0x2000
	v_lshl_add_u64 v[162:163], s[6:7], 0, v[0:1]
	global_load_lds_dwordx4 v0, s[6:7]
	s_ashr_i32 s7, s19, 31
	s_add_u32 s6, s28, s19
	s_addc_u32 s7, s29, s7
	s_add_i32 s10, s62, s47
	s_mov_b32 m0, s10
	v_lshl_add_u64 v[234:235], s[6:7], 0, v[0:1]
	global_load_lds_dwordx4 v0, s[6:7]
	s_add_u32 s6, s6, s73
	s_addc_u32 s7, s7, s11
	s_add_i32 m0, s10, 0x2000
	v_lshl_add_u64 v[236:237], s[6:7], 0, v[0:1]
	global_load_lds_dwordx4 v0, s[6:7]
	s_add_u32 s6, vcc_lo, s64
	v_lshl_add_u64 v[238:239], vcc, 0, v[136:137]
	s_mov_b32 m0, s54
	s_addc_u32 s7, vcc_hi, s65
	global_load_lds_dwordx4 v[238:239], off
	v_lshl_add_u64 v[240:241], s[6:7], 0, v[136:137]
	s_mov_b32 m0, s55
	v_lshl_add_u64 v[144:145], s[28:29], 0, v[0:1]
	global_load_lds_dwordx4 v[240:241], off
	s_waitcnt vmcnt(16)
	s_waitcnt lgkmcnt(0)
	s_barrier
; #define PG8_STAGE(bufoff, gbase, off, q) do { \
;         __builtin_amdgcn_global_load_lds((const unsigned*)((const char*)(gbase) + (off)), (LAS unsigned*)(lds + (bufoff) + ldsw), 16, 0, 0); \
;         __builtin_amdgcn_global_load_lds((const unsigned*)((const char*)(gbase) + (q) + (off)), (LAS unsigned*)(lds + (bufoff) + ldsw + 8192), 16, 0, 0); } while (0)
; #define PG8_LDA(dst, b, h) do { _Pragma("unroll") for (int m = 0; m < 4; ++m) _Pragma("unroll") for (int k = 0; k < 2; ++k) dst[m][k] = *(const LAS bf16x8*)(lds + PG8_SA(b, h) + aoff + m * 2048 + k * 1024); } while (0)
; #define PG8_LDB(dst, b, h) do { _Pragma("unroll") for (int n = 0; n < 2; ++n) _Pragma("unroll") for (int k = 0; k < 2; ++k) dst[n][k] = *(const LAS bf16x8*)(lds + PG8_SB(b, h) + boff + n * 2048 + k * 1024); } while (0)
; #define PG8_MMA(ai, bj, At, Bt) do { __builtin_amdgcn_s_setprio(1); _Pragma("unroll") for (int m = 0; m < 4; ++m) _Pragma("unroll") for (int n = 0; n < 2; ++n) _Pragma("unroll") for (int k = 0; k < 2; ++k) \
;         acc[ai][bj][m][n] = __builtin_amdgcn_mfma_f32_16x16x32_bf16(Bt[n][k], At[m][k], acc[ai][bj][m][n], 0, 0, 0); __builtin_amdgcn_s_setprio(0); } while (0)
; #define PG8_WAIT_V(n) asm volatile("s_waitcnt vmcnt(" #n ")" ::: "memory")
; #define PG8_WAIT_L(n) asm volatile("s_waitcnt lgkmcnt(" #n ")" ::: "memory")
; #define PG8_BAR __builtin_amdgcn_s_barrier()
; #define PG8_SCHED __builtin_amdgcn_sched_barrier(0)
; template <class Epi, class Sched>
; __device__ __forceinline__ void gemm_phase(LAS unsigned char* lds, const int tid, const Sched& S, const Epi& E) {
;     ...
;             PG8_WAIT_V(8); PG8_WAIT_L(0); PG8_BAR; PG8_MMA(1, 0, At, B0); PG8_MMA(1, 1, At, B1); PG8_BAR; PG8_SCHED;
;             PG8_LDB(B0, 1, 0); PG8_LDB(B1, 1, 1); PG8_SCHED; PG8_LDA(At, 1, 0); PG8_STAGE(PG8_SA(0, 1), a2 + hA2, oA2, qA2);
;             PG8_WAIT_V(8); PG8_WAIT_L(0); PG8_BAR; PG8_MMA(0, 0, At, B0); PG8_MMA(0, 1, At, B1); PG8_BAR; PG8_SCHED;
	s_setprio 1
	s_waitcnt lgkmcnt(0)
	v_mfma_f32_16x16x32_bf16 v[62:65], v[140:143], v[202:205], v[62:65]
	v_mfma_f32_16x16x32_bf16 v[58:61], v[154:157], v[202:205], v[58:61]
	v_mfma_f32_16x16x32_bf16 v[46:49], v[140:143], v[210:213], v[46:49]
	v_mfma_f32_16x16x32_bf16 v[42:45], v[154:157], v[210:213], v[42:45]
	v_mfma_f32_16x16x32_bf16 v[30:33], v[140:143], v[218:221], v[30:33]
	v_mfma_f32_16x16x32_bf16 v[26:29], v[154:157], v[218:221], v[26:29]
	v_mfma_f32_16x16x32_bf16 v[14:17], v[140:143], v[226:229], v[14:17]
	v_mfma_f32_16x16x32_bf16 v[10:13], v[154:157], v[226:229], v[10:13]
	v_mfma_f32_16x16x32_bf16 v[62:65], v[150:153], v[206:209], v[62:65]
	v_mfma_f32_16x16x32_bf16 v[58:61], v[158:161], v[206:209], v[58:61]
	v_mfma_f32_16x16x32_bf16 v[46:49], v[150:153], v[214:217], v[46:49]
	v_mfma_f32_16x16x32_bf16 v[42:45], v[158:161], v[214:217], v[42:45]
	v_mfma_f32_16x16x32_bf16 v[30:33], v[150:153], v[222:225], v[30:33]
	v_mfma_f32_16x16x32_bf16 v[26:29], v[158:161], v[222:225], v[26:29]
	v_mfma_f32_16x16x32_bf16 v[14:17], v[150:153], v[230:233], v[14:17]
	v_mfma_f32_16x16x32_bf16 v[10:13], v[158:161], v[230:233], v[10:13]
	s_setprio 0
	s_setprio 1
	v_mfma_f32_16x16x32_bf16 v[54:57], v[186:189], v[202:205], v[54:57]
	v_mfma_f32_16x16x32_bf16 v[50:53], v[194:197], v[202:205], v[50:53]
	v_mfma_f32_16x16x32_bf16 v[38:41], v[186:189], v[210:213], v[38:41]
	v_mfma_f32_16x16x32_bf16 v[34:37], v[194:197], v[210:213], v[34:37]
	v_mfma_f32_16x16x32_bf16 v[22:25], v[186:189], v[218:221], v[22:25]
	v_mfma_f32_16x16x32_bf16 v[18:21], v[194:197], v[218:221], v[18:21]
	v_mfma_f32_16x16x32_bf16 v[6:9], v[186:189], v[226:229], v[6:9]
	v_mfma_f32_16x16x32_bf16 v[2:5], v[194:197], v[226:229], v[2:5]
	v_mfma_f32_16x16x32_bf16 v[54:57], v[190:193], v[206:209], v[54:57]
	v_mfma_f32_16x16x32_bf16 v[50:53], v[198:201], v[206:209], v[50:53]
	v_mfma_f32_16x16x32_bf16 v[38:41], v[190:193], v[214:217], v[38:41]
	v_mfma_f32_16x16x32_bf16 v[34:37], v[198:201], v[214:217], v[34:37]
	v_mfma_f32_16x16x32_bf16 v[22:25], v[190:193], v[222:225], v[22:25]
	v_mfma_f32_16x16x32_bf16 v[18:21], v[198:201], v[222:225], v[18:21]
	v_mfma_f32_16x16x32_bf16 v[6:9], v[190:193], v[230:233], v[6:9]
	v_mfma_f32_16x16x32_bf16 v[2:5], v[198:201], v[230:233], v[2:5]
	s_setprio 0
	s_barrier
	s_add_i32 s10, 0, 0x18000
	v_add_u32_e32 v0, s10, v147
	s_add_i32 s11, 0, 0x1c000
	ds_read_b128 v[140:143], v0
	ds_read_b128 v[150:153], v0 offset:1024
	ds_read_b128 v[154:157], v0 offset:2048
	ds_read_b128 v[158:161], v0 offset:3072
	v_add_u32_e32 v0, s11, v147
	ds_read_b128 v[186:189], v0
	ds_read_b128 v[190:193], v0 offset:1024
	ds_read_b128 v[194:197], v0 offset:2048
	ds_read_b128 v[198:201], v0 offset:3072
	s_add_u32 s6, vcc_lo, s58
	s_addc_u32 s7, vcc_hi, s59
	v_lshl_add_u64 v[242:243], s[6:7], 0, v[136:137]
	s_add_u32 s6, s6, s64
	s_mov_b32 m0, s91
	s_addc_u32 s7, s7, s65
	ds_read_b128 v[202:205], v184 offset:32768
	ds_read_b128 v[206:209], v184 offset:33792
	ds_read_b128 v[210:213], v184 offset:34816
	ds_read_b128 v[214:217], v184 offset:35840
	ds_read_b128 v[218:221], v184 offset:36864
	ds_read_b128 v[222:225], v184 offset:37888
	ds_read_b128 v[226:229], v184 offset:38912
	ds_read_b128 v[230:233], v184 offset:39936
	global_load_lds_dwordx4 v[242:243], off
	v_lshl_add_u64 v[136:137], s[6:7], 0, v[136:137]
	s_mov_b32 m0, s93
	s_nop 0
	global_load_lds_dwordx4 v[136:137], off
	s_waitcnt vmcnt(8)
	s_waitcnt lgkmcnt(0)
	s_barrier
	s_setprio 1
	s_waitcnt lgkmcnt(0)
	v_mfma_f32_16x16x32_bf16 v[126:129], v[140:143], v[202:205], v[126:129]
	v_mfma_f32_16x16x32_bf16 v[122:125], v[154:157], v[202:205], v[122:125]
	v_mfma_f32_16x16x32_bf16 v[110:113], v[140:143], v[210:213], v[110:113]
	v_mfma_f32_16x16x32_bf16 v[106:109], v[154:157], v[210:213], v[106:109]
	v_mfma_f32_16x16x32_bf16 v[94:97], v[140:143], v[218:221], v[94:97]
	v_mfma_f32_16x16x32_bf16 v[90:93], v[154:157], v[218:221], v[90:93]
	v_mfma_f32_16x16x32_bf16 v[78:81], v[140:143], v[226:229], v[78:81]
	v_mfma_f32_16x16x32_bf16 v[74:77], v[154:157], v[226:229], v[74:77]
	v_mfma_f32_16x16x32_bf16 v[126:129], v[150:153], v[206:209], v[126:129]
	v_mfma_f32_16x16x32_bf16 v[122:125], v[158:161], v[206:209], v[122:125]
	v_mfma_f32_16x16x32_bf16 v[110:113], v[150:153], v[214:217], v[110:113]
	v_mfma_f32_16x16x32_bf16 v[106:109], v[158:161], v[214:217], v[106:109]
	v_mfma_f32_16x16x32_bf16 v[94:97], v[150:153], v[222:225], v[94:97]
	v_mfma_f32_16x16x32_bf16 v[90:93], v[158:161], v[222:225], v[90:93]
	v_mfma_f32_16x16x32_bf16 v[78:81], v[150:153], v[230:233], v[78:81]
	v_mfma_f32_16x16x32_bf16 v[74:77], v[158:161], v[230:233], v[74:77]
	s_setprio 0
	s_setprio 1
	v_mfma_f32_16x16x32_bf16 v[118:121], v[186:189], v[202:205], v[118:121]
	v_mfma_f32_16x16x32_bf16 v[114:117], v[194:197], v[202:205], v[114:117]
	v_mfma_f32_16x16x32_bf16 v[102:105], v[186:189], v[210:213], v[102:105]
	v_mfma_f32_16x16x32_bf16 v[98:101], v[194:197], v[210:213], v[98:101]
	v_mfma_f32_16x16x32_bf16 v[86:89], v[186:189], v[218:221], v[86:89]
	v_mfma_f32_16x16x32_bf16 v[82:85], v[194:197], v[218:221], v[82:85]
	v_mfma_f32_16x16x32_bf16 v[70:73], v[186:189], v[226:229], v[70:73]
	v_mfma_f32_16x16x32_bf16 v[66:69], v[194:197], v[226:229], v[66:69]
	v_mfma_f32_16x16x32_bf16 v[118:121], v[190:193], v[206:209], v[118:121]
	v_mfma_f32_16x16x32_bf16 v[114:117], v[198:201], v[206:209], v[114:117]
	v_mfma_f32_16x16x32_bf16 v[102:105], v[190:193], v[214:217], v[102:105]
	v_mfma_f32_16x16x32_bf16 v[98:101], v[198:201], v[214:217], v[98:101]
	v_mfma_f32_16x16x32_bf16 v[86:89], v[190:193], v[222:225], v[86:89]
	v_mfma_f32_16x16x32_bf16 v[82:85], v[198:201], v[222:225], v[82:85]
	v_mfma_f32_16x16x32_bf16 v[70:73], v[190:193], v[230:233], v[70:73]
	v_mfma_f32_16x16x32_bf16 v[66:69], v[198:201], v[230:233], v[66:69]
	s_setprio 0
	s_barrier
; #define PG8_STAGE(bufoff, gbase, off, q) do { \
;         __builtin_amdgcn_global_load_lds((const unsigned*)((const char*)(gbase) + (off)), (LAS unsigned*)(lds + (bufoff) + ldsw), 16, 0, 0); \
;         __builtin_amdgcn_global_load_lds((const unsigned*)((const char*)(gbase) + (q) + (off)), (LAS unsigned*)(lds + (bufoff) + ldsw + 8192), 16, 0, 0); } while (0)
; #define PG8_LDA(dst, b, h) do { _Pragma("unroll") for (int m = 0; m < 4; ++m) _Pragma("unroll") for (int k = 0; k < 2; ++k) dst[m][k] = *(const LAS bf16x8*)(lds + PG8_SA(b, h) + aoff + m * 2048 + k * 1024); } while (0)
; #define PG8_MMA(ai, bj, At, Bt) do { __builtin_amdgcn_s_setprio(1); _Pragma("unroll") for (int m = 0; m < 4; ++m) _Pragma("unroll") for (int n = 0; n < 2; ++n) _Pragma("unroll") for (int k = 0; k < 2; ++k) \
;         acc[ai][bj][m][n] = __builtin_amdgcn_mfma_f32_16x16x32_bf16(Bt[n][k], At[m][k], acc[ai][bj][m][n], 0, 0, 0); __builtin_amdgcn_s_setprio(0); } while (0)
; #define PG8_WAIT_V(n) asm volatile("s_waitcnt vmcnt(" #n ")" ::: "memory")
; #define PG8_WAIT_L(n) asm volatile("s_waitcnt lgkmcnt(" #n ")" ::: "memory")
; #define PG8_BAR __builtin_amdgcn_s_barrier()
; #define PG8_SCHED __builtin_amdgcn_sched_barrier(0)
; template <class Epi, class Sched>
; __device__ __forceinline__ void gemm_phase(LAS unsigned char* lds, const int tid, const Sched& S, const Epi& E) {
;     ...
;             PG8_LDA(At, 1, 1); PG8_STAGE(PG8_SB(1, 0), b3, oB2, qB2); PG8_STAGE(PG8_SB(1, 1), b3 + hB2, oB2, qB2); PG8_STAGE(PG8_SA(1, 0), a3, oA2, qA2);
;             PG8_WAIT_V(8); PG8_WAIT_L(0); PG8_BAR; PG8_MMA(1, 0, At, B0); PG8_MMA(1, 1, At, B1); PG8_BAR; PG8_SCHED;
;         }
	s_add_i32 s6, s10, s47
	v_lshl_add_u64 v[136:137], v[144:145], 0, s[26:27]
	s_mov_b32 m0, s6
	ds_read_b128 v[202:205], v184 offset:49152
	ds_read_b128 v[206:209], v184 offset:50176
	ds_read_b128 v[210:213], v184 offset:51200
	ds_read_b128 v[214:217], v184 offset:52224
	ds_read_b128 v[218:221], v184 offset:53248
	ds_read_b128 v[222:225], v184 offset:54272
	ds_read_b128 v[226:229], v184 offset:55296
	ds_read_b128 v[230:233], v184 offset:56320
	global_load_lds_dwordx4 v[136:137], off
	v_lshl_add_u64 v[136:137], v[162:163], 0, s[26:27]
	s_add_i32 m0, s6, 0x2000
	s_add_i32 s6, s11, s47
	global_load_lds_dwordx4 v[136:137], off
	v_lshl_add_u64 v[136:137], v[234:235], 0, s[26:27]
	s_mov_b32 m0, s6
	s_nop 0
	global_load_lds_dwordx4 v[136:137], off
	v_lshl_add_u64 v[136:137], v[236:237], 0, s[26:27]
	s_add_i32 m0, s6, 0x2000
	s_nop 0
	global_load_lds_dwordx4 v[136:137], off
	v_lshl_add_u64 v[136:137], v[238:239], 0, s[26:27]
	s_mov_b32 m0, s77
	s_nop 0
	global_load_lds_dwordx4 v[136:137], off
	v_lshl_add_u64 v[136:137], v[240:241], 0, s[26:27]
	s_mov_b32 m0, s88
	s_nop 0
	global_load_lds_dwordx4 v[136:137], off
	s_waitcnt vmcnt(8)
	s_waitcnt lgkmcnt(0)
	s_barrier
	s_setprio 1
	s_waitcnt lgkmcnt(0)
	v_mfma_f32_16x16x32_bf16 v[62:65], v[140:143], v[202:205], v[62:65]
	v_mfma_f32_16x16x32_bf16 v[58:61], v[154:157], v[202:205], v[58:61]
	v_mfma_f32_16x16x32_bf16 v[46:49], v[140:143], v[210:213], v[46:49]
	v_mfma_f32_16x16x32_bf16 v[42:45], v[154:157], v[210:213], v[42:45]
	v_mfma_f32_16x16x32_bf16 v[30:33], v[140:143], v[218:221], v[30:33]
	v_mfma_f32_16x16x32_bf16 v[26:29], v[154:157], v[218:221], v[26:29]
	v_mfma_f32_16x16x32_bf16 v[14:17], v[140:143], v[226:229], v[14:17]
	v_mfma_f32_16x16x32_bf16 v[10:13], v[154:157], v[226:229], v[10:13]
	v_mfma_f32_16x16x32_bf16 v[62:65], v[150:153], v[206:209], v[62:65]
	v_mfma_f32_16x16x32_bf16 v[58:61], v[158:161], v[206:209], v[58:61]
	v_mfma_f32_16x16x32_bf16 v[46:49], v[150:153], v[214:217], v[46:49]
	v_mfma_f32_16x16x32_bf16 v[42:45], v[158:161], v[214:217], v[42:45]
	v_mfma_f32_16x16x32_bf16 v[30:33], v[150:153], v[222:225], v[30:33]
	v_mfma_f32_16x16x32_bf16 v[26:29], v[158:161], v[222:225], v[26:29]
	v_mfma_f32_16x16x32_bf16 v[14:17], v[150:153], v[230:233], v[14:17]
	v_mfma_f32_16x16x32_bf16 v[10:13], v[158:161], v[230:233], v[10:13]
	s_setprio 0
	s_setprio 1
	v_mfma_f32_16x16x32_bf16 v[54:57], v[186:189], v[202:205], v[54:57]
	v_mfma_f32_16x16x32_bf16 v[50:53], v[194:197], v[202:205], v[50:53]
	v_mfma_f32_16x16x32_bf16 v[38:41], v[186:189], v[210:213], v[38:41]
	v_mfma_f32_16x16x32_bf16 v[34:37], v[194:197], v[210:213], v[34:37]
	v_mfma_f32_16x16x32_bf16 v[22:25], v[186:189], v[218:221], v[22:25]
	v_mfma_f32_16x16x32_bf16 v[18:21], v[194:197], v[218:221], v[18:21]
	v_mfma_f32_16x16x32_bf16 v[6:9], v[186:189], v[226:229], v[6:9]
	v_mfma_f32_16x16x32_bf16 v[2:5], v[194:197], v[226:229], v[2:5]
	v_mfma_f32_16x16x32_bf16 v[54:57], v[190:193], v[206:209], v[54:57]
	v_mfma_f32_16x16x32_bf16 v[50:53], v[198:201], v[206:209], v[50:53]
	v_mfma_f32_16x16x32_bf16 v[38:41], v[190:193], v[214:217], v[38:41]
	v_mfma_f32_16x16x32_bf16 v[34:37], v[198:201], v[214:217], v[34:37]
	v_mfma_f32_16x16x32_bf16 v[22:25], v[190:193], v[222:225], v[22:25]
	v_mfma_f32_16x16x32_bf16 v[18:21], v[198:201], v[222:225], v[18:21]
	v_mfma_f32_16x16x32_bf16 v[6:9], v[190:193], v[230:233], v[6:9]
	v_mfma_f32_16x16x32_bf16 v[2:5], v[198:201], v[230:233], v[2:5]
	s_setprio 0
	s_barrier
	s_cmp_ge_i32 s20, s37
	s_cbranch_scc1 .LBB0_177
	s_mov_b32 s17, s20
	s_branch .LBB0_173

; #define PG8_STAGE(bufoff, gbase, off, q) do { \
;         __builtin_amdgcn_global_load_lds((const unsigned*)((const char*)(gbase) + (off)), (LAS unsigned*)(lds + (bufoff) + ldsw), 16, 0, 0); \
;         __builtin_amdgcn_global_load_lds((const unsigned*)((const char*)(gbase) + (q) + (off)), (LAS unsigned*)(lds + (bufoff) + ldsw + 8192), 16, 0, 0); } while (0)
; #define PG8_LDA(dst, b, h) do { _Pragma("unroll") for (int m = 0; m < 4; ++m) _Pragma("unroll") for (int k = 0; k < 2; ++k) dst[m][k] = *(const LAS bf16x8*)(lds + PG8_SA(b, h) + aoff + m * 2048 + k * 1024); } while (0)
; #define PG8_LDB(dst, b, h) do { _Pragma("unroll") for (int n = 0; n < 2; ++n) _Pragma("unroll") for (int k = 0; k < 2; ++k) dst[n][k] = *(const LAS bf16x8*)(lds + PG8_SB(b, h) + boff + n * 2048 + k * 1024); } while (0)
; #define PG8_MMA(ai, bj, At, Bt) do { __builtin_amdgcn_s_setprio(1); _Pragma("unroll") for (int m = 0; m < 4; ++m) _Pragma("unroll") for (int n = 0; n < 2; ++n) _Pragma("unroll") for (int k = 0; k < 2; ++k) \
;         acc[ai][bj][m][n] = __builtin_amdgcn_mfma_f32_16x16x32_bf16(Bt[n][k], At[m][k], acc[ai][bj][m][n], 0, 0, 0); __builtin_amdgcn_s_setprio(0); } while (0)
; template <class Epi, class Sched>
; __device__ __forceinline__ void gemm_phase(LAS unsigned char* lds, const int tid, const Sched& S, const Epi& E) {
;     ...
;             const bool last = (t == nt - 2);
;             const char* a1 = cA + (size_t)(t + 1) * kstep;
;             const char* a2 = last ? nA : cA + (size_t)(t + 2) * kstep; const char* b2 = last ? nB : cB + (size_t)(t + 2) * kstep;
;             const char* a3 = a2 + kstep; const char* b3 = b2 + kstep;
;             const unsigned oA2 = last ? noffA : offA, oB2 = last ? noffB : offB;
;             const int qA2 = last ? nqA : qA, qB2 = last ? nqB : qB, hA2 = last ? nhA : hA, hB2 = last ? nhB : hB;
;             PG8_LDB(B0, 0, 0); PG8_LDB(B1, 0, 1); PG8_SCHED; PG8_LDA(At, 0, 0); PG8_STAGE(PG8_SA(1, 1), a1 + hA, offA, qA);
;             PG8_WAIT_V(8); PG8_WAIT_L(0); PG8_BAR; PG8_MMA(0, 0, At, B0); PG8_MMA(0, 1, At, B1); PG8_BAR; PG8_SCHED;
;             PG8_LDA(At, 0, 1); PG8_STAGE(PG8_SB(0, 0), b2, oB2, qB2); PG8_STAGE(PG8_SB(0, 1), b2 + hB2, oB2, qB2); PG8_STAGE(PG8_SA(0, 0), a2, oA2, qA2);
;             PG8_WAIT_V(8); PG8_WAIT_L(0); PG8_BAR; PG8_MMA(1, 0, At, B0); PG8_MMA(1, 1, At, B1); PG8_BAR; PG8_SCHED;
.Lk0b_175:
	s_or_b32 vcc_lo, s17, 1
	s_mov_b32 vcc_hi, s21
	s_lshl_b64 s[10:11], vcc, 7
	s_add_u32 s17, s40, s6
	s_addc_u32 vcc_lo, s41, s7
	s_and_b64 s[6:7], exec, s[62:63]
	s_cselect_b32 vcc_hi, s82, vcc_lo
	s_cselect_b32 vcc_lo, s48, s17
	s_add_i32 s17, 0, 0x10000
	v_add_u32_e32 v133, s17, v147
	s_add_i32 s62, 0, 0x14000
	ds_read_b128 v[140:143], v133
	ds_read_b128 v[150:153], v133 offset:1024
	ds_read_b128 v[154:157], v133 offset:2048
	ds_read_b128 v[158:161], v133 offset:3072
	v_add_u32_e32 v133, s62, v147
	ds_read_b128 v[186:189], v133
	ds_read_b128 v[190:193], v133 offset:1024
	ds_read_b128 v[194:197], v133 offset:2048
	ds_read_b128 v[198:201], v133 offset:3072
	s_add_u32 s6, s68, s10
	s_addc_u32 s7, s16, s11
	s_add_i32 m0, s54, 0xc000
	v_lshl_add_u64 v[144:145], s[6:7], 0, v[134:135]
	s_add_u32 s6, s6, s66
	s_addc_u32 s7, s7, s67
	ds_read_b128 v[202:205], v184
	ds_read_b128 v[206:209], v184 offset:1024
	ds_read_b128 v[210:213], v184 offset:2048
	ds_read_b128 v[214:217], v184 offset:3072
	ds_read_b128 v[218:221], v184 offset:4096
	ds_read_b128 v[222:225], v184 offset:5120
	ds_read_b128 v[226:229], v184 offset:6144
	ds_read_b128 v[230:233], v184 offset:7168
	global_load_lds_dwordx4 v[144:145], off
	v_lshl_add_u64 v[144:145], s[6:7], 0, v[134:135]
	s_add_i32 m0, s54, 0xe000
	s_nop 0
	global_load_lds_dwordx4 v[144:145], off
	s_waitcnt vmcnt(24)
	s_waitcnt lgkmcnt(0)
	s_barrier
	s_setprio 1
	s_waitcnt lgkmcnt(0)
	v_mfma_f32_16x16x32_bf16 v[126:129], v[140:143], v[202:205], v[126:129]
	v_mfma_f32_16x16x32_bf16 v[122:125], v[154:157], v[202:205], v[122:125]
	v_mfma_f32_16x16x32_bf16 v[110:113], v[140:143], v[210:213], v[110:113]
	v_mfma_f32_16x16x32_bf16 v[106:109], v[154:157], v[210:213], v[106:109]
	v_mfma_f32_16x16x32_bf16 v[94:97], v[140:143], v[218:221], v[94:97]
	v_mfma_f32_16x16x32_bf16 v[90:93], v[154:157], v[218:221], v[90:93]
	v_mfma_f32_16x16x32_bf16 v[78:81], v[140:143], v[226:229], v[78:81]
	v_mfma_f32_16x16x32_bf16 v[74:77], v[154:157], v[226:229], v[74:77]
	v_mfma_f32_16x16x32_bf16 v[126:129], v[150:153], v[206:209], v[126:129]
	v_mfma_f32_16x16x32_bf16 v[122:125], v[158:161], v[206:209], v[122:125]
	v_mfma_f32_16x16x32_bf16 v[110:113], v[150:153], v[214:217], v[110:113]
	v_mfma_f32_16x16x32_bf16 v[106:109], v[158:161], v[214:217], v[106:109]
	v_mfma_f32_16x16x32_bf16 v[94:97], v[150:153], v[222:225], v[94:97]
	v_mfma_f32_16x16x32_bf16 v[90:93], v[158:161], v[222:225], v[90:93]
	v_mfma_f32_16x16x32_bf16 v[78:81], v[150:153], v[230:233], v[78:81]
	v_mfma_f32_16x16x32_bf16 v[74:77], v[158:161], v[230:233], v[74:77]
	s_setprio 0
	s_setprio 1
	v_mfma_f32_16x16x32_bf16 v[118:121], v[186:189], v[202:205], v[118:121]
	v_mfma_f32_16x16x32_bf16 v[114:117], v[194:197], v[202:205], v[114:117]
	v_mfma_f32_16x16x32_bf16 v[102:105], v[186:189], v[210:213], v[102:105]
	v_mfma_f32_16x16x32_bf16 v[98:101], v[194:197], v[210:213], v[98:101]
	v_mfma_f32_16x16x32_bf16 v[86:89], v[186:189], v[218:221], v[86:89]
	v_mfma_f32_16x16x32_bf16 v[82:85], v[194:197], v[218:221], v[82:85]
	v_mfma_f32_16x16x32_bf16 v[70:73], v[186:189], v[226:229], v[70:73]
	v_mfma_f32_16x16x32_bf16 v[66:69], v[194:197], v[226:229], v[66:69]
	v_mfma_f32_16x16x32_bf16 v[118:121], v[190:193], v[206:209], v[118:121]
	v_mfma_f32_16x16x32_bf16 v[114:117], v[198:201], v[206:209], v[114:117]
	v_mfma_f32_16x16x32_bf16 v[102:105], v[190:193], v[214:217], v[102:105]
	v_mfma_f32_16x16x32_bf16 v[98:101], v[198:201], v[214:217], v[98:101]
	v_mfma_f32_16x16x32_bf16 v[86:89], v[190:193], v[222:225], v[86:89]
	v_mfma_f32_16x16x32_bf16 v[82:85], v[198:201], v[222:225], v[82:85]
	v_mfma_f32_16x16x32_bf16 v[70:73], v[190:193], v[230:233], v[70:73]
	v_mfma_f32_16x16x32_bf16 v[66:69], v[198:201], v[230:233], v[66:69]
	s_setprio 0
	s_barrier
	s_add_i32 s10, s17, s47
	s_ashr_i32 s11, s73, 31
	s_mov_b32 m0, s10
	s_add_u32 s6, s28, s73
	ds_read_b128 v[202:205], v184 offset:16384
	ds_read_b128 v[206:209], v184 offset:17408
	ds_read_b128 v[210:213], v184 offset:18432
	ds_read_b128 v[214:217], v184 offset:19456
	ds_read_b128 v[218:221], v184 offset:20480
	ds_read_b128 v[222:225], v184 offset:21504
	ds_read_b128 v[226:229], v184 offset:22528
	ds_read_b128 v[230:233], v184 offset:23552
	global_load_lds_dwordx4 v0, s[28:29]
	s_addc_u32 s7, s29, s11
	s_add_i32 m0, s10, 0x2000
	v_lshl_add_u64 v[162:163], s[6:7], 0, v[0:1]
	global_load_lds_dwordx4 v0, s[6:7]
	s_ashr_i32 s7, s19, 31
	s_add_u32 s6, s28, s19
	s_addc_u32 s7, s29, s7
	s_add_i32 s10, s62, s47
	s_mov_b32 m0, s10
	v_lshl_add_u64 v[234:235], s[6:7], 0, v[0:1]
	global_load_lds_dwordx4 v0, s[6:7]
	s_add_u32 s6, s6, s73
	s_addc_u32 s7, s7, s11
	s_add_i32 m0, s10, 0x2000
	v_lshl_add_u64 v[236:237], s[6:7], 0, v[0:1]
	global_load_lds_dwordx4 v0, s[6:7]
	s_add_u32 s6, vcc_lo, s64
	v_lshl_add_u64 v[238:239], vcc, 0, v[136:137]
	s_mov_b32 m0, s54
	s_addc_u32 s7, vcc_hi, s65
	global_load_lds_dwordx4 v[238:239], off
	v_lshl_add_u64 v[240:241], s[6:7], 0, v[136:137]
	s_mov_b32 m0, s55
	v_lshl_add_u64 v[144:145], s[28:29], 0, v[0:1]
	global_load_lds_dwordx4 v[240:241], off
	s_waitcnt vmcnt(24)
	s_waitcnt lgkmcnt(0)
	s_barrier
; #define PG8_STAGE(bufoff, gbase, off, q) do { \
;         __builtin_amdgcn_global_load_lds((const unsigned*)((const char*)(gbase) + (off)), (LAS unsigned*)(lds + (bufoff) + ldsw), 16, 0, 0); \
;         __builtin_amdgcn_global_load_lds((const unsigned*)((const char*)(gbase) + (q) + (off)), (LAS unsigned*)(lds + (bufoff) + ldsw + 8192), 16, 0, 0); } while (0)
; #define PG8_LDA(dst, b, h) do { _Pragma("unroll") for (int m = 0; m < 4; ++m) _Pragma("unroll") for (int k = 0; k < 2; ++k) dst[m][k] = *(const LAS bf16x8*)(lds + PG8_SA(b, h) + aoff + m * 2048 + k * 1024); } while (0)
; #define PG8_LDB(dst, b, h) do { _Pragma("unroll") for (int n = 0; n < 2; ++n) _Pragma("unroll") for (int k = 0; k < 2; ++k) dst[n][k] = *(const LAS bf16x8*)(lds + PG8_SB(b, h) + boff + n * 2048 + k * 1024); } while (0)
; #define PG8_MMA(ai, bj, At, Bt) do { __builtin_amdgcn_s_setprio(1); _Pragma("unroll") for (int m = 0; m < 4; ++m) _Pragma("unroll") for (int n = 0; n < 2; ++n) _Pragma("unroll") for (int k = 0; k < 2; ++k) \
;         acc[ai][bj][m][n] = __builtin_amdgcn_mfma_f32_16x16x32_bf16(Bt[n][k], At[m][k], acc[ai][bj][m][n], 0, 0, 0); __builtin_amdgcn_s_setprio(0); } while (0)
; #define PG8_WAIT_V(n) asm volatile("s_waitcnt vmcnt(" #n ")" ::: "memory")
; #define PG8_WAIT_L(n) asm volatile("s_waitcnt lgkmcnt(" #n ")" ::: "memory")
; #define PG8_BAR __builtin_amdgcn_s_barrier()
; #define PG8_SCHED __builtin_amdgcn_sched_barrier(0)
; template <class Epi, class Sched>
; __device__ __forceinline__ void gemm_phase(LAS unsigned char* lds, const int tid, const Sched& S, const Epi& E) {
;     ...
;             PG8_WAIT_V(8); PG8_WAIT_L(0); PG8_BAR; PG8_MMA(1, 0, At, B0); PG8_MMA(1, 1, At, B1); PG8_BAR; PG8_SCHED;
;             PG8_LDB(B0, 1, 0); PG8_LDB(B1, 1, 1); PG8_SCHED; PG8_LDA(At, 1, 0); PG8_STAGE(PG8_SA(0, 1), a2 + hA2, oA2, qA2);
;             PG8_WAIT_V(8); PG8_WAIT_L(0); PG8_BAR; PG8_MMA(0, 0, At, B0); PG8_MMA(0, 1, At, B1); PG8_BAR; PG8_SCHED;
	s_setprio 1
	s_waitcnt lgkmcnt(0)
	v_mfma_f32_16x16x32_bf16 v[62:65], v[140:143], v[202:205], v[62:65]
	v_mfma_f32_16x16x32_bf16 v[58:61], v[154:157], v[202:205], v[58:61]
	v_mfma_f32_16x16x32_bf16 v[46:49], v[140:143], v[210:213], v[46:49]
	v_mfma_f32_16x16x32_bf16 v[42:45], v[154:157], v[210:213], v[42:45]
	v_mfma_f32_16x16x32_bf16 v[30:33], v[140:143], v[218:221], v[30:33]
	v_mfma_f32_16x16x32_bf16 v[26:29], v[154:157], v[218:221], v[26:29]
	v_mfma_f32_16x16x32_bf16 v[14:17], v[140:143], v[226:229], v[14:17]
	v_mfma_f32_16x16x32_bf16 v[10:13], v[154:157], v[226:229], v[10:13]
	v_mfma_f32_16x16x32_bf16 v[62:65], v[150:153], v[206:209], v[62:65]
	v_mfma_f32_16x16x32_bf16 v[58:61], v[158:161], v[206:209], v[58:61]
	v_mfma_f32_16x16x32_bf16 v[46:49], v[150:153], v[214:217], v[46:49]
	v_mfma_f32_16x16x32_bf16 v[42:45], v[158:161], v[214:217], v[42:45]
	v_mfma_f32_16x16x32_bf16 v[30:33], v[150:153], v[222:225], v[30:33]
	v_mfma_f32_16x16x32_bf16 v[26:29], v[158:161], v[222:225], v[26:29]
	v_mfma_f32_16x16x32_bf16 v[14:17], v[150:153], v[230:233], v[14:17]
	v_mfma_f32_16x16x32_bf16 v[10:13], v[158:161], v[230:233], v[10:13]
	s_setprio 0
	s_setprio 1
	v_mfma_f32_16x16x32_bf16 v[54:57], v[186:189], v[202:205], v[54:57]
	v_mfma_f32_16x16x32_bf16 v[50:53], v[194:197], v[202:205], v[50:53]
	v_mfma_f32_16x16x32_bf16 v[38:41], v[186:189], v[210:213], v[38:41]
	v_mfma_f32_16x16x32_bf16 v[34:37], v[194:197], v[210:213], v[34:37]
	v_mfma_f32_16x16x32_bf16 v[22:25], v[186:189], v[218:221], v[22:25]
	v_mfma_f32_16x16x32_bf16 v[18:21], v[194:197], v[218:221], v[18:21]
	v_mfma_f32_16x16x32_bf16 v[6:9], v[186:189], v[226:229], v[6:9]
	v_mfma_f32_16x16x32_bf16 v[2:5], v[194:197], v[226:229], v[2:5]
	v_mfma_f32_16x16x32_bf16 v[54:57], v[190:193], v[206:209], v[54:57]
	v_mfma_f32_16x16x32_bf16 v[50:53], v[198:201], v[206:209], v[50:53]
	v_mfma_f32_16x16x32_bf16 v[38:41], v[190:193], v[214:217], v[38:41]
	v_mfma_f32_16x16x32_bf16 v[34:37], v[198:201], v[214:217], v[34:37]
	v_mfma_f32_16x16x32_bf16 v[22:25], v[190:193], v[222:225], v[22:25]
	v_mfma_f32_16x16x32_bf16 v[18:21], v[198:201], v[222:225], v[18:21]
	v_mfma_f32_16x16x32_bf16 v[6:9], v[190:193], v[230:233], v[6:9]
	v_mfma_f32_16x16x32_bf16 v[2:5], v[198:201], v[230:233], v[2:5]
	s_setprio 0
	s_barrier
	s_add_i32 s10, 0, 0x18000
	v_add_u32_e32 v0, s10, v147
	s_add_i32 s11, 0, 0x1c000
	ds_read_b128 v[140:143], v0
	ds_read_b128 v[150:153], v0 offset:1024
	ds_read_b128 v[154:157], v0 offset:2048
	ds_read_b128 v[158:161], v0 offset:3072
	v_add_u32_e32 v0, s11, v147
	ds_read_b128 v[186:189], v0
	ds_read_b128 v[190:193], v0 offset:1024
	ds_read_b128 v[194:197], v0 offset:2048
	ds_read_b128 v[198:201], v0 offset:3072
	s_add_u32 s6, vcc_lo, s58
	s_addc_u32 s7, vcc_hi, s59
	v_lshl_add_u64 v[242:243], s[6:7], 0, v[136:137]
	s_add_u32 s6, s6, s64
	s_mov_b32 m0, s91
	s_addc_u32 s7, s7, s65
	ds_read_b128 v[202:205], v184 offset:32768
	ds_read_b128 v[206:209], v184 offset:33792
	ds_read_b128 v[210:213], v184 offset:34816
	ds_read_b128 v[214:217], v184 offset:35840
	ds_read_b128 v[218:221], v184 offset:36864
	ds_read_b128 v[222:225], v184 offset:37888
	ds_read_b128 v[226:229], v184 offset:38912
	ds_read_b128 v[230:233], v184 offset:39936
	global_load_lds_dwordx4 v[242:243], off
	v_lshl_add_u64 v[136:137], s[6:7], 0, v[136:137]
	s_mov_b32 m0, s93
	s_nop 0
	global_load_lds_dwordx4 v[136:137], off
	s_waitcnt vmcnt(8)
	s_waitcnt lgkmcnt(0)
	s_barrier
	s_setprio 1
	s_waitcnt lgkmcnt(0)
	v_mfma_f32_16x16x32_bf16 v[126:129], v[140:143], v[202:205], v[126:129]
	v_mfma_f32_16x16x32_bf16 v[122:125], v[154:157], v[202:205], v[122:125]
	v_mfma_f32_16x16x32_bf16 v[110:113], v[140:143], v[210:213], v[110:113]
	v_mfma_f32_16x16x32_bf16 v[106:109], v[154:157], v[210:213], v[106:109]
	v_mfma_f32_16x16x32_bf16 v[94:97], v[140:143], v[218:221], v[94:97]
	v_mfma_f32_16x16x32_bf16 v[90:93], v[154:157], v[218:221], v[90:93]
	v_mfma_f32_16x16x32_bf16 v[78:81], v[140:143], v[226:229], v[78:81]
	v_mfma_f32_16x16x32_bf16 v[74:77], v[154:157], v[226:229], v[74:77]
	v_mfma_f32_16x16x32_bf16 v[126:129], v[150:153], v[206:209], v[126:129]
	v_mfma_f32_16x16x32_bf16 v[122:125], v[158:161], v[206:209], v[122:125]
	v_mfma_f32_16x16x32_bf16 v[110:113], v[150:153], v[214:217], v[110:113]
	v_mfma_f32_16x16x32_bf16 v[106:109], v[158:161], v[214:217], v[106:109]
	v_mfma_f32_16x16x32_bf16 v[94:97], v[150:153], v[222:225], v[94:97]
	v_mfma_f32_16x16x32_bf16 v[90:93], v[158:161], v[222:225], v[90:93]
	v_mfma_f32_16x16x32_bf16 v[78:81], v[150:153], v[230:233], v[78:81]
	v_mfma_f32_16x16x32_bf16 v[74:77], v[158:161], v[230:233], v[74:77]
	s_setprio 0
	s_setprio 1
	v_mfma_f32_16x16x32_bf16 v[118:121], v[186:189], v[202:205], v[118:121]
	v_mfma_f32_16x16x32_bf16 v[114:117], v[194:197], v[202:205], v[114:117]
	v_mfma_f32_16x16x32_bf16 v[102:105], v[186:189], v[210:213], v[102:105]
	v_mfma_f32_16x16x32_bf16 v[98:101], v[194:197], v[210:213], v[98:101]
	v_mfma_f32_16x16x32_bf16 v[86:89], v[186:189], v[218:221], v[86:89]
	v_mfma_f32_16x16x32_bf16 v[82:85], v[194:197], v[218:221], v[82:85]
	v_mfma_f32_16x16x32_bf16 v[70:73], v[186:189], v[226:229], v[70:73]
	v_mfma_f32_16x16x32_bf16 v[66:69], v[194:197], v[226:229], v[66:69]
	v_mfma_f32_16x16x32_bf16 v[118:121], v[190:193], v[206:209], v[118:121]
	v_mfma_f32_16x16x32_bf16 v[114:117], v[198:201], v[206:209], v[114:117]
	v_mfma_f32_16x16x32_bf16 v[102:105], v[190:193], v[214:217], v[102:105]
	v_mfma_f32_16x16x32_bf16 v[98:101], v[198:201], v[214:217], v[98:101]
	v_mfma_f32_16x16x32_bf16 v[86:89], v[190:193], v[222:225], v[86:89]
	v_mfma_f32_16x16x32_bf16 v[82:85], v[198:201], v[222:225], v[82:85]
	v_mfma_f32_16x16x32_bf16 v[70:73], v[190:193], v[230:233], v[70:73]
	v_mfma_f32_16x16x32_bf16 v[66:69], v[198:201], v[230:233], v[66:69]
	s_setprio 0
	s_barrier
; #define PG8_STAGE(bufoff, gbase, off, q) do { \
;         __builtin_amdgcn_global_load_lds((const unsigned*)((const char*)(gbase) + (off)), (LAS unsigned*)(lds + (bufoff) + ldsw), 16, 0, 0); \
;         __builtin_amdgcn_global_load_lds((const unsigned*)((const char*)(gbase) + (q) + (off)), (LAS unsigned*)(lds + (bufoff) + ldsw + 8192), 16, 0, 0); } while (0)
; #define PG8_LDA(dst, b, h) do { _Pragma("unroll") for (int m = 0; m < 4; ++m) _Pragma("unroll") for (int k = 0; k < 2; ++k) dst[m][k] = *(const LAS bf16x8*)(lds + PG8_SA(b, h) + aoff + m * 2048 + k * 1024); } while (0)
; #define PG8_MMA(ai, bj, At, Bt) do { __builtin_amdgcn_s_setprio(1); _Pragma("unroll") for (int m = 0; m < 4; ++m) _Pragma("unroll") for (int n = 0; n < 2; ++n) _Pragma("unroll") for (int k = 0; k < 2; ++k) \
;         acc[ai][bj][m][n] = __builtin_amdgcn_mfma_f32_16x16x32_bf16(Bt[n][k], At[m][k], acc[ai][bj][m][n], 0, 0, 0); __builtin_amdgcn_s_setprio(0); } while (0)
; #define PG8_WAIT_V(n) asm volatile("s_waitcnt vmcnt(" #n ")" ::: "memory")
; #define PG8_WAIT_L(n) asm volatile("s_waitcnt lgkmcnt(" #n ")" ::: "memory")
; #define PG8_BAR __builtin_amdgcn_s_barrier()
; #define PG8_SCHED __builtin_amdgcn_sched_barrier(0)
; template <class Epi, class Sched>
; __device__ __forceinline__ void gemm_phase(LAS unsigned char* lds, const int tid, const Sched& S, const Epi& E) {
;     ...
;             PG8_LDA(At, 1, 1); PG8_STAGE(PG8_SB(1, 0), b3, oB2, qB2); PG8_STAGE(PG8_SB(1, 1), b3 + hB2, oB2, qB2); PG8_STAGE(PG8_SA(1, 0), a3, oA2, qA2);
;             PG8_WAIT_V(8); PG8_WAIT_L(0); PG8_BAR; PG8_MMA(1, 0, At, B0); PG8_MMA(1, 1, At, B1); PG8_BAR; PG8_SCHED;
;         }
	s_add_i32 s6, s10, s47
	v_lshl_add_u64 v[136:137], v[144:145], 0, s[26:27]
	s_mov_b32 m0, s6
	ds_read_b128 v[202:205], v184 offset:49152
	ds_read_b128 v[206:209], v184 offset:50176
	ds_read_b128 v[210:213], v184 offset:51200
	ds_read_b128 v[214:217], v184 offset:52224
	ds_read_b128 v[218:221], v184 offset:53248
	ds_read_b128 v[222:225], v184 offset:54272
	ds_read_b128 v[226:229], v184 offset:55296
	ds_read_b128 v[230:233], v184 offset:56320
	global_load_lds_dwordx4 v[136:137], off
	v_lshl_add_u64 v[136:137], v[162:163], 0, s[26:27]
	s_add_i32 m0, s6, 0x2000
	s_add_i32 s6, s11, s47
	global_load_lds_dwordx4 v[136:137], off
	v_lshl_add_u64 v[136:137], v[234:235], 0, s[26:27]
	s_mov_b32 m0, s6
	s_nop 0
	global_load_lds_dwordx4 v[136:137], off
	v_lshl_add_u64 v[136:137], v[236:237], 0, s[26:27]
	s_add_i32 m0, s6, 0x2000
	s_nop 0
	global_load_lds_dwordx4 v[136:137], off
	v_lshl_add_u64 v[136:137], v[238:239], 0, s[26:27]
	s_mov_b32 m0, s77
	s_nop 0
	global_load_lds_dwordx4 v[136:137], off
	v_lshl_add_u64 v[136:137], v[240:241], 0, s[26:27]
	s_mov_b32 m0, s88
	s_nop 0
	global_load_lds_dwordx4 v[136:137], off
	s_waitcnt vmcnt(8)
	s_waitcnt lgkmcnt(0)
	s_barrier
	s_setprio 1
	s_waitcnt lgkmcnt(0)
	v_mfma_f32_16x16x32_bf16 v[62:65], v[140:143], v[202:205], v[62:65]
	v_mfma_f32_16x16x32_bf16 v[58:61], v[154:157], v[202:205], v[58:61]
	v_mfma_f32_16x16x32_bf16 v[46:49], v[140:143], v[210:213], v[46:49]
	v_mfma_f32_16x16x32_bf16 v[42:45], v[154:157], v[210:213], v[42:45]
	v_mfma_f32_16x16x32_bf16 v[30:33], v[140:143], v[218:221], v[30:33]
	v_mfma_f32_16x16x32_bf16 v[26:29], v[154:157], v[218:221], v[26:29]
	v_mfma_f32_16x16x32_bf16 v[14:17], v[140:143], v[226:229], v[14:17]
	v_mfma_f32_16x16x32_bf16 v[10:13], v[154:157], v[226:229], v[10:13]
	v_mfma_f32_16x16x32_bf16 v[62:65], v[150:153], v[206:209], v[62:65]
	v_mfma_f32_16x16x32_bf16 v[58:61], v[158:161], v[206:209], v[58:61]
	v_mfma_f32_16x16x32_bf16 v[46:49], v[150:153], v[214:217], v[46:49]
	v_mfma_f32_16x16x32_bf16 v[42:45], v[158:161], v[214:217], v[42:45]
	v_mfma_f32_16x16x32_bf16 v[30:33], v[150:153], v[222:225], v[30:33]
	v_mfma_f32_16x16x32_bf16 v[26:29], v[158:161], v[222:225], v[26:29]
	v_mfma_f32_16x16x32_bf16 v[14:17], v[150:153], v[230:233], v[14:17]
	v_mfma_f32_16x16x32_bf16 v[10:13], v[158:161], v[230:233], v[10:13]
	s_setprio 0
	s_setprio 1
	v_mfma_f32_16x16x32_bf16 v[54:57], v[186:189], v[202:205], v[54:57]
	v_mfma_f32_16x16x32_bf16 v[50:53], v[194:197], v[202:205], v[50:53]
	v_mfma_f32_16x16x32_bf16 v[38:41], v[186:189], v[210:213], v[38:41]
	v_mfma_f32_16x16x32_bf16 v[34:37], v[194:197], v[210:213], v[34:37]
	v_mfma_f32_16x16x32_bf16 v[22:25], v[186:189], v[218:221], v[22:25]
	v_mfma_f32_16x16x32_bf16 v[18:21], v[194:197], v[218:221], v[18:21]
	v_mfma_f32_16x16x32_bf16 v[6:9], v[186:189], v[226:229], v[6:9]
	v_mfma_f32_16x16x32_bf16 v[2:5], v[194:197], v[226:229], v[2:5]
	v_mfma_f32_16x16x32_bf16 v[54:57], v[190:193], v[206:209], v[54:57]
	v_mfma_f32_16x16x32_bf16 v[50:53], v[198:201], v[206:209], v[50:53]
	v_mfma_f32_16x16x32_bf16 v[38:41], v[190:193], v[214:217], v[38:41]
	v_mfma_f32_16x16x32_bf16 v[34:37], v[198:201], v[214:217], v[34:37]
	v_mfma_f32_16x16x32_bf16 v[22:25], v[190:193], v[222:225], v[22:25]
	v_mfma_f32_16x16x32_bf16 v[18:21], v[198:201], v[222:225], v[18:21]
	v_mfma_f32_16x16x32_bf16 v[6:9], v[190:193], v[230:233], v[6:9]
	v_mfma_f32_16x16x32_bf16 v[2:5], v[198:201], v[230:233], v[2:5]
	s_setprio 0
	s_barrier
	s_cmp_ge_i32 s20, s37
	s_cbranch_scc1 .LBB0_177
	s_mov_b32 s17, s20
	s_branch .LBB0_173

; __device__ __forceinline__ unsigned cvt_pk_bf16(float lo, float hi) { const f32x2_t v = {lo, hi}; const bf16x2_t b = __builtin_convertvector(v, bf16x2_t); return __builtin_bit_cast(unsigned, b); }
; #define SG2(v, bb) __builtin_amdgcn_rcpf(1.0f + __builtin_amdgcn_exp2f(__builtin_fmaf((v), -1.4426950408889634f, (bb))))
;     __device__ __forceinline__ void operator()(const f32x4 (&acc)[2][2][4][2], const pg8::Unit& u, int tid, int wr, int wc, int fr, int fq) const {
;     ...
;                         const f32x4 v0 = acc[ai][bj][m][0], v1 = acc[ai][bj][m][1];
;                         u32x4* slot = pk + ((ai * 4 + m) * 2 + bj) * 512;
;                         if (isg) {
;     ...
;                             u32x4 w; w.x = cvt_pk_bf16(SG2(v0[0], b0[0]), SG2(v0[1], b0[1])); w.y = cvt_pk_bf16(SG2(v0[2], b0[2]), SG2(v0[3], b0[3]));
;                             w.z = cvt_pk_bf16(SG2(v1[0], b1[0]), SG2(v1[1], b1[1])); w.w = cvt_pk_bf16(SG2(v1[2], b1[2]), SG2(v1[3], b1[3]));
;     ...
;                             *slot = w;
.LBB0_189:
	s_and_b64 vcc, exec, s[6:7]
	s_cbranch_vccz .LBB0_191
	v_fmamk_f32 v135, v126, 0xbfb8aa3b, v150
	v_fmamk_f32 v152, v127, 0xbfb8aa3b, v151
	v_exp_f32_e32 v135, v135
	v_exp_f32_e32 v152, v152
	v_fmamk_f32 v153, v129, 0xbfb8aa3b, v145
	v_exp_f32_e32 v153, v153
	v_add_f32_e32 v135, 1.0, v135
	v_add_f32_e32 v152, 1.0, v152
	v_rcp_f32_e32 v135, v135
	v_rcp_f32_e32 v152, v152
	v_add_f32_e32 v153, 1.0, v153
	v_rcp_f32_e32 v153, v153
	v_fmamk_f32 v154, v123, 0xbfb8aa3b, v143
	v_cvt_pk_bf16_f32 v152, v135, v152
	v_fmamk_f32 v135, v128, 0xbfb8aa3b, v144
	v_exp_f32_e32 v135, v135
	v_exp_f32_e32 v154, v154
	v_fmamk_f32 v155, v125, 0xbfb8aa3b, v141
	v_exp_f32_e32 v155, v155
	v_add_f32_e32 v135, 1.0, v135
	v_rcp_f32_e32 v135, v135
	v_add_f32_e32 v154, 1.0, v154
	v_rcp_f32_e32 v154, v154
	v_add_f32_e32 v155, 1.0, v155
	v_cvt_pk_bf16_f32 v153, v135, v153
	v_fmamk_f32 v135, v122, 0xbfb8aa3b, v142
	v_exp_f32_e32 v135, v135
	v_rcp_f32_e32 v155, v155
	v_add_f32_e32 v135, 1.0, v135
	v_rcp_f32_e32 v135, v135
	s_nop 0
	v_cvt_pk_bf16_f32 v154, v135, v154
	v_fmamk_f32 v135, v124, 0xbfb8aa3b, v140
	v_exp_f32_e32 v135, v135
	s_nop 0
	v_add_f32_e32 v135, 1.0, v135
	v_rcp_f32_e32 v135, v135
	s_nop 0
	v_cvt_pk_bf16_f32 v155, v135, v155
	global_store_dwordx4 v[138:139], v[152:155], off

; __device__ __forceinline__ unsigned cvt_pk_bf16(float lo, float hi) { const f32x2_t v = {lo, hi}; const bf16x2_t b = __builtin_convertvector(v, bf16x2_t); return __builtin_bit_cast(unsigned, b); }
; #define SG2(v, bb) __builtin_amdgcn_rcpf(1.0f + __builtin_amdgcn_exp2f(__builtin_fmaf((v), -1.4426950408889634f, (bb))))
;     __device__ __forceinline__ void operator()(const f32x4 (&acc)[2][2][4][2], const pg8::Unit& u, int tid, int wr, int wc, int fr, int fq) const {
;     ...
;                         const f32x4 v0 = acc[ai][bj][m][0], v1 = acc[ai][bj][m][1];
;                         u32x4* slot = pk + ((ai * 4 + m) * 2 + bj) * 512;
;                         if (isg) {
;     ...
;                             u32x4 w; w.x = cvt_pk_bf16(SG2(v0[0], b0[0]), SG2(v0[1], b0[1])); w.y = cvt_pk_bf16(SG2(v0[2], b0[2]), SG2(v0[3], b0[3]));
;                             w.z = cvt_pk_bf16(SG2(v1[0], b1[0]), SG2(v1[1], b1[1])); w.w = cvt_pk_bf16(SG2(v1[2], b1[2]), SG2(v1[3], b1[3]));
;     ...
;                             *slot = w;
.LBB0_195:
	s_and_b64 vcc, exec, s[6:7]
	s_cbranch_vccz .LBB0_197
	v_fmamk_f32 v135, v110, 0xbfb8aa3b, v150
	v_fmamk_f32 v154, v111, 0xbfb8aa3b, v151
	v_exp_f32_e32 v135, v135
	v_exp_f32_e32 v154, v154
	v_fmamk_f32 v155, v113, 0xbfb8aa3b, v145
	v_exp_f32_e32 v155, v155
	v_add_f32_e32 v135, 1.0, v135
	v_add_f32_e32 v154, 1.0, v154
	v_rcp_f32_e32 v135, v135
	v_rcp_f32_e32 v154, v154
	v_add_f32_e32 v155, 1.0, v155
	v_rcp_f32_e32 v155, v155
	v_fmamk_f32 v156, v107, 0xbfb8aa3b, v143
	v_cvt_pk_bf16_f32 v154, v135, v154
	v_fmamk_f32 v135, v112, 0xbfb8aa3b, v144
	v_exp_f32_e32 v135, v135
	v_exp_f32_e32 v156, v156
	v_fmamk_f32 v157, v109, 0xbfb8aa3b, v141
	v_exp_f32_e32 v157, v157
	v_add_f32_e32 v135, 1.0, v135
	v_rcp_f32_e32 v135, v135
	v_add_f32_e32 v156, 1.0, v156
	v_rcp_f32_e32 v156, v156
	v_add_f32_e32 v157, 1.0, v157
	v_cvt_pk_bf16_f32 v155, v135, v155
	v_fmamk_f32 v135, v106, 0xbfb8aa3b, v142
	v_exp_f32_e32 v135, v135
	v_rcp_f32_e32 v157, v157
	v_add_f32_e32 v135, 1.0, v135
	v_rcp_f32_e32 v135, v135
	s_nop 0
	v_cvt_pk_bf16_f32 v156, v135, v156
	v_fmamk_f32 v135, v108, 0xbfb8aa3b, v140
	v_exp_f32_e32 v135, v135
	s_nop 0
	v_add_f32_e32 v135, 1.0, v135
	v_rcp_f32_e32 v135, v135
	s_nop 0
	v_cvt_pk_bf16_f32 v157, v135, v157
	global_store_dwordx4 v[152:153], v[154:157], off

; __device__ __forceinline__ unsigned cvt_pk_bf16(float lo, float hi) { const f32x2_t v = {lo, hi}; const bf16x2_t b = __builtin_convertvector(v, bf16x2_t); return __builtin_bit_cast(unsigned, b); }
; #define SG2(v, bb) __builtin_amdgcn_rcpf(1.0f + __builtin_amdgcn_exp2f(__builtin_fmaf((v), -1.4426950408889634f, (bb))))
;     __device__ __forceinline__ void operator()(const f32x4 (&acc)[2][2][4][2], const pg8::Unit& u, int tid, int wr, int wc, int fr, int fq) const {
;     ...
;                         const f32x4 v0 = acc[ai][bj][m][0], v1 = acc[ai][bj][m][1];
;                         u32x4* slot = pk + ((ai * 4 + m) * 2 + bj) * 512;
;                         if (isg) {
;     ...
;                             u32x4 w; w.x = cvt_pk_bf16(SG2(v0[0], b0[0]), SG2(v0[1], b0[1])); w.y = cvt_pk_bf16(SG2(v0[2], b0[2]), SG2(v0[3], b0[3]));
;                             w.z = cvt_pk_bf16(SG2(v1[0], b1[0]), SG2(v1[1], b1[1])); w.w = cvt_pk_bf16(SG2(v1[2], b1[2]), SG2(v1[3], b1[3]));
;     ...
;                             *slot = w;
.LBB0_201:
	s_and_b64 vcc, exec, s[6:7]
	s_cbranch_vccz .LBB0_203
	v_fmamk_f32 v135, v94, 0xbfb8aa3b, v150
	v_fmamk_f32 v154, v95, 0xbfb8aa3b, v151
	v_exp_f32_e32 v135, v135
	v_exp_f32_e32 v154, v154
	v_fmamk_f32 v155, v97, 0xbfb8aa3b, v145
	v_exp_f32_e32 v155, v155
	v_add_f32_e32 v135, 1.0, v135
	v_add_f32_e32 v154, 1.0, v154
	v_rcp_f32_e32 v135, v135
	v_rcp_f32_e32 v154, v154
	v_add_f32_e32 v155, 1.0, v155
	v_rcp_f32_e32 v155, v155
	v_fmamk_f32 v156, v91, 0xbfb8aa3b, v143
	v_cvt_pk_bf16_f32 v154, v135, v154
	v_fmamk_f32 v135, v96, 0xbfb8aa3b, v144
	v_exp_f32_e32 v135, v135
	v_exp_f32_e32 v156, v156
	v_fmamk_f32 v157, v93, 0xbfb8aa3b, v141
	v_exp_f32_e32 v157, v157
	v_add_f32_e32 v135, 1.0, v135
	v_rcp_f32_e32 v135, v135
	v_add_f32_e32 v156, 1.0, v156
	v_rcp_f32_e32 v156, v156
	v_add_f32_e32 v157, 1.0, v157
	v_cvt_pk_bf16_f32 v155, v135, v155
	v_fmamk_f32 v135, v90, 0xbfb8aa3b, v142
	v_exp_f32_e32 v135, v135
	v_rcp_f32_e32 v157, v157
	v_add_f32_e32 v135, 1.0, v135
	v_rcp_f32_e32 v135, v135
	s_nop 0
	v_cvt_pk_bf16_f32 v156, v135, v156
	v_fmamk_f32 v135, v92, 0xbfb8aa3b, v140
	v_exp_f32_e32 v135, v135
	s_nop 0
	v_add_f32_e32 v135, 1.0, v135
	v_rcp_f32_e32 v135, v135
	s_nop 0
	v_cvt_pk_bf16_f32 v157, v135, v157
	global_store_dwordx4 v[152:153], v[154:157], off

; __device__ __forceinline__ unsigned cvt_pk_bf16(float lo, float hi) { const f32x2_t v = {lo, hi}; const bf16x2_t b = __builtin_convertvector(v, bf16x2_t); return __builtin_bit_cast(unsigned, b); }
; #define SG2(v, bb) __builtin_amdgcn_rcpf(1.0f + __builtin_amdgcn_exp2f(__builtin_fmaf((v), -1.4426950408889634f, (bb))))
;     __device__ __forceinline__ void operator()(const f32x4 (&acc)[2][2][4][2], const pg8::Unit& u, int tid, int wr, int wc, int fr, int fq) const {
;     ...
;                         const f32x4 v0 = acc[ai][bj][m][0], v1 = acc[ai][bj][m][1];
;                         u32x4* slot = pk + ((ai * 4 + m) * 2 + bj) * 512;
;                         if (isg) {
;     ...
;                             u32x4 w; w.x = cvt_pk_bf16(SG2(v0[0], b0[0]), SG2(v0[1], b0[1])); w.y = cvt_pk_bf16(SG2(v0[2], b0[2]), SG2(v0[3], b0[3]));
;                             w.z = cvt_pk_bf16(SG2(v1[0], b1[0]), SG2(v1[1], b1[1])); w.w = cvt_pk_bf16(SG2(v1[2], b1[2]), SG2(v1[3], b1[3]));
;     ...
;                             *slot = w;
.LBB0_207:
	s_and_b64 vcc, exec, s[6:7]
	s_cbranch_vccz .LBB0_209
	v_fmamk_f32 v135, v78, 0xbfb8aa3b, v150
	v_fmamk_f32 v154, v79, 0xbfb8aa3b, v151
	v_exp_f32_e32 v135, v135
	v_exp_f32_e32 v154, v154
	v_fmamk_f32 v155, v81, 0xbfb8aa3b, v145
	v_exp_f32_e32 v155, v155
	v_add_f32_e32 v135, 1.0, v135
	v_add_f32_e32 v154, 1.0, v154
	v_rcp_f32_e32 v135, v135
	v_rcp_f32_e32 v154, v154
	v_add_f32_e32 v155, 1.0, v155
	v_rcp_f32_e32 v155, v155
	v_fmamk_f32 v156, v75, 0xbfb8aa3b, v143
	v_cvt_pk_bf16_f32 v154, v135, v154
	v_fmamk_f32 v135, v80, 0xbfb8aa3b, v144
	v_exp_f32_e32 v135, v135
	v_exp_f32_e32 v156, v156
	v_fmamk_f32 v157, v77, 0xbfb8aa3b, v141
	v_exp_f32_e32 v157, v157
	v_add_f32_e32 v135, 1.0, v135
	v_rcp_f32_e32 v135, v135
	v_add_f32_e32 v156, 1.0, v156
	v_rcp_f32_e32 v156, v156
	v_add_f32_e32 v157, 1.0, v157
	v_cvt_pk_bf16_f32 v155, v135, v155
	v_fmamk_f32 v135, v74, 0xbfb8aa3b, v142
	v_exp_f32_e32 v135, v135
	v_rcp_f32_e32 v157, v157
	v_add_f32_e32 v135, 1.0, v135
	v_rcp_f32_e32 v135, v135
	s_nop 0
	v_cvt_pk_bf16_f32 v156, v135, v156
	v_fmamk_f32 v135, v76, 0xbfb8aa3b, v140
	v_exp_f32_e32 v135, v135
	s_nop 0
	v_add_f32_e32 v135, 1.0, v135
	v_rcp_f32_e32 v135, v135
	s_nop 0
	v_cvt_pk_bf16_f32 v157, v135, v157
	global_store_dwordx4 v[152:153], v[154:157], off

; __device__ __forceinline__ unsigned cvt_pk_bf16(float lo, float hi) { const f32x2_t v = {lo, hi}; const bf16x2_t b = __builtin_convertvector(v, bf16x2_t); return __builtin_bit_cast(unsigned, b); }
; #define SG2(v, bb) __builtin_amdgcn_rcpf(1.0f + __builtin_amdgcn_exp2f(__builtin_fmaf((v), -1.4426950408889634f, (bb))))
;     __device__ __forceinline__ void operator()(const f32x4 (&acc)[2][2][4][2], const pg8::Unit& u, int tid, int wr, int wc, int fr, int fq) const {
;     ...
;                         const f32x4 v0 = acc[ai][bj][m][0], v1 = acc[ai][bj][m][1];
;                         u32x4* slot = pk + ((ai * 4 + m) * 2 + bj) * 512;
;                         if (isg) {
;     ...
;                             u32x4 w; w.x = cvt_pk_bf16(SG2(v0[0], b0[0]), SG2(v0[1], b0[1])); w.y = cvt_pk_bf16(SG2(v0[2], b0[2]), SG2(v0[3], b0[3]));
;                             w.z = cvt_pk_bf16(SG2(v1[0], b1[0]), SG2(v1[1], b1[1])); w.w = cvt_pk_bf16(SG2(v1[2], b1[2]), SG2(v1[3], b1[3]));
;     ...
;                             *slot = w;
.LBB0_213:
	s_and_b64 vcc, exec, s[6:7]
	s_cbranch_vccz .LBB0_215
	v_fmamk_f32 v154, v62, 0xbfb8aa3b, v150
	v_fmamk_f32 v155, v63, 0xbfb8aa3b, v151
	v_exp_f32_e32 v154, v154
	v_exp_f32_e32 v155, v155
	v_fmamk_f32 v156, v65, 0xbfb8aa3b, v145
	v_exp_f32_e32 v156, v156
	v_add_f32_e32 v154, 1.0, v154
	v_add_f32_e32 v155, 1.0, v155
	v_rcp_f32_e32 v154, v154
	v_rcp_f32_e32 v155, v155
	v_add_f32_e32 v156, 1.0, v156
	v_rcp_f32_e32 v156, v156
	v_fmamk_f32 v157, v59, 0xbfb8aa3b, v143
	v_cvt_pk_bf16_f32 v154, v154, v155
	v_fmamk_f32 v155, v64, 0xbfb8aa3b, v144
	v_exp_f32_e32 v155, v155
	v_exp_f32_e32 v157, v157
	v_fmamk_f32 v158, v61, 0xbfb8aa3b, v141
	v_exp_f32_e32 v158, v158
	v_add_f32_e32 v155, 1.0, v155
	v_rcp_f32_e32 v155, v155
	v_add_f32_e32 v157, 1.0, v157
	v_rcp_f32_e32 v157, v157
	v_add_f32_e32 v158, 1.0, v158
	v_cvt_pk_bf16_f32 v155, v155, v156
	v_fmamk_f32 v156, v58, 0xbfb8aa3b, v142
	v_exp_f32_e32 v156, v156
	v_rcp_f32_e32 v158, v158
	v_add_f32_e32 v156, 1.0, v156
	v_rcp_f32_e32 v156, v156
	s_nop 0
	v_cvt_pk_bf16_f32 v156, v156, v157
	v_fmamk_f32 v157, v60, 0xbfb8aa3b, v140
	v_exp_f32_e32 v157, v157
	s_nop 0
	v_add_f32_e32 v157, 1.0, v157
	v_rcp_f32_e32 v157, v157
	s_nop 0
	v_cvt_pk_bf16_f32 v157, v157, v158
	global_store_dwordx4 v[152:153], v[154:157], off

; __device__ __forceinline__ unsigned cvt_pk_bf16(float lo, float hi) { const f32x2_t v = {lo, hi}; const bf16x2_t b = __builtin_convertvector(v, bf16x2_t); return __builtin_bit_cast(unsigned, b); }
; #define SG2(v, bb) __builtin_amdgcn_rcpf(1.0f + __builtin_amdgcn_exp2f(__builtin_fmaf((v), -1.4426950408889634f, (bb))))
;     __device__ __forceinline__ void operator()(const f32x4 (&acc)[2][2][4][2], const pg8::Unit& u, int tid, int wr, int wc, int fr, int fq) const {
;     ...
;                         const f32x4 v0 = acc[ai][bj][m][0], v1 = acc[ai][bj][m][1];
;                         u32x4* slot = pk + ((ai * 4 + m) * 2 + bj) * 512;
;                         if (isg) {
;     ...
;                             u32x4 w; w.x = cvt_pk_bf16(SG2(v0[0], b0[0]), SG2(v0[1], b0[1])); w.y = cvt_pk_bf16(SG2(v0[2], b0[2]), SG2(v0[3], b0[3]));
;                             w.z = cvt_pk_bf16(SG2(v1[0], b1[0]), SG2(v1[1], b1[1])); w.w = cvt_pk_bf16(SG2(v1[2], b1[2]), SG2(v1[3], b1[3]));
;     ...
;                             *slot = w;
.LBB0_219:
	s_and_b64 vcc, exec, s[6:7]
	s_cbranch_vccz .LBB0_221
	v_fmamk_f32 v154, v46, 0xbfb8aa3b, v150
	v_fmamk_f32 v155, v47, 0xbfb8aa3b, v151
	v_exp_f32_e32 v154, v154
	v_exp_f32_e32 v155, v155
	v_fmamk_f32 v156, v49, 0xbfb8aa3b, v145
	v_exp_f32_e32 v156, v156
	v_add_f32_e32 v154, 1.0, v154
	v_add_f32_e32 v155, 1.0, v155
	v_rcp_f32_e32 v154, v154
	v_rcp_f32_e32 v155, v155
	v_add_f32_e32 v156, 1.0, v156
	v_rcp_f32_e32 v156, v156
	v_fmamk_f32 v157, v43, 0xbfb8aa3b, v143
	v_cvt_pk_bf16_f32 v154, v154, v155
	v_fmamk_f32 v155, v48, 0xbfb8aa3b, v144
	v_exp_f32_e32 v155, v155
	v_exp_f32_e32 v157, v157
	v_fmamk_f32 v158, v45, 0xbfb8aa3b, v141
	v_exp_f32_e32 v158, v158
	v_add_f32_e32 v155, 1.0, v155
	v_rcp_f32_e32 v155, v155
	v_add_f32_e32 v157, 1.0, v157
	v_rcp_f32_e32 v157, v157
	v_add_f32_e32 v158, 1.0, v158
	v_cvt_pk_bf16_f32 v155, v155, v156
	v_fmamk_f32 v156, v42, 0xbfb8aa3b, v142
	v_exp_f32_e32 v156, v156
	v_rcp_f32_e32 v158, v158
	v_add_f32_e32 v156, 1.0, v156
	v_rcp_f32_e32 v156, v156
	s_nop 0
	v_cvt_pk_bf16_f32 v156, v156, v157
	v_fmamk_f32 v157, v44, 0xbfb8aa3b, v140
	v_exp_f32_e32 v157, v157
	s_nop 0
	v_add_f32_e32 v157, 1.0, v157
	v_rcp_f32_e32 v157, v157
	s_nop 0
	v_cvt_pk_bf16_f32 v157, v157, v158
	global_store_dwordx4 v[152:153], v[154:157], off

; __device__ __forceinline__ unsigned cvt_pk_bf16(float lo, float hi) { const f32x2_t v = {lo, hi}; const bf16x2_t b = __builtin_convertvector(v, bf16x2_t); return __builtin_bit_cast(unsigned, b); }
; #define SG2(v, bb) __builtin_amdgcn_rcpf(1.0f + __builtin_amdgcn_exp2f(__builtin_fmaf((v), -1.4426950408889634f, (bb))))
;     __device__ __forceinline__ void operator()(const f32x4 (&acc)[2][2][4][2], const pg8::Unit& u, int tid, int wr, int wc, int fr, int fq) const {
;     ...
;                         const f32x4 v0 = acc[ai][bj][m][0], v1 = acc[ai][bj][m][1];
;                         u32x4* slot = pk + ((ai * 4 + m) * 2 + bj) * 512;
;                         if (isg) {
;     ...
;                             u32x4 w; w.x = cvt_pk_bf16(SG2(v0[0], b0[0]), SG2(v0[1], b0[1])); w.y = cvt_pk_bf16(SG2(v0[2], b0[2]), SG2(v0[3], b0[3]));
;                             w.z = cvt_pk_bf16(SG2(v1[0], b1[0]), SG2(v1[1], b1[1])); w.w = cvt_pk_bf16(SG2(v1[2], b1[2]), SG2(v1[3], b1[3]));
;     ...
;                             *slot = w;
.LBB0_225:
	s_and_b64 vcc, exec, s[6:7]
	s_cbranch_vccz .LBB0_227
	v_fmamk_f32 v154, v30, 0xbfb8aa3b, v150
	v_fmamk_f32 v155, v31, 0xbfb8aa3b, v151
	v_exp_f32_e32 v154, v154
	v_exp_f32_e32 v155, v155
	v_fmamk_f32 v156, v33, 0xbfb8aa3b, v145
	v_exp_f32_e32 v156, v156
	v_add_f32_e32 v154, 1.0, v154
	v_add_f32_e32 v155, 1.0, v155
	v_rcp_f32_e32 v154, v154
	v_rcp_f32_e32 v155, v155
	v_add_f32_e32 v156, 1.0, v156
	v_rcp_f32_e32 v156, v156
	v_fmamk_f32 v157, v27, 0xbfb8aa3b, v143
	v_cvt_pk_bf16_f32 v154, v154, v155
	v_fmamk_f32 v155, v32, 0xbfb8aa3b, v144
	v_exp_f32_e32 v155, v155
	v_exp_f32_e32 v157, v157
	v_fmamk_f32 v158, v29, 0xbfb8aa3b, v141
	v_exp_f32_e32 v158, v158
	v_add_f32_e32 v155, 1.0, v155
	v_rcp_f32_e32 v155, v155
	v_add_f32_e32 v157, 1.0, v157
	v_rcp_f32_e32 v157, v157
	v_add_f32_e32 v158, 1.0, v158
	v_cvt_pk_bf16_f32 v155, v155, v156
	v_fmamk_f32 v156, v26, 0xbfb8aa3b, v142
	v_exp_f32_e32 v156, v156
	v_rcp_f32_e32 v158, v158
	v_add_f32_e32 v156, 1.0, v156
	v_rcp_f32_e32 v156, v156
	s_nop 0
	v_cvt_pk_bf16_f32 v156, v156, v157
	v_fmamk_f32 v157, v28, 0xbfb8aa3b, v140
	v_exp_f32_e32 v157, v157
	s_nop 0
	v_add_f32_e32 v157, 1.0, v157
	v_rcp_f32_e32 v157, v157
	s_nop 0
	v_cvt_pk_bf16_f32 v157, v157, v158
	global_store_dwordx4 v[152:153], v[154:157], off

; __device__ __forceinline__ unsigned cvt_pk_bf16(float lo, float hi) { const f32x2_t v = {lo, hi}; const bf16x2_t b = __builtin_convertvector(v, bf16x2_t); return __builtin_bit_cast(unsigned, b); }
; #define SG2(v, bb) __builtin_amdgcn_rcpf(1.0f + __builtin_amdgcn_exp2f(__builtin_fmaf((v), -1.4426950408889634f, (bb))))
;     __device__ __forceinline__ void operator()(const f32x4 (&acc)[2][2][4][2], const pg8::Unit& u, int tid, int wr, int wc, int fr, int fq) const {
;     ...
;                         const f32x4 v0 = acc[ai][bj][m][0], v1 = acc[ai][bj][m][1];
;                         u32x4* slot = pk + ((ai * 4 + m) * 2 + bj) * 512;
;                         if (isg) {
;     ...
;                             u32x4 w; w.x = cvt_pk_bf16(SG2(v0[0], b0[0]), SG2(v0[1], b0[1])); w.y = cvt_pk_bf16(SG2(v0[2], b0[2]), SG2(v0[3], b0[3]));
;                             w.z = cvt_pk_bf16(SG2(v1[0], b1[0]), SG2(v1[1], b1[1])); w.w = cvt_pk_bf16(SG2(v1[2], b1[2]), SG2(v1[3], b1[3]));
;     ...
;                             *slot = w;
.LBB0_231:
	s_and_b64 vcc, exec, s[6:7]
	s_cbranch_vccz .LBB0_233
	v_fmac_f32_e32 v140, 0xbfb8aa3b, v12
	v_fmac_f32_e32 v150, 0xbfb8aa3b, v14
	v_fmac_f32_e32 v151, 0xbfb8aa3b, v15
	v_fmac_f32_e32 v144, 0xbfb8aa3b, v16
	v_fmac_f32_e32 v145, 0xbfb8aa3b, v17
	v_fmac_f32_e32 v142, 0xbfb8aa3b, v10
	v_fmac_f32_e32 v143, 0xbfb8aa3b, v11
	v_exp_f32_e32 v140, v140
	v_fmac_f32_e32 v141, 0xbfb8aa3b, v13
	v_exp_f32_e32 v150, v150
	v_exp_f32_e32 v151, v151
	v_exp_f32_e32 v144, v144
	v_exp_f32_e32 v145, v145
	v_exp_f32_e32 v142, v142
	v_exp_f32_e32 v143, v143
	v_exp_f32_e32 v141, v141
	v_add_f32_e32 v140, 1.0, v140
	v_add_f32_e32 v150, 1.0, v150
	v_add_f32_e32 v151, 1.0, v151
	v_add_f32_e32 v144, 1.0, v144
	v_add_f32_e32 v145, 1.0, v145
	v_add_f32_e32 v142, 1.0, v142
	v_add_f32_e32 v143, 1.0, v143
	v_rcp_f32_e32 v154, v140
	v_add_f32_e32 v140, 1.0, v141
	v_rcp_f32_e32 v150, v150
	v_rcp_f32_e32 v151, v151
	v_rcp_f32_e32 v144, v144
	v_rcp_f32_e32 v145, v145
	v_rcp_f32_e32 v142, v142
	v_rcp_f32_e32 v143, v143
	v_rcp_f32_e32 v155, v140
	v_cvt_pk_bf16_f32 v140, v150, v151
	v_cvt_pk_bf16_f32 v141, v144, v145
	v_cvt_pk_bf16_f32 v142, v142, v143
	v_cvt_pk_bf16_f32 v143, v154, v155
	global_store_dwordx4 v[152:153], v[140:143], off

; __device__ __forceinline__ unsigned cvt_pk_bf16(float lo, float hi) { const f32x2_t v = {lo, hi}; const bf16x2_t b = __builtin_convertvector(v, bf16x2_t); return __builtin_bit_cast(unsigned, b); }
; #define SG2(v, bb) __builtin_amdgcn_rcpf(1.0f + __builtin_amdgcn_exp2f(__builtin_fmaf((v), -1.4426950408889634f, (bb))))
;     __device__ __forceinline__ void operator()(const f32x4 (&acc)[2][2][4][2], const pg8::Unit& u, int tid, int wr, int wc, int fr, int fq) const {
;     ...
;                         const f32x4 v0 = acc[ai][bj][m][0], v1 = acc[ai][bj][m][1];
;                         u32x4* slot = pk + ((ai * 4 + m) * 2 + bj) * 512;
;                         if (isg) {
;     ...
;                             u32x4 w; w.x = cvt_pk_bf16(SG2(v0[0], b0[0]), SG2(v0[1], b0[1])); w.y = cvt_pk_bf16(SG2(v0[2], b0[2]), SG2(v0[3], b0[3]));
;                             w.z = cvt_pk_bf16(SG2(v1[0], b1[0]), SG2(v1[1], b1[1])); w.w = cvt_pk_bf16(SG2(v1[2], b1[2]), SG2(v1[3], b1[3]));
;     ...
;                             *slot = w;
.LBB0_239:
	s_and_b64 vcc, exec, s[6:7]
	s_cbranch_vccz .LBB0_241
	v_fmamk_f32 v154, v118, 0xbfb8aa3b, v150
	v_fmamk_f32 v155, v119, 0xbfb8aa3b, v151
	v_exp_f32_e32 v154, v154
	v_exp_f32_e32 v155, v155
	v_fmamk_f32 v156, v121, 0xbfb8aa3b, v145
	v_exp_f32_e32 v156, v156
	v_add_f32_e32 v154, 1.0, v154
	v_add_f32_e32 v155, 1.0, v155
	v_rcp_f32_e32 v154, v154
	v_rcp_f32_e32 v155, v155
	v_add_f32_e32 v156, 1.0, v156
	v_rcp_f32_e32 v156, v156
	v_fmamk_f32 v157, v115, 0xbfb8aa3b, v143
	v_cvt_pk_bf16_f32 v154, v154, v155
	v_fmamk_f32 v155, v120, 0xbfb8aa3b, v144
	v_exp_f32_e32 v155, v155
	v_exp_f32_e32 v157, v157
	v_fmamk_f32 v158, v117, 0xbfb8aa3b, v141
	v_exp_f32_e32 v158, v158
	v_add_f32_e32 v155, 1.0, v155
	v_rcp_f32_e32 v155, v155
	v_add_f32_e32 v157, 1.0, v157
	v_rcp_f32_e32 v157, v157
	v_add_f32_e32 v158, 1.0, v158
	v_cvt_pk_bf16_f32 v155, v155, v156
	v_fmamk_f32 v156, v114, 0xbfb8aa3b, v142
	v_exp_f32_e32 v156, v156
	v_rcp_f32_e32 v158, v158
	v_add_f32_e32 v156, 1.0, v156
	v_rcp_f32_e32 v156, v156
	s_nop 0
	v_cvt_pk_bf16_f32 v156, v156, v157
	v_fmamk_f32 v157, v116, 0xbfb8aa3b, v140
	v_exp_f32_e32 v157, v157
	s_nop 0
	v_add_f32_e32 v157, 1.0, v157
	v_rcp_f32_e32 v157, v157
	s_nop 0
	v_cvt_pk_bf16_f32 v157, v157, v158
	global_store_dwordx4 v[152:153], v[154:157], off

; __device__ __forceinline__ unsigned cvt_pk_bf16(float lo, float hi) { const f32x2_t v = {lo, hi}; const bf16x2_t b = __builtin_convertvector(v, bf16x2_t); return __builtin_bit_cast(unsigned, b); }
; #define SG2(v, bb) __builtin_amdgcn_rcpf(1.0f + __builtin_amdgcn_exp2f(__builtin_fmaf((v), -1.4426950408889634f, (bb))))
;     __device__ __forceinline__ void operator()(const f32x4 (&acc)[2][2][4][2], const pg8::Unit& u, int tid, int wr, int wc, int fr, int fq) const {
;     ...
;                         const f32x4 v0 = acc[ai][bj][m][0], v1 = acc[ai][bj][m][1];
;                         u32x4* slot = pk + ((ai * 4 + m) * 2 + bj) * 512;
;                         if (isg) {
;     ...
;                             u32x4 w; w.x = cvt_pk_bf16(SG2(v0[0], b0[0]), SG2(v0[1], b0[1])); w.y = cvt_pk_bf16(SG2(v0[2], b0[2]), SG2(v0[3], b0[3]));
;                             w.z = cvt_pk_bf16(SG2(v1[0], b1[0]), SG2(v1[1], b1[1])); w.w = cvt_pk_bf16(SG2(v1[2], b1[2]), SG2(v1[3], b1[3]));
;     ...
;                             *slot = w;
.LBB0_245:
	s_and_b64 vcc, exec, s[6:7]
	s_cbranch_vccz .LBB0_247
	v_fmamk_f32 v154, v102, 0xbfb8aa3b, v150
	v_fmamk_f32 v155, v103, 0xbfb8aa3b, v151
	v_exp_f32_e32 v154, v154
	v_exp_f32_e32 v155, v155
	v_fmamk_f32 v156, v105, 0xbfb8aa3b, v145
	v_exp_f32_e32 v156, v156
	v_add_f32_e32 v154, 1.0, v154
	v_add_f32_e32 v155, 1.0, v155
	v_rcp_f32_e32 v154, v154
	v_rcp_f32_e32 v155, v155
	v_add_f32_e32 v156, 1.0, v156
	v_rcp_f32_e32 v156, v156
	v_fmamk_f32 v157, v99, 0xbfb8aa3b, v143
	v_cvt_pk_bf16_f32 v154, v154, v155
	v_fmamk_f32 v155, v104, 0xbfb8aa3b, v144
	v_exp_f32_e32 v155, v155
	v_exp_f32_e32 v157, v157
	v_fmamk_f32 v158, v101, 0xbfb8aa3b, v141
	v_exp_f32_e32 v158, v158
	v_add_f32_e32 v155, 1.0, v155
	v_rcp_f32_e32 v155, v155
	v_add_f32_e32 v157, 1.0, v157
	v_rcp_f32_e32 v157, v157
	v_add_f32_e32 v158, 1.0, v158
	v_cvt_pk_bf16_f32 v155, v155, v156
	v_fmamk_f32 v156, v98, 0xbfb8aa3b, v142
	v_exp_f32_e32 v156, v156
	v_rcp_f32_e32 v158, v158
	v_add_f32_e32 v156, 1.0, v156
	v_rcp_f32_e32 v156, v156
	s_nop 0
	v_cvt_pk_bf16_f32 v156, v156, v157
	v_fmamk_f32 v157, v100, 0xbfb8aa3b, v140
	v_exp_f32_e32 v157, v157
	s_nop 0
	v_add_f32_e32 v157, 1.0, v157
	v_rcp_f32_e32 v157, v157
	s_nop 0
	v_cvt_pk_bf16_f32 v157, v157, v158
	global_store_dwordx4 v[152:153], v[154:157], off

; __device__ __forceinline__ unsigned cvt_pk_bf16(float lo, float hi) { const f32x2_t v = {lo, hi}; const bf16x2_t b = __builtin_convertvector(v, bf16x2_t); return __builtin_bit_cast(unsigned, b); }
; #define SG2(v, bb) __builtin_amdgcn_rcpf(1.0f + __builtin_amdgcn_exp2f(__builtin_fmaf((v), -1.4426950408889634f, (bb))))
;     __device__ __forceinline__ void operator()(const f32x4 (&acc)[2][2][4][2], const pg8::Unit& u, int tid, int wr, int wc, int fr, int fq) const {
;     ...
;                         const f32x4 v0 = acc[ai][bj][m][0], v1 = acc[ai][bj][m][1];
;                         u32x4* slot = pk + ((ai * 4 + m) * 2 + bj) * 512;
;                         if (isg) {
;     ...
;                             u32x4 w; w.x = cvt_pk_bf16(SG2(v0[0], b0[0]), SG2(v0[1], b0[1])); w.y = cvt_pk_bf16(SG2(v0[2], b0[2]), SG2(v0[3], b0[3]));
;                             w.z = cvt_pk_bf16(SG2(v1[0], b1[0]), SG2(v1[1], b1[1])); w.w = cvt_pk_bf16(SG2(v1[2], b1[2]), SG2(v1[3], b1[3]));
;     ...
;                             *slot = w;
.LBB0_251:
	s_and_b64 vcc, exec, s[6:7]
	s_cbranch_vccz .LBB0_253
	v_fmamk_f32 v154, v86, 0xbfb8aa3b, v150
	v_fmamk_f32 v155, v87, 0xbfb8aa3b, v151
	v_exp_f32_e32 v154, v154
	v_exp_f32_e32 v155, v155
	v_fmamk_f32 v156, v89, 0xbfb8aa3b, v145
	v_exp_f32_e32 v156, v156
	v_add_f32_e32 v154, 1.0, v154
	v_add_f32_e32 v155, 1.0, v155
	v_rcp_f32_e32 v154, v154
	v_rcp_f32_e32 v155, v155
	v_add_f32_e32 v156, 1.0, v156
	v_rcp_f32_e32 v156, v156
	v_fmamk_f32 v157, v83, 0xbfb8aa3b, v143
	v_cvt_pk_bf16_f32 v154, v154, v155
	v_fmamk_f32 v155, v88, 0xbfb8aa3b, v144
	v_exp_f32_e32 v155, v155
	v_exp_f32_e32 v157, v157
	v_fmamk_f32 v158, v85, 0xbfb8aa3b, v141
	v_exp_f32_e32 v158, v158
	v_add_f32_e32 v155, 1.0, v155
	v_rcp_f32_e32 v155, v155
	v_add_f32_e32 v157, 1.0, v157
	v_rcp_f32_e32 v157, v157
	v_add_f32_e32 v158, 1.0, v158
	v_cvt_pk_bf16_f32 v155, v155, v156
	v_fmamk_f32 v156, v82, 0xbfb8aa3b, v142
	v_exp_f32_e32 v156, v156
	v_rcp_f32_e32 v158, v158
	v_add_f32_e32 v156, 1.0, v156
	v_rcp_f32_e32 v156, v156
	s_nop 0
	v_cvt_pk_bf16_f32 v156, v156, v157
	v_fmamk_f32 v157, v84, 0xbfb8aa3b, v140
	v_exp_f32_e32 v157, v157
	s_nop 0
	v_add_f32_e32 v157, 1.0, v157
	v_rcp_f32_e32 v157, v157
	s_nop 0
	v_cvt_pk_bf16_f32 v157, v157, v158
	global_store_dwordx4 v[152:153], v[154:157], off

; __device__ __forceinline__ unsigned cvt_pk_bf16(float lo, float hi) { const f32x2_t v = {lo, hi}; const bf16x2_t b = __builtin_convertvector(v, bf16x2_t); return __builtin_bit_cast(unsigned, b); }
; #define SG2(v, bb) __builtin_amdgcn_rcpf(1.0f + __builtin_amdgcn_exp2f(__builtin_fmaf((v), -1.4426950408889634f, (bb))))
;     __device__ __forceinline__ void operator()(const f32x4 (&acc)[2][2][4][2], const pg8::Unit& u, int tid, int wr, int wc, int fr, int fq) const {
;     ...
;                         const f32x4 v0 = acc[ai][bj][m][0], v1 = acc[ai][bj][m][1];
;                         u32x4* slot = pk + ((ai * 4 + m) * 2 + bj) * 512;
;                         if (isg) {
;     ...
;                             u32x4 w; w.x = cvt_pk_bf16(SG2(v0[0], b0[0]), SG2(v0[1], b0[1])); w.y = cvt_pk_bf16(SG2(v0[2], b0[2]), SG2(v0[3], b0[3]));
;                             w.z = cvt_pk_bf16(SG2(v1[0], b1[0]), SG2(v1[1], b1[1])); w.w = cvt_pk_bf16(SG2(v1[2], b1[2]), SG2(v1[3], b1[3]));
;     ...
;                             *slot = w;
.LBB0_257:
	s_and_b64 vcc, exec, s[6:7]
	s_cbranch_vccz .LBB0_259
	v_fmamk_f32 v154, v70, 0xbfb8aa3b, v150
	v_fmamk_f32 v155, v71, 0xbfb8aa3b, v151
	v_exp_f32_e32 v154, v154
	v_exp_f32_e32 v155, v155
	v_fmamk_f32 v156, v73, 0xbfb8aa3b, v145
	v_exp_f32_e32 v156, v156
	v_add_f32_e32 v154, 1.0, v154
	v_add_f32_e32 v155, 1.0, v155
	v_rcp_f32_e32 v154, v154
	v_rcp_f32_e32 v155, v155
	v_add_f32_e32 v156, 1.0, v156
	v_rcp_f32_e32 v156, v156
	v_fmamk_f32 v157, v67, 0xbfb8aa3b, v143
	v_cvt_pk_bf16_f32 v154, v154, v155
	v_fmamk_f32 v155, v72, 0xbfb8aa3b, v144
	v_exp_f32_e32 v155, v155
	v_exp_f32_e32 v157, v157
	v_fmamk_f32 v158, v69, 0xbfb8aa3b, v141
	v_exp_f32_e32 v158, v158
	v_add_f32_e32 v155, 1.0, v155
	v_rcp_f32_e32 v155, v155
	v_add_f32_e32 v157, 1.0, v157
	v_rcp_f32_e32 v157, v157
	v_add_f32_e32 v158, 1.0, v158
	v_cvt_pk_bf16_f32 v155, v155, v156
	v_fmamk_f32 v156, v66, 0xbfb8aa3b, v142
	v_exp_f32_e32 v156, v156
	v_rcp_f32_e32 v158, v158
	v_add_f32_e32 v156, 1.0, v156
	v_rcp_f32_e32 v156, v156
	s_nop 0
	v_cvt_pk_bf16_f32 v156, v156, v157
	v_fmamk_f32 v157, v68, 0xbfb8aa3b, v140
	v_exp_f32_e32 v157, v157
	s_nop 0
	v_add_f32_e32 v157, 1.0, v157
	v_rcp_f32_e32 v157, v157
	s_nop 0
	v_cvt_pk_bf16_f32 v157, v157, v158
	global_store_dwordx4 v[152:153], v[154:157], off

; __device__ __forceinline__ unsigned cvt_pk_bf16(float lo, float hi) { const f32x2_t v = {lo, hi}; const bf16x2_t b = __builtin_convertvector(v, bf16x2_t); return __builtin_bit_cast(unsigned, b); }
; #define SG2(v, bb) __builtin_amdgcn_rcpf(1.0f + __builtin_amdgcn_exp2f(__builtin_fmaf((v), -1.4426950408889634f, (bb))))
;     __device__ __forceinline__ void operator()(const f32x4 (&acc)[2][2][4][2], const pg8::Unit& u, int tid, int wr, int wc, int fr, int fq) const {
;     ...
;                         const f32x4 v0 = acc[ai][bj][m][0], v1 = acc[ai][bj][m][1];
;                         u32x4* slot = pk + ((ai * 4 + m) * 2 + bj) * 512;
;                         if (isg) {
;     ...
;                             u32x4 w; w.x = cvt_pk_bf16(SG2(v0[0], b0[0]), SG2(v0[1], b0[1])); w.y = cvt_pk_bf16(SG2(v0[2], b0[2]), SG2(v0[3], b0[3]));
;                             w.z = cvt_pk_bf16(SG2(v1[0], b1[0]), SG2(v1[1], b1[1])); w.w = cvt_pk_bf16(SG2(v1[2], b1[2]), SG2(v1[3], b1[3]));
;     ...
;                             *slot = w;
.LBB0_263:
	s_and_b64 vcc, exec, s[6:7]
	s_cbranch_vccz .LBB0_265
	v_fmamk_f32 v135, v54, 0xbfb8aa3b, v150
	v_fmamk_f32 v154, v55, 0xbfb8aa3b, v151
	v_exp_f32_e32 v135, v135
	v_exp_f32_e32 v154, v154
	v_fmamk_f32 v155, v57, 0xbfb8aa3b, v145
	v_exp_f32_e32 v155, v155
	v_add_f32_e32 v135, 1.0, v135
	v_add_f32_e32 v154, 1.0, v154
	v_rcp_f32_e32 v135, v135
	v_rcp_f32_e32 v154, v154
	v_add_f32_e32 v155, 1.0, v155
	v_rcp_f32_e32 v155, v155
	v_fmamk_f32 v156, v51, 0xbfb8aa3b, v143
	v_cvt_pk_bf16_f32 v154, v135, v154
	v_fmamk_f32 v135, v56, 0xbfb8aa3b, v144
	v_exp_f32_e32 v135, v135
	v_exp_f32_e32 v156, v156
	v_fmamk_f32 v157, v53, 0xbfb8aa3b, v141
	v_exp_f32_e32 v157, v157
	v_add_f32_e32 v135, 1.0, v135
	v_rcp_f32_e32 v135, v135
	v_add_f32_e32 v156, 1.0, v156
	v_rcp_f32_e32 v156, v156
	v_add_f32_e32 v157, 1.0, v157
	v_cvt_pk_bf16_f32 v155, v135, v155
	v_fmamk_f32 v135, v50, 0xbfb8aa3b, v142
	v_exp_f32_e32 v135, v135
	v_rcp_f32_e32 v157, v157
	v_add_f32_e32 v135, 1.0, v135
	v_rcp_f32_e32 v135, v135
	s_nop 0
	v_cvt_pk_bf16_f32 v156, v135, v156
	v_fmamk_f32 v135, v52, 0xbfb8aa3b, v140
	v_exp_f32_e32 v135, v135
	s_nop 0
	v_add_f32_e32 v135, 1.0, v135
	v_rcp_f32_e32 v135, v135
	s_nop 0
	v_cvt_pk_bf16_f32 v157, v135, v157
	global_store_dwordx4 v[152:153], v[154:157], off

; __device__ __forceinline__ unsigned cvt_pk_bf16(float lo, float hi) { const f32x2_t v = {lo, hi}; const bf16x2_t b = __builtin_convertvector(v, bf16x2_t); return __builtin_bit_cast(unsigned, b); }
; #define SG2(v, bb) __builtin_amdgcn_rcpf(1.0f + __builtin_amdgcn_exp2f(__builtin_fmaf((v), -1.4426950408889634f, (bb))))
;     __device__ __forceinline__ void operator()(const f32x4 (&acc)[2][2][4][2], const pg8::Unit& u, int tid, int wr, int wc, int fr, int fq) const {
;     ...
;                         const f32x4 v0 = acc[ai][bj][m][0], v1 = acc[ai][bj][m][1];
;                         u32x4* slot = pk + ((ai * 4 + m) * 2 + bj) * 512;
;                         if (isg) {
;     ...
;                             u32x4 w; w.x = cvt_pk_bf16(SG2(v0[0], b0[0]), SG2(v0[1], b0[1])); w.y = cvt_pk_bf16(SG2(v0[2], b0[2]), SG2(v0[3], b0[3]));
;                             w.z = cvt_pk_bf16(SG2(v1[0], b1[0]), SG2(v1[1], b1[1])); w.w = cvt_pk_bf16(SG2(v1[2], b1[2]), SG2(v1[3], b1[3]));
;     ...
;                             *slot = w;
.LBB0_269:
	s_and_b64 vcc, exec, s[6:7]
	s_cbranch_vccz .LBB0_271
	v_fmamk_f32 v135, v38, 0xbfb8aa3b, v150
	v_fmamk_f32 v154, v39, 0xbfb8aa3b, v151
	v_exp_f32_e32 v135, v135
	v_exp_f32_e32 v154, v154
	v_fmamk_f32 v155, v41, 0xbfb8aa3b, v145
	v_exp_f32_e32 v155, v155
	v_add_f32_e32 v135, 1.0, v135
	v_add_f32_e32 v154, 1.0, v154
	v_rcp_f32_e32 v135, v135
	v_rcp_f32_e32 v154, v154
	v_add_f32_e32 v155, 1.0, v155
	v_rcp_f32_e32 v155, v155
	v_fmamk_f32 v156, v35, 0xbfb8aa3b, v143
	v_cvt_pk_bf16_f32 v154, v135, v154
	v_fmamk_f32 v135, v40, 0xbfb8aa3b, v144
	v_exp_f32_e32 v135, v135
	v_exp_f32_e32 v156, v156
	v_fmamk_f32 v157, v37, 0xbfb8aa3b, v141
	v_exp_f32_e32 v157, v157
	v_add_f32_e32 v135, 1.0, v135
	v_rcp_f32_e32 v135, v135
	v_add_f32_e32 v156, 1.0, v156
	v_rcp_f32_e32 v156, v156
	v_add_f32_e32 v157, 1.0, v157
	v_cvt_pk_bf16_f32 v155, v135, v155
	v_fmamk_f32 v135, v34, 0xbfb8aa3b, v142
	v_exp_f32_e32 v135, v135
	v_rcp_f32_e32 v157, v157
	v_add_f32_e32 v135, 1.0, v135
	v_rcp_f32_e32 v135, v135
	s_nop 0
	v_cvt_pk_bf16_f32 v156, v135, v156
	v_fmamk_f32 v135, v36, 0xbfb8aa3b, v140
	v_exp_f32_e32 v135, v135
	s_nop 0
	v_add_f32_e32 v135, 1.0, v135
	v_rcp_f32_e32 v135, v135
	s_nop 0
	v_cvt_pk_bf16_f32 v157, v135, v157
	global_store_dwordx4 v[152:153], v[154:157], off

; __device__ __forceinline__ unsigned cvt_pk_bf16(float lo, float hi) { const f32x2_t v = {lo, hi}; const bf16x2_t b = __builtin_convertvector(v, bf16x2_t); return __builtin_bit_cast(unsigned, b); }
; #define SG2(v, bb) __builtin_amdgcn_rcpf(1.0f + __builtin_amdgcn_exp2f(__builtin_fmaf((v), -1.4426950408889634f, (bb))))
;     __device__ __forceinline__ void operator()(const f32x4 (&acc)[2][2][4][2], const pg8::Unit& u, int tid, int wr, int wc, int fr, int fq) const {
;     ...
;                         const f32x4 v0 = acc[ai][bj][m][0], v1 = acc[ai][bj][m][1];
;                         u32x4* slot = pk + ((ai * 4 + m) * 2 + bj) * 512;
;                         if (isg) {
;     ...
;                             u32x4 w; w.x = cvt_pk_bf16(SG2(v0[0], b0[0]), SG2(v0[1], b0[1])); w.y = cvt_pk_bf16(SG2(v0[2], b0[2]), SG2(v0[3], b0[3]));
;                             w.z = cvt_pk_bf16(SG2(v1[0], b1[0]), SG2(v1[1], b1[1])); w.w = cvt_pk_bf16(SG2(v1[2], b1[2]), SG2(v1[3], b1[3]));
;     ...
;                             *slot = w;
.LBB0_275:
	s_and_b64 vcc, exec, s[6:7]
	s_cbranch_vccz .LBB0_277
	v_fmamk_f32 v135, v22, 0xbfb8aa3b, v150
	v_fmamk_f32 v154, v23, 0xbfb8aa3b, v151
	v_exp_f32_e32 v135, v135
	v_exp_f32_e32 v154, v154
	v_fmamk_f32 v155, v25, 0xbfb8aa3b, v145
	v_exp_f32_e32 v155, v155
	v_add_f32_e32 v135, 1.0, v135
	v_add_f32_e32 v154, 1.0, v154
	v_rcp_f32_e32 v135, v135
	v_rcp_f32_e32 v154, v154
	v_add_f32_e32 v155, 1.0, v155
	v_rcp_f32_e32 v155, v155
	v_fmamk_f32 v156, v19, 0xbfb8aa3b, v143
	v_cvt_pk_bf16_f32 v154, v135, v154
	v_fmamk_f32 v135, v24, 0xbfb8aa3b, v144
	v_exp_f32_e32 v135, v135
	v_exp_f32_e32 v156, v156
	v_fmamk_f32 v157, v21, 0xbfb8aa3b, v141
	v_exp_f32_e32 v157, v157
	v_add_f32_e32 v135, 1.0, v135
	v_rcp_f32_e32 v135, v135
	v_add_f32_e32 v156, 1.0, v156
	v_rcp_f32_e32 v156, v156
	v_add_f32_e32 v157, 1.0, v157
	v_cvt_pk_bf16_f32 v155, v135, v155
	v_fmamk_f32 v135, v18, 0xbfb8aa3b, v142
	v_exp_f32_e32 v135, v135
	v_rcp_f32_e32 v157, v157
	v_add_f32_e32 v135, 1.0, v135
	v_rcp_f32_e32 v135, v135
	s_nop 0
	v_cvt_pk_bf16_f32 v156, v135, v156
	v_fmamk_f32 v135, v20, 0xbfb8aa3b, v140
	v_exp_f32_e32 v135, v135
	s_nop 0
	v_add_f32_e32 v135, 1.0, v135
	v_rcp_f32_e32 v135, v135
	s_nop 0
	v_cvt_pk_bf16_f32 v157, v135, v157
	global_store_dwordx4 v[152:153], v[154:157], off

; __device__ __forceinline__ unsigned cvt_pk_bf16(float lo, float hi) { const f32x2_t v = {lo, hi}; const bf16x2_t b = __builtin_convertvector(v, bf16x2_t); return __builtin_bit_cast(unsigned, b); }
; #define SG2(v, bb) __builtin_amdgcn_rcpf(1.0f + __builtin_amdgcn_exp2f(__builtin_fmaf((v), -1.4426950408889634f, (bb))))
;     __device__ __forceinline__ void operator()(const f32x4 (&acc)[2][2][4][2], const pg8::Unit& u, int tid, int wr, int wc, int fr, int fq) const {
;     ...
;                         const f32x4 v0 = acc[ai][bj][m][0], v1 = acc[ai][bj][m][1];
;                         u32x4* slot = pk + ((ai * 4 + m) * 2 + bj) * 512;
;                         if (isg) {
;     ...
;                             u32x4 w; w.x = cvt_pk_bf16(SG2(v0[0], b0[0]), SG2(v0[1], b0[1])); w.y = cvt_pk_bf16(SG2(v0[2], b0[2]), SG2(v0[3], b0[3]));
;                             w.z = cvt_pk_bf16(SG2(v1[0], b1[0]), SG2(v1[1], b1[1])); w.w = cvt_pk_bf16(SG2(v1[2], b1[2]), SG2(v1[3], b1[3]));
;     ...
;                             *slot = w;
.LBB0_281:
	s_and_b64 vcc, exec, s[6:7]
	s_cbranch_vccz .LBB0_283
	v_fmac_f32_e32 v140, 0xbfb8aa3b, v4
	v_fmac_f32_e32 v150, 0xbfb8aa3b, v6
	v_fmac_f32_e32 v151, 0xbfb8aa3b, v7
	v_fmac_f32_e32 v144, 0xbfb8aa3b, v8
	v_fmac_f32_e32 v145, 0xbfb8aa3b, v9
	v_fmac_f32_e32 v142, 0xbfb8aa3b, v2
	v_fmac_f32_e32 v143, 0xbfb8aa3b, v3
	v_exp_f32_e32 v140, v140
	v_fmac_f32_e32 v141, 0xbfb8aa3b, v5
	v_exp_f32_e32 v135, v150
	v_exp_f32_e32 v136, v151
	v_exp_f32_e32 v137, v144
	v_exp_f32_e32 v144, v145
	v_exp_f32_e32 v142, v142
	v_exp_f32_e32 v143, v143
	v_exp_f32_e32 v141, v141
	v_add_f32_e32 v140, 1.0, v140
	v_add_f32_e32 v135, 1.0, v135
	v_add_f32_e32 v136, 1.0, v136
	v_add_f32_e32 v137, 1.0, v137
	v_add_f32_e32 v144, 1.0, v144
	v_add_f32_e32 v142, 1.0, v142
	v_add_f32_e32 v143, 1.0, v143
	v_rcp_f32_e32 v145, v140
	v_add_f32_e32 v140, 1.0, v141
	v_rcp_f32_e32 v135, v135
	v_rcp_f32_e32 v136, v136
	v_rcp_f32_e32 v137, v137
	v_rcp_f32_e32 v144, v144
	v_rcp_f32_e32 v142, v142
	v_rcp_f32_e32 v143, v143
	v_rcp_f32_e32 v150, v140
	v_cvt_pk_bf16_f32 v140, v135, v136
	v_cvt_pk_bf16_f32 v141, v137, v144
	v_cvt_pk_bf16_f32 v142, v142, v143
	v_cvt_pk_bf16_f32 v143, v145, v150
	global_store_dwordx4 v[138:139], v[140:143], off

; __device__ __forceinline__ unsigned cvt_pk_bf16(float lo, float hi) { const f32x2_t v = {lo, hi}; const bf16x2_t b = __builtin_convertvector(v, bf16x2_t); return __builtin_bit_cast(unsigned, b); }
; __device__ __forceinline__ float sigmoidf_(float x) { return __builtin_amdgcn_rcpf(1.0f + __expf(-x)); }
;     __device__ __forceinline__ void operator()(const f32x4 (&acc)[2][2][4][2], const pg8::Unit& u, int tid, int wr, int wc, int fr, int fq) const {
;     ...
;             const int col0 = u.pn * 128 + wc * 32 + 8 * fq;
; #pragma unroll
;             for (int ai = 0; ai < 2; ++ai)
; #pragma unroll
;                 for (int m = 0; m < 4; ++m) {
;                     float r[8];
; #pragma unroll
;                     for (int n = 0; n < 2; ++n)
; #pragma unroll
;                         for (int e = 0; e < 4; ++e) { const float av = acc[ai][0][m][n][e], bv = acc[ai][1][m][n][e]; r[n * 4 + e] = av * sigmoidf_(av) * bv; }
;                     u32x4 w; w.x = cvt_pk_bf16(r[0], r[1]); w.y = cvt_pk_bf16(r[2], r[3]); w.z = cvt_pk_bf16(r[4], r[5]); w.w = cvt_pk_bf16(r[6], r[7]);
;                     *(u32x4*)(O + (size_t)(row0 + ai * 128 + m * 16) * DFF + col0) = w; }
.LBB0_284:
	s_and_b64 vcc, exec, s[6:7]
	s_cbranch_vccz .LBB0_286
	v_mul_f32_e32 v135, 0xbfb8aa3b, v126
	v_exp_f32_e32 v135, v135
	v_mul_f32_e32 v136, 0xbfb8aa3b, v127
	v_exp_f32_e32 v137, v136
	s_lshl_b32 s6, s52, 7
	v_add_f32_e32 v135, 1.0, v135
	v_rcp_f32_e32 v136, v135
	v_add_f32_e32 v135, 1.0, v137
	v_rcp_f32_e32 v137, v135
	v_lshl_or_b32 v135, v0, 3, s6
	v_or_b32_e32 v138, s53, v135
	v_mul_f32_e32 v135, 0xbfb8aa3b, v128
	v_exp_f32_e32 v135, v135
	v_mul_f32_e32 v140, 0xbfb8aa3b, v129
	v_exp_f32_e32 v141, v140
	v_mul_f32_e32 v142, 0xbfb8aa3b, v123
	v_add_f32_e32 v135, 1.0, v135
	v_rcp_f32_e32 v140, v135
	v_add_f32_e32 v135, 1.0, v141
	v_rcp_f32_e32 v141, v135
	v_mul_f32_e32 v135, 0xbfb8aa3b, v122
	v_exp_f32_e32 v135, v135
	v_exp_f32_e32 v143, v142
	v_pk_mul_f32 v[140:141], v[128:129], v[140:141]
	v_pk_mul_f32 v[136:137], v[126:127], v[136:137]
	v_add_f32_e32 v135, 1.0, v135
	v_rcp_f32_e32 v142, v135
	v_add_f32_e32 v135, 1.0, v143
	v_mul_f32_e32 v143, 0xbfb8aa3b, v124
	v_exp_f32_e32 v144, v143
	v_mul_f32_e32 v143, 0xbfb8aa3b, v125
	v_exp_f32_e32 v145, v143
	v_rcp_f32_e32 v143, v135
	v_add_f32_e32 v135, 1.0, v144
	v_rcp_f32_e32 v144, v135
	v_add_f32_e32 v135, 1.0, v145
	v_rcp_f32_e32 v145, v135
	v_pk_mul_f32 v[150:151], v[120:121], v[140:141]
	v_pk_mul_f32 v[140:141], v[122:123], v[142:143]
	v_mul_f32_e32 v135, 0xbfb8aa3b, v110
	v_pk_mul_f32 v[142:143], v[114:115], v[140:141]
	v_pk_mul_f32 v[140:141], v[124:125], v[144:145]
	v_cvt_pk_bf16_f32 v142, v142, v143
	v_pk_mul_f32 v[144:145], v[116:117], v[140:141]
	v_exp_f32_e32 v135, v135
	v_cvt_pk_bf16_f32 v143, v144, v145
	v_mul_f32_e32 v144, 0xbfb8aa3b, v111
	v_cvt_pk_bf16_f32 v141, v150, v151
	v_exp_f32_e32 v151, v144
	v_pk_mul_f32 v[136:137], v[118:119], v[136:137]
	v_ashrrev_i32_e32 v139, 31, v138
	v_cvt_pk_bf16_f32 v140, v136, v137
	v_mov_b64_e32 v[136:137], s[50:51]
	s_movk_i32 s10, 0x1600
	v_add_f32_e32 v135, 1.0, v135
	v_mad_i64_i32 v[144:145], s[6:7], v131, s10, v[136:137]
	v_rcp_f32_e32 v150, v135
	v_add_f32_e32 v135, 1.0, v151
	v_lshlrev_b64 v[138:139], 1, v[138:139]
	v_rcp_f32_e32 v151, v135
	v_lshl_add_u64 v[144:145], v[144:145], 0, v[138:139]
	v_mul_f32_e32 v135, 0xbfb8aa3b, v112
	global_store_dwordx4 v[144:145], v[140:143], off nt
	v_exp_f32_e32 v135, v135
	v_mul_f32_e32 v144, 0xbfb8aa3b, v107
	v_mul_f32_e32 v142, 0xbfb8aa3b, v113
	v_exp_f32_e32 v143, v142
	v_add_f32_e32 v135, 1.0, v135
	v_rcp_f32_e32 v142, v135
	v_exp_f32_e32 v145, v144
	v_add_f32_e32 v135, 1.0, v143
	v_rcp_f32_e32 v143, v135
	v_mul_f32_e32 v135, 0xbfb8aa3b, v106
	v_exp_f32_e32 v135, v135
	v_pk_mul_f32 v[140:141], v[110:111], v[150:151]
	v_pk_mul_f32 v[142:143], v[112:113], v[142:143]
	v_pk_mul_f32 v[140:141], v[102:103], v[140:141]
	v_add_f32_e32 v135, 1.0, v135
	v_rcp_f32_e32 v144, v135
	v_add_f32_e32 v135, 1.0, v145
	v_mul_f32_e32 v145, 0xbfb8aa3b, v108
	v_exp_f32_e32 v150, v145
	v_mul_f32_e32 v145, 0xbfb8aa3b, v109
	v_exp_f32_e32 v151, v145
	v_rcp_f32_e32 v145, v135
	v_add_f32_e32 v135, 1.0, v150
	v_rcp_f32_e32 v150, v135
	v_add_f32_e32 v135, 1.0, v151
	v_rcp_f32_e32 v151, v135
	v_pk_mul_f32 v[144:145], v[106:107], v[144:145]
	v_pk_mul_f32 v[142:143], v[104:105], v[142:143]
	v_pk_mul_f32 v[144:145], v[98:99], v[144:145]
	v_mul_f32_e32 v135, 0xbfb8aa3b, v94
	v_cvt_pk_bf16_f32 v140, v140, v141
	v_cvt_pk_bf16_f32 v141, v142, v143
	v_cvt_pk_bf16_f32 v142, v144, v145
	v_exp_f32_e32 v135, v135
	v_mul_f32_e32 v144, 0xbfb8aa3b, v95
	v_exp_f32_e32 v145, v144
	v_pk_mul_f32 v[150:151], v[108:109], v[150:151]
	v_add_f32_e32 v135, 1.0, v135
	v_pk_mul_f32 v[150:151], v[100:101], v[150:151]
	v_rcp_f32_e32 v144, v135
	v_cvt_pk_bf16_f32 v143, v150, v151
	v_or_b32_e32 v150, 16, v131
	v_add_f32_e32 v135, 1.0, v145
	v_mad_i64_i32 v[150:151], s[6:7], v150, s10, v[136:137]
	v_rcp_f32_e32 v145, v135
	v_lshl_add_u64 v[150:151], v[150:151], 0, v[138:139]
	v_mul_f32_e32 v135, 0xbfb8aa3b, v96
	global_store_dwordx4 v[150:151], v[140:143], off nt
	v_exp_f32_e32 v135, v135
	s_nop 0
	v_mul_f32_e32 v142, 0xbfb8aa3b, v97
	v_exp_f32_e32 v143, v142
	v_add_f32_e32 v135, 1.0, v135
	v_rcp_f32_e32 v142, v135
	v_pk_mul_f32 v[140:141], v[94:95], v[144:145]
	v_add_f32_e32 v135, 1.0, v143
	v_rcp_f32_e32 v143, v135
	v_mul_f32_e32 v135, 0xbfb8aa3b, v90
	v_exp_f32_e32 v135, v135
	v_mul_f32_e32 v144, 0xbfb8aa3b, v91
	v_exp_f32_e32 v145, v144
	v_pk_mul_f32 v[142:143], v[96:97], v[142:143]
	v_add_f32_e32 v135, 1.0, v135
	v_rcp_f32_e32 v144, v135
	v_add_f32_e32 v135, 1.0, v145
	v_mul_f32_e32 v145, 0xbfb8aa3b, v92
	v_exp_f32_e32 v150, v145
	v_mul_f32_e32 v145, 0xbfb8aa3b, v93
	v_exp_f32_e32 v151, v145
	v_rcp_f32_e32 v145, v135
	v_add_f32_e32 v135, 1.0, v150
	v_rcp_f32_e32 v150, v135
	v_add_f32_e32 v135, 1.0, v151
	v_rcp_f32_e32 v151, v135
	v_pk_mul_f32 v[144:145], v[90:91], v[144:145]
	v_pk_mul_f32 v[140:141], v[86:87], v[140:141]
	v_pk_mul_f32 v[142:143], v[88:89], v[142:143]
	v_pk_mul_f32 v[144:145], v[82:83], v[144:145]
	v_mul_f32_e32 v135, 0xbfb8aa3b, v78
	v_cvt_pk_bf16_f32 v140, v140, v141
	v_cvt_pk_bf16_f32 v141, v142, v143
	v_cvt_pk_bf16_f32 v142, v144, v145
	v_exp_f32_e32 v135, v135
	v_mul_f32_e32 v144, 0xbfb8aa3b, v79
	v_exp_f32_e32 v145, v144
	v_pk_mul_f32 v[150:151], v[92:93], v[150:151]
	v_add_f32_e32 v135, 1.0, v135
	v_pk_mul_f32 v[150:151], v[84:85], v[150:151]
	v_rcp_f32_e32 v144, v135
	v_cvt_pk_bf16_f32 v143, v150, v151
	v_or_b32_e32 v150, 32, v131
	v_add_f32_e32 v135, 1.0, v145
	v_mad_i64_i32 v[150:151], s[6:7], v150, s10, v[136:137]
	v_rcp_f32_e32 v145, v135
	v_lshl_add_u64 v[150:151], v[150:151], 0, v[138:139]
	v_mul_f32_e32 v135, 0xbfb8aa3b, v80
	global_store_dwordx4 v[150:151], v[140:143], off nt
	v_exp_f32_e32 v135, v135
	s_nop 0
; __device__ __forceinline__ unsigned cvt_pk_bf16(float lo, float hi) { const f32x2_t v = {lo, hi}; const bf16x2_t b = __builtin_convertvector(v, bf16x2_t); return __builtin_bit_cast(unsigned, b); }
; __device__ __forceinline__ float sigmoidf_(float x) { return __builtin_amdgcn_rcpf(1.0f + __expf(-x)); }
;     __device__ __forceinline__ void operator()(const f32x4 (&acc)[2][2][4][2], const pg8::Unit& u, int tid, int wr, int wc, int fr, int fq) const {
;     ...
;             const int col0 = u.pn * 128 + wc * 32 + 8 * fq;
; #pragma unroll
;             for (int ai = 0; ai < 2; ++ai)
; #pragma unroll
;                 for (int m = 0; m < 4; ++m) {
;                     float r[8];
; #pragma unroll
;                     for (int n = 0; n < 2; ++n)
; #pragma unroll
;                         for (int e = 0; e < 4; ++e) { const float av = acc[ai][0][m][n][e], bv = acc[ai][1][m][n][e]; r[n * 4 + e] = av * sigmoidf_(av) * bv; }
;                     u32x4 w; w.x = cvt_pk_bf16(r[0], r[1]); w.y = cvt_pk_bf16(r[2], r[3]); w.z = cvt_pk_bf16(r[4], r[5]); w.w = cvt_pk_bf16(r[6], r[7]);
;                     *(u32x4*)(O + (size_t)(row0 + ai * 128 + m * 16) * DFF + col0) = w; }
	v_mul_f32_e32 v142, 0xbfb8aa3b, v81
	v_exp_f32_e32 v143, v142
	v_add_f32_e32 v135, 1.0, v135
	v_rcp_f32_e32 v142, v135
	v_pk_mul_f32 v[140:141], v[78:79], v[144:145]
	v_add_f32_e32 v135, 1.0, v143
	v_rcp_f32_e32 v143, v135
	v_mul_f32_e32 v135, 0xbfb8aa3b, v74
	v_exp_f32_e32 v135, v135
	v_mul_f32_e32 v144, 0xbfb8aa3b, v75
	v_exp_f32_e32 v145, v144
	v_pk_mul_f32 v[142:143], v[80:81], v[142:143]
	v_add_f32_e32 v135, 1.0, v135
	v_rcp_f32_e32 v144, v135
	v_add_f32_e32 v135, 1.0, v145
	v_mul_f32_e32 v145, 0xbfb8aa3b, v76
	v_exp_f32_e32 v150, v145
	v_mul_f32_e32 v145, 0xbfb8aa3b, v77
	v_exp_f32_e32 v151, v145
	v_rcp_f32_e32 v145, v135
	v_add_f32_e32 v135, 1.0, v150
	v_rcp_f32_e32 v150, v135
	v_add_f32_e32 v135, 1.0, v151
	v_rcp_f32_e32 v151, v135
	v_pk_mul_f32 v[144:145], v[74:75], v[144:145]
	v_pk_mul_f32 v[140:141], v[70:71], v[140:141]
	v_pk_mul_f32 v[142:143], v[72:73], v[142:143]
	v_pk_mul_f32 v[144:145], v[66:67], v[144:145]
	v_pk_mul_f32 v[150:151], v[76:77], v[150:151]
	v_cvt_pk_bf16_f32 v140, v140, v141
	v_pk_mul_f32 v[150:151], v[68:69], v[150:151]
	v_cvt_pk_bf16_f32 v141, v142, v143
	v_cvt_pk_bf16_f32 v142, v144, v145
	v_mul_f32_e32 v144, 0xbfb8aa3b, v62
	v_cvt_pk_bf16_f32 v143, v150, v151
	v_exp_f32_e32 v150, v144
	v_mul_f32_e32 v144, 0xbfb8aa3b, v63
	v_exp_f32_e32 v151, v144
	v_or_b32_e32 v135, 48, v131
	v_mad_i64_i32 v[144:145], s[6:7], v135, s10, v[136:137]
	v_add_f32_e32 v135, 1.0, v150
	v_rcp_f32_e32 v150, v135
	v_add_f32_e32 v135, 1.0, v151
	v_rcp_f32_e32 v151, v135
	v_lshl_add_u64 v[144:145], v[144:145], 0, v[138:139]
	global_store_dwordx4 v[144:145], v[140:143], off nt
	v_mul_f32_e32 v144, 0xbfb8aa3b, v58
	v_mul_f32_e32 v145, 0xbfb8aa3b, v59
	v_mul_f32_e32 v142, 0xbfb8aa3b, v64
	v_mul_f32_e32 v143, 0xbfb8aa3b, v65
	v_exp_f32_e32 v142, v142
	v_exp_f32_e32 v143, v143
	v_pk_mul_f32 v[140:141], v[62:63], v[150:151]
	v_exp_f32_e32 v144, v144
	v_exp_f32_e32 v145, v145
	v_mul_f32_e32 v150, 0xbfb8aa3b, v60
	v_mul_f32_e32 v151, 0xbfb8aa3b, v61
	v_exp_f32_e32 v150, v150
	v_exp_f32_e32 v151, v151
	v_add_f32_e32 v142, 1.0, v142
	v_add_f32_e32 v143, 1.0, v143
	v_rcp_f32_e32 v142, v142
	v_rcp_f32_e32 v143, v143
	v_add_f32_e32 v144, 1.0, v144
	v_add_f32_e32 v145, 1.0, v145
	v_rcp_f32_e32 v144, v144
	v_rcp_f32_e32 v145, v145
	v_add_f32_e32 v150, 1.0, v150
	v_add_f32_e32 v151, 1.0, v151
	v_rcp_f32_e32 v150, v150
	v_rcp_f32_e32 v151, v151
	v_pk_mul_f32 v[142:143], v[64:65], v[142:143]
	v_pk_mul_f32 v[140:141], v[54:55], v[140:141]
	v_pk_mul_f32 v[142:143], v[56:57], v[142:143]
	v_pk_mul_f32 v[144:145], v[58:59], v[144:145]
	v_pk_mul_f32 v[150:151], v[60:61], v[150:151]
	v_pk_mul_f32 v[144:145], v[50:51], v[144:145]
	v_cvt_pk_bf16_f32 v140, v140, v141
	v_cvt_pk_bf16_f32 v141, v142, v143
	v_mul_f32_e32 v143, 0xbfb8aa3b, v46
	v_add_u32_e32 v135, 0x80, v131
	v_pk_mul_f32 v[150:151], v[52:53], v[150:151]
	v_cvt_pk_bf16_f32 v142, v144, v145
	v_exp_f32_e32 v144, v143
	v_mul_f32_e32 v143, 0xbfb8aa3b, v47
	v_exp_f32_e32 v145, v143
	v_cvt_pk_bf16_f32 v143, v150, v151
	v_mad_i64_i32 v[150:151], s[6:7], v135, s10, v[136:137]
	v_lshl_add_u64 v[150:151], v[150:151], 0, v[138:139]
	v_mul_f32_e32 v135, 0xbfb8aa3b, v48
	global_store_dwordx4 v[150:151], v[140:143], off nt
	v_exp_f32_e32 v135, v135
	v_add_f32_e32 v144, 1.0, v144
	v_mul_f32_e32 v142, 0xbfb8aa3b, v49
	v_exp_f32_e32 v143, v142
	v_add_f32_e32 v145, 1.0, v145
	v_rcp_f32_e32 v144, v144
	v_rcp_f32_e32 v145, v145
	v_add_f32_e32 v135, 1.0, v135
	v_rcp_f32_e32 v142, v135
	v_add_f32_e32 v135, 1.0, v143
	v_rcp_f32_e32 v143, v135
	v_mul_f32_e32 v135, 0xbfb8aa3b, v42
	v_pk_mul_f32 v[140:141], v[46:47], v[144:145]
	v_exp_f32_e32 v135, v135
	v_mul_f32_e32 v144, 0xbfb8aa3b, v43
	v_exp_f32_e32 v145, v144
	v_pk_mul_f32 v[142:143], v[48:49], v[142:143]
	v_add_f32_e32 v135, 1.0, v135
	v_rcp_f32_e32 v144, v135
	v_add_f32_e32 v135, 1.0, v145
	v_mul_f32_e32 v145, 0xbfb8aa3b, v44
	v_exp_f32_e32 v150, v145
	v_mul_f32_e32 v145, 0xbfb8aa3b, v45
	v_exp_f32_e32 v151, v145
	v_rcp_f32_e32 v145, v135
	v_add_f32_e32 v135, 1.0, v150
	v_rcp_f32_e32 v150, v135
; __device__ __forceinline__ unsigned cvt_pk_bf16(float lo, float hi) { const f32x2_t v = {lo, hi}; const bf16x2_t b = __builtin_convertvector(v, bf16x2_t); return __builtin_bit_cast(unsigned, b); }
; __device__ __forceinline__ float sigmoidf_(float x) { return __builtin_amdgcn_rcpf(1.0f + __expf(-x)); }
;     __device__ __forceinline__ void operator()(const f32x4 (&acc)[2][2][4][2], const pg8::Unit& u, int tid, int wr, int wc, int fr, int fq) const {
;     ...
;             const int col0 = u.pn * 128 + wc * 32 + 8 * fq;
; #pragma unroll
;             for (int ai = 0; ai < 2; ++ai)
; #pragma unroll
;                 for (int m = 0; m < 4; ++m) {
;                     float r[8];
; #pragma unroll
;                     for (int n = 0; n < 2; ++n)
; #pragma unroll
;                         for (int e = 0; e < 4; ++e) { const float av = acc[ai][0][m][n][e], bv = acc[ai][1][m][n][e]; r[n * 4 + e] = av * sigmoidf_(av) * bv; }
;                     u32x4 w; w.x = cvt_pk_bf16(r[0], r[1]); w.y = cvt_pk_bf16(r[2], r[3]); w.z = cvt_pk_bf16(r[4], r[5]); w.w = cvt_pk_bf16(r[6], r[7]);
;                     *(u32x4*)(O + (size_t)(row0 + ai * 128 + m * 16) * DFF + col0) = w; }
	v_add_f32_e32 v135, 1.0, v151
	v_rcp_f32_e32 v151, v135
	v_pk_mul_f32 v[144:145], v[42:43], v[144:145]
	v_pk_mul_f32 v[140:141], v[38:39], v[140:141]
	v_pk_mul_f32 v[142:143], v[40:41], v[142:143]
	v_pk_mul_f32 v[144:145], v[34:35], v[144:145]
	v_mul_f32_e32 v135, 0xbfb8aa3b, v30
	v_cvt_pk_bf16_f32 v140, v140, v141
	v_cvt_pk_bf16_f32 v141, v142, v143
	v_cvt_pk_bf16_f32 v142, v144, v145
	v_exp_f32_e32 v135, v135
	v_mul_f32_e32 v144, 0xbfb8aa3b, v31
	v_exp_f32_e32 v145, v144
	v_pk_mul_f32 v[150:151], v[44:45], v[150:151]
	v_add_f32_e32 v135, 1.0, v135
	v_pk_mul_f32 v[150:151], v[36:37], v[150:151]
	v_rcp_f32_e32 v144, v135
	v_cvt_pk_bf16_f32 v143, v150, v151
	v_add_u32_e32 v150, 0x90, v131
	v_add_f32_e32 v135, 1.0, v145
	v_mad_i64_i32 v[150:151], s[6:7], v150, s10, v[136:137]
	v_rcp_f32_e32 v145, v135
	v_lshl_add_u64 v[150:151], v[150:151], 0, v[138:139]
	v_mul_f32_e32 v135, 0xbfb8aa3b, v32
	global_store_dwordx4 v[150:151], v[140:143], off nt
	v_exp_f32_e32 v135, v135
	s_nop 0
	v_mul_f32_e32 v142, 0xbfb8aa3b, v33
	v_exp_f32_e32 v143, v142
	v_add_f32_e32 v135, 1.0, v135
	v_rcp_f32_e32 v142, v135
	v_pk_mul_f32 v[140:141], v[30:31], v[144:145]
	v_add_f32_e32 v135, 1.0, v143
	v_rcp_f32_e32 v143, v135
	v_mul_f32_e32 v135, 0xbfb8aa3b, v26
	v_exp_f32_e32 v135, v135
	v_mul_f32_e32 v144, 0xbfb8aa3b, v27
	v_exp_f32_e32 v145, v144
	v_pk_mul_f32 v[142:143], v[32:33], v[142:143]
	v_add_f32_e32 v135, 1.0, v135
	v_rcp_f32_e32 v144, v135
	v_add_f32_e32 v135, 1.0, v145
	v_mul_f32_e32 v145, 0xbfb8aa3b, v28
	v_exp_f32_e32 v150, v145
	v_mul_f32_e32 v145, 0xbfb8aa3b, v29
	v_exp_f32_e32 v151, v145
	v_rcp_f32_e32 v145, v135
	v_add_f32_e32 v135, 1.0, v150
	v_rcp_f32_e32 v150, v135
	v_add_f32_e32 v135, 1.0, v151
	v_rcp_f32_e32 v151, v135
	v_pk_mul_f32 v[144:145], v[26:27], v[144:145]
	v_pk_mul_f32 v[140:141], v[22:23], v[140:141]
	v_pk_mul_f32 v[142:143], v[24:25], v[142:143]
	v_pk_mul_f32 v[144:145], v[18:19], v[144:145]
	v_mul_f32_e32 v135, 0xbfb8aa3b, v14
	v_cvt_pk_bf16_f32 v140, v140, v141
	v_cvt_pk_bf16_f32 v141, v142, v143
	v_cvt_pk_bf16_f32 v142, v144, v145
	v_exp_f32_e32 v135, v135
	v_mul_f32_e32 v144, 0xbfb8aa3b, v15
	v_exp_f32_e32 v145, v144
	v_pk_mul_f32 v[150:151], v[28:29], v[150:151]
	v_add_f32_e32 v135, 1.0, v135
	v_pk_mul_f32 v[150:151], v[20:21], v[150:151]
	v_rcp_f32_e32 v144, v135
	v_cvt_pk_bf16_f32 v143, v150, v151
	v_add_u32_e32 v150, 0xa0, v131
	v_add_f32_e32 v135, 1.0, v145
	v_mad_i64_i32 v[150:151], s[6:7], v150, s10, v[136:137]
	v_rcp_f32_e32 v145, v135
	v_lshl_add_u64 v[150:151], v[150:151], 0, v[138:139]
	v_mul_f32_e32 v135, 0xbfb8aa3b, v16
	global_store_dwordx4 v[150:151], v[140:143], off nt
	v_exp_f32_e32 v135, v135
	s_nop 0
	v_mul_f32_e32 v142, 0xbfb8aa3b, v17
	v_exp_f32_e32 v143, v142
	v_add_f32_e32 v135, 1.0, v135
	v_rcp_f32_e32 v142, v135
	v_pk_mul_f32 v[140:141], v[14:15], v[144:145]
	v_add_f32_e32 v135, 1.0, v143
	v_rcp_f32_e32 v143, v135
	v_mul_f32_e32 v135, 0xbfb8aa3b, v10
	v_exp_f32_e32 v135, v135
	v_mul_f32_e32 v144, 0xbfb8aa3b, v11
	v_exp_f32_e32 v145, v144
	v_pk_mul_f32 v[142:143], v[16:17], v[142:143]
	v_add_f32_e32 v135, 1.0, v135
	v_rcp_f32_e32 v144, v135
	v_add_f32_e32 v135, 1.0, v145
	v_mul_f32_e32 v145, 0xbfb8aa3b, v12
	v_exp_f32_e32 v150, v145
	v_mul_f32_e32 v145, 0xbfb8aa3b, v13
	v_exp_f32_e32 v151, v145
	v_rcp_f32_e32 v145, v135
	v_add_f32_e32 v135, 1.0, v150
	v_rcp_f32_e32 v150, v135
	v_add_f32_e32 v135, 1.0, v151
	v_rcp_f32_e32 v151, v135
	v_pk_mul_f32 v[144:145], v[10:11], v[144:145]
	v_add_u32_e32 v135, 0xb0, v131
	v_pk_mul_f32 v[140:141], v[6:7], v[140:141]
	v_pk_mul_f32 v[150:151], v[12:13], v[150:151]
	v_pk_mul_f32 v[142:143], v[8:9], v[142:143]
	v_pk_mul_f32 v[144:145], v[2:3], v[144:145]
	v_pk_mul_f32 v[150:151], v[4:5], v[150:151]
	v_mad_i64_i32 v[136:137], s[6:7], v135, s10, v[136:137]
	v_cvt_pk_bf16_f32 v140, v140, v141
	v_cvt_pk_bf16_f32 v141, v142, v143
	v_cvt_pk_bf16_f32 v142, v144, v145
	v_cvt_pk_bf16_f32 v143, v150, v151
	v_lshl_add_u64 v[136:137], v[136:137], 0, v[138:139]
	global_store_dwordx4 v[136:137], v[140:143], off nt

; #define LAS __attribute__((address_space(3)))
; __device__ __forceinline__ void na_block(bf16_t* PB, const bf16_t* VT, const float* rpb_h, int b, int hh, int rp, LAS unsigned char* lds, int tid, bool fill_rp, u32x4 (&kpre)[9], bf16x8 (&qpre)[2], bool have, int nx) {
;     const bool has_next = nx < 5120; const int nb = nx >> 9, nhh = nx & 7, nrp = (nx >> 3) & 63;
;     const int lane = tid & 63, w = tid >> 6, c15 = lane & 15, g = lane >> 4;
;     const int r = 2 * rp + (w >> 2), j = w & 3;
;     const int rsU = min(max(2 * rp - 4, 0), 120), rs = min(max(r - 4, 0), 120), ro = rs - rsU, bs = min(max(16 * j - 8, 0), 32);
;     LAS unsigned char* KS = lds;
;     LAS float* RP = (LAS float*)(lds + L_RP + w * 2048);
;     __syncthreads();
.LBB0_790:
	v_mov_b32_e32 v47, v183
	v_mov_b32_e32 v0, s77
	ds_read_b64 v[48:49], v0
	v_readlane_b32 s2, v245, 34
	s_cmp_eq_u32 s54, 0
	s_cselect_b64 s[40:41], -1, 0
	v_mov_b32_e32 v0, s2
	s_waitcnt lgkmcnt(0)
	v_readfirstlane_b32 s17, v49
	v_readfirstlane_b32 s34, v48
	ds_read_b64 v[48:49], v0
	s_mov_b64 s[6:7], -1
	s_and_b64 vcc, exec, s[40:41]
	v_ashrrev_i32_e32 v0, 3, v47
	s_waitcnt vmcnt(4) lgkmcnt(0)
	v_readfirstlane_b32 s14, v49
	v_readfirstlane_b32 s15, v48
	s_barrier
	s_cbranch_vccnz .LBB0_792
	v_ashrrev_i32_e32 v161, 3, v47
	s_mov_b64 s[6:7], 0

; #define LAS __attribute__((address_space(3)))
; __device__ __forceinline__ void na_block(bf16_t* PB, const bf16_t* VT, const float* rpb_h, int b, int hh, int rp, LAS unsigned char* lds, int tid, bool fill_rp, u32x4 (&kpre)[9], bf16x8 (&qpre)[2], bool have, int nx) {
;     ...
;     if (!have) {
;         { unsigned off = ((unsigned)(b * SEQ + rsU * 64 + (tid >> 3)) * (unsigned)PC + (unsigned)(512 + hh * 64 + 8 * (tid & 7))) * 2u;
; #pragma unroll
;           for (int i = 0; i < 9; ++i) { kpre[i] = (rsU + i) < 128 ? *(const u32x4*)((const char*)PB + off) : (u32x4){0u, 0u, 0u, 0u}; off += 64u * PC * 2u; } }
;     }
; #pragma unroll
;     for (int i = 0; i < 9; ++i) { const int v = tid + 512 * i; *(LAS u32x4*)(KS + (v >> 3) * 144 + (v & 7) * 16) = kpre[i]; }
;     if (fill_rp) {
; #pragma unroll
;         for (int i = 0; i < 8; ++i) { const int idx = lane + 64 * i; if (idx < 465) RP[idx] = 1.4426950408889634f * rpb_h[idx]; }
.LBB0_796:
	v_ashrrev_i32_e32 v49, 6, v47
	s_add_i32 s6, 0, 0x1e600
	v_lshlrev_b32_e32 v0, 4, v47
	v_lshl_add_u32 v152, v49, 11, s6
	v_and_b32_e32 v0, 0x70, v0
	s_movk_i32 s6, 0x90
	v_add_u32_e32 v0, 0, v0
	v_mul_lo_u32 v50, v161, s6
	v_add_u32_e32 v163, v0, v50
	v_add_u32_e32 v50, 0x200, v47
	v_lshrrev_b32_e32 v50, 3, v50
	v_mul_lo_u32 v50, v50, s6
	v_add_u32_e32 v184, v0, v50
	v_add_u32_e32 v50, 0x400, v47
	v_lshrrev_b32_e32 v50, 3, v50
	v_mul_lo_u32 v50, v50, s6
	v_add_u32_e32 v186, v0, v50
	v_add_u32_e32 v50, 0x600, v47
	v_lshrrev_b32_e32 v50, 3, v50
	v_mul_lo_u32 v50, v50, s6
	v_add_u32_e32 v187, v0, v50
	v_add_u32_e32 v50, 0x800, v47
	v_lshrrev_b32_e32 v50, 3, v50
	v_mul_lo_u32 v50, v50, s6
	v_add_u32_e32 v188, v0, v50
	v_add_u32_e32 v50, 0xa00, v47
	v_lshrrev_b32_e32 v50, 3, v50
	v_mul_lo_u32 v50, v50, s6
	v_add_u32_e32 v189, v0, v50
	v_add_u32_e32 v50, 0xc00, v47
	v_lshrrev_b32_e32 v50, 3, v50
	v_mul_lo_u32 v50, v50, s6
	v_add_u32_e32 v190, v0, v50
	v_add_u32_e32 v50, 0xe00, v47
	v_lshrrev_b32_e32 v50, 3, v50
	v_mul_lo_u32 v50, v50, s6
	v_add_u32_e32 v191, v0, v50
	v_add_u32_e32 v50, 0x1000, v47
	v_lshrrev_b32_e32 v50, 3, v50
	v_mul_lo_u32 v50, v50, s6
	v_readlane_b32 s6, v246, 59
	v_readlane_b32 s7, v246, 60
	s_or_b64 s[6:7], s[40:41], s[6:7]
	v_and_b32_e32 v48, 63, v47
	v_add_u32_e32 v192, v0, v50
	s_andn2_b64 vcc, exec, s[6:7]
	s_cmp_lg_u32 s54, 0
	s_cbranch_scc1 .Lna_kw_steady
	s_waitcnt vmcnt(7)
	ds_write_b128 v163, v[2:5]
	s_waitcnt vmcnt(6)
	ds_write_b128 v184, v[6:9]
	s_waitcnt vmcnt(5)
	ds_write_b128 v186, v[10:13]
	s_waitcnt vmcnt(4)
	ds_write_b128 v187, v[14:17]
	s_waitcnt vmcnt(3)
	ds_write_b128 v188, v[18:21]
	s_waitcnt vmcnt(2)
	ds_write_b128 v189, v[22:25]
	s_waitcnt vmcnt(1)
	ds_write_b128 v190, v[26:29]
	s_waitcnt vmcnt(0)
	ds_write_b128 v191, v[30:33]
	ds_write_b128 v192, v[34:37]
	s_branch .Lna_kw_done
.Lna_kw_steady:
	ds_write_b128 v163, v[2:5]
	ds_write_b128 v184, v[6:9]
	ds_write_b128 v186, v[10:13]
	ds_write_b128 v187, v[14:17]
	ds_write_b128 v188, v[18:21]
	ds_write_b128 v189, v[22:25]
	ds_write_b128 v190, v[26:29]
	ds_write_b128 v191, v[30:33]
	ds_write_b128 v192, v[34:37]
.Lna_kw_done:
	s_cbranch_vccnz .LBB0_800
	s_or_b32 s6, s20, s22
	s_mul_hi_u32 s7, s6, 0x744
	s_mulk_i32 s6, 0x744
	s_add_u32 s6, s15, s6
	s_addc_u32 s7, s14, s7
	v_lshlrev_b32_e32 v0, 2, v48
	global_load_dword v51, v0, s[6:7]
	global_load_dword v52, v0, s[6:7] offset:256
	v_add_u32_e32 v50, v152, v0
	s_movk_i32 s10, 0x1d1
	s_waitcnt vmcnt(1)
	v_mul_f32_e32 v51, 0x3fb8aa3b, v51
	s_waitcnt vmcnt(0)
	v_mul_f32_e32 v52, 0x3fb8aa3b, v52
	ds_write2st64_b32 v50, v51, v52 offset1:1
	global_load_dword v51, v0, s[6:7] offset:512
	global_load_dword v52, v0, s[6:7] offset:768
	s_waitcnt vmcnt(1)
	v_mul_f32_e32 v51, 0x3fb8aa3b, v51
	s_waitcnt vmcnt(0)
	v_mul_f32_e32 v52, 0x3fb8aa3b, v52
	ds_write2st64_b32 v50, v51, v52 offset0:2 offset1:3
	global_load_dword v51, v0, s[6:7] offset:1024
	global_load_dword v52, v0, s[6:7] offset:1280
	s_waitcnt vmcnt(1)
	v_mul_f32_e32 v51, 0x3fb8aa3b, v51
	s_waitcnt vmcnt(0)
	v_mul_f32_e32 v52, 0x3fb8aa3b, v52
	ds_write2st64_b32 v50, v51, v52 offset0:4 offset1:5
	global_load_dword v51, v0, s[6:7] offset:1536
	s_waitcnt vmcnt(0)
	v_mul_f32_e32 v51, 0x3fb8aa3b, v51
	ds_write_b32 v50, v51 offset:1536
	v_or_b32_e32 v51, 0x1c0, v48
	v_cmp_gt_u32_e32 vcc, s10, v51
	s_and_saveexec_b64 s[14:15], vcc
	s_cbranch_execz .LBB0_799
	v_lshl_add_u64 v[52:53], s[6:7], 0, v[0:1]
	global_load_dword v0, v[52:53], off offset:1792
	s_waitcnt vmcnt(0)
	v_mul_f32_e32 v0, 0x3fb8aa3b, v0
	ds_write_b32 v50, v0 offset:1792

; #define LAS __attribute__((address_space(3)))
; __device__ __forceinline__ void na_block(bf16_t* PB, const bf16_t* VT, const float* rpb_h, int b, int hh, int rp, LAS unsigned char* lds, int tid, bool fill_rp, u32x4 (&kpre)[9], bf16x8 (&qpre)[2], bool have, int nx) {
;     ...
;     f32x4 S[16];
; #pragma unroll
;     for (int kt = 0; kt < 16; ++kt) {
;         const int key = (ro + (kt >> 1)) * 64 + bs + 16 * (kt & 1) + c15;
;         f32x4 acc = (f32x4){0.f, 0.f, 0.f, 0.f};
; #pragma unroll
;         for (int dc = 0; dc < 2; ++dc) { const bf16x8 kf = *(const LAS bf16x8*)(KS + key * 144 + (32 * dc + 8 * g) * 2); acc = __builtin_amdgcn_mfma_f32_16x16x32_bf16(kf, qf[dc], acc, 0, 0, 0); }
;         S[kt] = acc;
;         if ((kt & 3) == 3) asm volatile("" ::: "memory");
;     }
;     u32x4 vv[9];
;     { unsigned off = ((unsigned)((((b * 8 + hh) * 128 + rsU) * 64 + (tid >> 3)) * 64) + (unsigned)(8 * (tid & 7))) * 2u;
; #pragma unroll
;       for (int i = 0; i < 9; ++i) { vv[i] = (rsU + i) < 128 ? *(const u32x4*)((const char*)VT + off) : (u32x4){0u, 0u, 0u, 0u}; off += 64u * 64u * 2u; } }
;     ...
;     if (has_next) {
;         const int nrsU = min(max(2 * nrp - 4, 0), 120);
;         { unsigned off = ((unsigned)(nb * SEQ + nrsU * 64 + (tid >> 3)) * (unsigned)PC + (unsigned)(512 + nhh * 64 + 8 * (tid & 7))) * 2u;
; #pragma unroll
;           for (int i = 0; i < 9; ++i) { kpre[i] = (nrsU + i) < 128 ? *(const u32x4*)((const char*)PB + off) : (u32x4){0u, 0u, 0u, 0u}; off += 64u * PC * 2u; } }
.LBB0_802:
	v_max_i32_e32 v0, 4, v153
	v_add_u32_e32 v0, -4, v0
	v_min_u32_e32 v0, 0x78, v0
	v_sub_u32_e64 v48, v196, 8 clamp
	v_min_u32_e32 v194, 32, v48
	v_sub_u32_e32 v48, v0, v46
	v_add_u32_e32 v56, v194, v147
	v_and_b32_e32 v47, 48, v47
	v_lshlrev_b32_e32 v193, 6, v48
	v_add_u32_e32 v47, 0, v47
	v_add_u32_e32 v48, v193, v56
	s_movk_i32 s3, 0x90
	v_mad_i32_i24 v52, v48, s3, v47
	s_waitcnt lgkmcnt(0)
	s_barrier
	s_waitcnt vmcnt(0)
	v_mov_b32_e32 v240, v52
	v_add_u32_e32 v241, 0x9000, v52
	ds_read_b128 v[212:215], v240
	ds_read_b128 v[216:219], v240 offset:64
	ds_read_b128 v[220:223], v240 offset:2304
	ds_read_b128 v[224:227], v240 offset:2368
	ds_read_b128 v[228:231], v240 offset:9216
	ds_read_b128 v[232:235], v240 offset:9280
	ds_read_b128 v[236:239], v240 offset:11520
	v_add_u32_e32 v185, 64, v193
	v_add_u32_e32 v162, 0x80, v193
	v_add_u32_e32 v160, 0xc0, v193
	v_add_u32_e32 v158, 0x100, v193
	v_add_u32_e32 v157, 0x140, v193
	v_add_u32_e32 v156, 0x180, v193
	v_add_u32_e32 v154, 0x1c0, v193
	v_readlane_b32 s98, v245, 12
	s_nop 0
	s_add_i32 s98, s98, s54
	s_cmpk_lt_i32 s98, 0x1400
	s_cbranch_scc0 .Lna_nokpf
	s_lshr_b32 s99, s98, 2
	s_and_b32 s99, s99, 0x7e
	v_sub_u32_e64 v242, s99, 4 clamp
	s_ashr_i32 s100, s98, 9
	v_min_u32_e32 v242, 0x78, v242
	s_lshl_b32 s100, s100, 13
	v_lshlrev_b32_e32 v242, 6, v242
	v_or_b32_e32 v242, s100, v242
	v_add_u32_e32 v242, v242, v161
	v_mul_lo_u32 v242, v242, s11
	s_and_b32 s100, s55, 0x1c0
	v_or3_b32 v242, v242, s100, v159
	v_lshlrev_b32_e32 v242, 1, v242
	v_or_b32_e32 v2, 0x400, v242
	v_add_u32_e32 v6, 0x60400, v242
	v_add_u32_e32 v10, 0xc0400, v242
	v_add_u32_e32 v14, 0x120400, v242
	v_add_u32_e32 v18, 0x180400, v242
	v_add_u32_e32 v22, 0x1e0400, v242
	v_add_u32_e32 v26, 0x240400, v242
	v_add_u32_e32 v30, 0x2a0400, v242
	global_load_dwordx4 v[2:5], v2, s[28:29]
	global_load_dwordx4 v[6:9], v6, s[28:29]
	global_load_dwordx4 v[10:13], v10, s[28:29]
	global_load_dwordx4 v[14:17], v14, s[28:29]
	global_load_dwordx4 v[18:21], v18, s[28:29]
	global_load_dwordx4 v[22:25], v22, s[28:29]
	global_load_dwordx4 v[26:29], v26, s[28:29]
	global_load_dwordx4 v[30:33], v30, s[28:29]
	v_mov_b32_e32 v34, 0
	v_mov_b32_e32 v35, 0
	v_mov_b32_e32 v36, 0
	v_mov_b32_e32 v37, 0
	s_cmpk_gt_u32 s99, 0x7b
	s_cbranch_scc1 .Lna_nokpf
	v_add_u32_e32 v242, 0x300400, v242
	global_load_dwordx4 v[34:37], v242, s[28:29]
.Lna_nokpf:
	s_add_u32 s40, s34, 0x36800000
	s_addc_u32 s41, s17, 0
	s_lshl_b32 s2, s2, 10
	s_or_b32 s2, s20, s2
	v_or_b32_e32 v46, s2, v46
	v_lshlrev_b32_e32 v46, 12, v46
	v_lshl_add_u32 v46, v161, 6, v46
	v_or_b32_e32 v46, v46, v159
	v_lshlrev_b32_e32 v155, 1, v46
	v_add_u32_e32 v58, 0x6000, v155
	v_add_u32_e32 v62, 0x8000, v155
	v_add_u32_e32 v54, 0x4000, v155
	v_add_u32_e32 v74, 0xe000, v155
	v_add_u32_e32 v50, 0x2000, v155
	v_add_u32_e32 v66, 0xa000, v155
	v_add_u32_e32 v70, 0xc000, v155
	global_load_dwordx4 v[58:61], v58, s[40:41]
	global_load_dwordx4 v[62:65], v62, s[40:41]
	global_load_dwordx4 v[54:57], v54, s[40:41]
	global_load_dwordx4 v[46:49], v155, s[40:41]
	global_load_dwordx4 v[74:77], v74, s[40:41]
	global_load_dwordx4 v[50:53], v50, s[40:41]
	global_load_dwordx4 v[66:69], v66, s[40:41]
	global_load_dwordx4 v[70:73], v70, s[40:41]
	v_mov_b32_e32 v78, 0
	v_mov_b32_e32 v79, 0
	v_mov_b32_e32 v80, 0
	v_mov_b32_e32 v81, 0
	s_cmp_gt_u32 s16, 61
	s_cbranch_scc1 .Lna_skip9
	v_add_u32_e32 v78, 0x10000, v155
	global_load_dwordx4 v[78:81], v78, s[40:41]

; __device__ __forceinline__ void na_block(bf16_t* PB, const bf16_t* VT, const float* rpb_h, int b, int hh, int rp, LAS unsigned char* lds, int tid, bool fill_rp, u32x4 (&kpre)[9], bf16x8 (&qpre)[2], bool have, int nx) {
;     ...
;     if (has_next) {
;         const int nrsU = min(max(2 * nrp - 4, 0), 120);
;         { unsigned off = ((unsigned)(nb * SEQ + nrsU * 64 + (tid >> 3)) * (unsigned)PC + (unsigned)(512 + nhh * 64 + 8 * (tid & 7))) * 2u;
; #pragma unroll
;           for (int i = 0; i < 9; ++i) { kpre[i] = (nrsU + i) < 128 ? *(const u32x4*)((const char*)PB + off) : (u32x4){0u, 0u, 0u, 0u}; off += 64u * PC * 2u; } }
;         const bf16_t* nqp = PB + ((size_t)nb * SEQ + (2 * nrp + (w >> 2)) * 64 + 16 * j + c15) * PC + nhh * 64;
; #pragma unroll
;         for (int dc = 0; dc < 2; ++dc) qpre[dc] = *(const bf16x8*)(nqp + 32 * dc + 8 * g);
.LBB0_934:
	s_andn2_b64 vcc, exec, s[2:3]
	s_cbranch_vccnz .LBB0_789
	s_lshr_b32 s3, s6, 2
	s_and_b32 s7, s3, 0x7e
	s_ashr_i32 s2, s6, 9
	s_and_b32 s6, s55, 0x1c0
	s_branch .LBB0_788

; #define LAS __attribute__((address_space(3)))
; __device__ __forceinline__ void ca_block(bf16_t* PB, const bf16_t* KV, const bf16_t* VT, int b, int hh, int q256, LAS unsigned char* lds, int tid, u32x4 (&pk)[8], u32x4 (&pv)[8], bool have, int nx) {
;     ...
;         const int qt = q256 * 16 + round * 8 + w;
;         bf16_t* qp = PB + ((size_t)b * SEQ + qt * 16 + c15) * PC + 2560 + hh * 128;
;         bf16x8 qf[4];
; #pragma unroll
;         for (int dc = 0; dc < 4; ++dc) qf[dc] = *(const bf16x8*)(qp + 32 * dc + 8 * g);
;         f32x4 S[16];
; #pragma unroll
;         for (int kt = 0; kt < 16; ++kt) {
;             f32x4 acc = (f32x4){0.f, 0.f, 0.f, 0.f};
; #pragma unroll
;             for (int dc = 0; dc < 4; ++dc) { const bf16x8 kf = *(const LAS bf16x8*)(Ks + (16 * kt + c15) * 272 + (32 * dc + 8 * g) * 2); acc = __builtin_amdgcn_mfma_f32_16x16x32_bf16(kf, qf[dc], acc, 0, 0, 0); }
;             S[kt] = acc;
;             if (kt & 1) asm volatile("" ::: "memory");
;         }
.LBB0_946:
	v_add_u32_e32 v66, s2, v147
	v_ashrrev_i32_e32 v67, 31, v66
	v_lshl_add_u64 v[66:67], v[142:143], 0, v[66:67]
	v_mov_b64_e32 v[68:69], s[28:29]
	v_mad_u64_u32 v[68:69], s[2:3], v66, s23, v[68:69]
	v_mov_b32_e32 v66, v69
	v_mad_u64_u32 v[66:67], s[2:3], v67, s23, v[66:67]
	v_mov_b32_e32 v69, v66
	v_lshl_add_u64 v[66:67], v[68:69], 0, s[20:21]
	s_mov_b64 s[2:3], 0x1400
	v_lshl_add_u64 v[150:151], v[66:67], 0, s[2:3]
	v_lshl_add_u64 v[66:67], v[150:151], 0, v[0:1]
	global_load_dwordx4 v[138:141], v[66:67], off
	global_load_dwordx4 v[134:137], v[66:67], off offset:64
	global_load_dwordx4 v[130:133], v[66:67], off offset:128
	global_load_dwordx4 v[126:129], v[66:67], off offset:192
	ds_read_b128 v[196:199], v152
	ds_read_b128 v[200:203], v152 offset:64
	ds_read_b128 v[204:207], v152 offset:128
	ds_read_b128 v[208:211], v152 offset:192
	ds_read_b128 v[212:215], v152 offset:4352
	ds_read_b128 v[216:219], v152 offset:4416
	ds_read_b128 v[220:223], v152 offset:4480
	s_waitcnt vmcnt(0)
	s_waitcnt lgkmcnt(6)
	v_mfma_f32_16x16x32_bf16 v[66:69], v[196:199], v[138:141], 0
	ds_read_b128 v[196:199], v152 offset:4544
	s_waitcnt lgkmcnt(6)
	v_mfma_f32_16x16x32_bf16 v[66:69], v[200:203], v[134:137], v[66:69]
	ds_read_b128 v[200:203], v152 offset:8704
	s_waitcnt lgkmcnt(6)
	v_mfma_f32_16x16x32_bf16 v[66:69], v[204:207], v[130:133], v[66:69]
	ds_read_b128 v[204:207], v152 offset:8768
	s_waitcnt lgkmcnt(6)
	v_mfma_f32_16x16x32_bf16 v[66:69], v[208:211], v[126:129], v[66:69]
	ds_read_b128 v[208:211], v152 offset:8832
	s_waitcnt lgkmcnt(6)
	v_mfma_f32_16x16x32_bf16 v[70:73], v[212:215], v[138:141], 0
	ds_read_b128 v[212:215], v152 offset:8896
	s_waitcnt lgkmcnt(6)
	v_mfma_f32_16x16x32_bf16 v[70:73], v[216:219], v[134:137], v[70:73]
	ds_read_b128 v[216:219], v152 offset:13056
	s_waitcnt lgkmcnt(6)
	v_mfma_f32_16x16x32_bf16 v[70:73], v[220:223], v[130:133], v[70:73]
	ds_read_b128 v[220:223], v152 offset:13120
	s_waitcnt lgkmcnt(6)
	v_mfma_f32_16x16x32_bf16 v[70:73], v[196:199], v[126:129], v[70:73]
	ds_read_b128 v[196:199], v152 offset:13184
	s_waitcnt lgkmcnt(6)
	v_mfma_f32_16x16x32_bf16 v[74:77], v[200:203], v[138:141], 0
	ds_read_b128 v[200:203], v152 offset:13248
	s_waitcnt lgkmcnt(6)
	v_mfma_f32_16x16x32_bf16 v[74:77], v[204:207], v[134:137], v[74:77]
	ds_read_b128 v[204:207], v152 offset:17408
	s_waitcnt lgkmcnt(6)
	v_mfma_f32_16x16x32_bf16 v[74:77], v[208:211], v[130:133], v[74:77]
	ds_read_b128 v[208:211], v152 offset:17472
	s_waitcnt lgkmcnt(6)
	v_mfma_f32_16x16x32_bf16 v[74:77], v[212:215], v[126:129], v[74:77]
	ds_read_b128 v[212:215], v152 offset:17536
	s_waitcnt lgkmcnt(6)
	v_mfma_f32_16x16x32_bf16 v[78:81], v[216:219], v[138:141], 0
	ds_read_b128 v[216:219], v152 offset:17600
	s_waitcnt lgkmcnt(6)
	v_mfma_f32_16x16x32_bf16 v[78:81], v[220:223], v[134:137], v[78:81]
	ds_read_b128 v[220:223], v152 offset:21760
	s_waitcnt lgkmcnt(6)
	v_mfma_f32_16x16x32_bf16 v[78:81], v[196:199], v[130:133], v[78:81]
	ds_read_b128 v[196:199], v152 offset:21824
	s_waitcnt lgkmcnt(6)
	v_mfma_f32_16x16x32_bf16 v[78:81], v[200:203], v[126:129], v[78:81]
	ds_read_b128 v[200:203], v152 offset:21888
	s_waitcnt lgkmcnt(6)
	v_mfma_f32_16x16x32_bf16 v[82:85], v[204:207], v[138:141], 0
	ds_read_b128 v[204:207], v152 offset:21952
	s_waitcnt lgkmcnt(6)
	v_mfma_f32_16x16x32_bf16 v[82:85], v[208:211], v[134:137], v[82:85]
	ds_read_b128 v[208:211], v152 offset:26112
	s_waitcnt lgkmcnt(6)
	v_mfma_f32_16x16x32_bf16 v[82:85], v[212:215], v[130:133], v[82:85]
	ds_read_b128 v[212:215], v152 offset:26176
	s_waitcnt lgkmcnt(6)
	v_mfma_f32_16x16x32_bf16 v[82:85], v[216:219], v[126:129], v[82:85]
	ds_read_b128 v[216:219], v152 offset:26240
	s_waitcnt lgkmcnt(6)
	v_mfma_f32_16x16x32_bf16 v[86:89], v[220:223], v[138:141], 0
	ds_read_b128 v[220:223], v152 offset:26304
	s_waitcnt lgkmcnt(6)
	v_mfma_f32_16x16x32_bf16 v[86:89], v[196:199], v[134:137], v[86:89]
	ds_read_b128 v[196:199], v152 offset:30464
	s_waitcnt lgkmcnt(6)
	v_mfma_f32_16x16x32_bf16 v[86:89], v[200:203], v[130:133], v[86:89]
	ds_read_b128 v[200:203], v152 offset:30528
	s_waitcnt lgkmcnt(6)
	v_mfma_f32_16x16x32_bf16 v[86:89], v[204:207], v[126:129], v[86:89]
	ds_read_b128 v[204:207], v152 offset:30592
	s_waitcnt lgkmcnt(6)
	v_mfma_f32_16x16x32_bf16 v[90:93], v[208:211], v[138:141], 0
	ds_read_b128 v[208:211], v152 offset:30656
	s_waitcnt lgkmcnt(6)
	v_mfma_f32_16x16x32_bf16 v[90:93], v[212:215], v[134:137], v[90:93]
	ds_read_b128 v[212:215], v152 offset:34816
	s_waitcnt lgkmcnt(6)
	v_mfma_f32_16x16x32_bf16 v[90:93], v[216:219], v[130:133], v[90:93]
	ds_read_b128 v[216:219], v152 offset:34880
	s_waitcnt lgkmcnt(6)
	v_mfma_f32_16x16x32_bf16 v[90:93], v[220:223], v[126:129], v[90:93]
	ds_read_b128 v[220:223], v152 offset:34944
	s_waitcnt lgkmcnt(6)
	v_mfma_f32_16x16x32_bf16 v[94:97], v[196:199], v[138:141], 0
	ds_read_b128 v[196:199], v152 offset:35008
	s_waitcnt lgkmcnt(6)
	v_mfma_f32_16x16x32_bf16 v[94:97], v[200:203], v[134:137], v[94:97]
	ds_read_b128 v[200:203], v152 offset:39168
	s_waitcnt lgkmcnt(6)
	v_mfma_f32_16x16x32_bf16 v[94:97], v[204:207], v[130:133], v[94:97]
	ds_read_b128 v[204:207], v152 offset:39232
	s_waitcnt lgkmcnt(6)
	v_mfma_f32_16x16x32_bf16 v[94:97], v[208:211], v[126:129], v[94:97]
	ds_read_b128 v[208:211], v152 offset:39296
	s_waitcnt lgkmcnt(6)
	v_mfma_f32_16x16x32_bf16 v[98:101], v[212:215], v[138:141], 0
	ds_read_b128 v[212:215], v152 offset:39360
	s_waitcnt lgkmcnt(6)
	v_mfma_f32_16x16x32_bf16 v[98:101], v[216:219], v[134:137], v[98:101]
	ds_read_b128 v[216:219], v152 offset:43520
	s_waitcnt lgkmcnt(6)
	v_mfma_f32_16x16x32_bf16 v[98:101], v[220:223], v[130:133], v[98:101]
	ds_read_b128 v[220:223], v152 offset:43584
	s_waitcnt lgkmcnt(6)
; #define LAS __attribute__((address_space(3)))
; __device__ __forceinline__ void ca_block(bf16_t* PB, const bf16_t* KV, const bf16_t* VT, int b, int hh, int q256, LAS unsigned char* lds, int tid, u32x4 (&pk)[8], u32x4 (&pv)[8], bool have, int nx) {
;     ...
;         for (int kt = 0; kt < 16; ++kt) {
;             f32x4 acc = (f32x4){0.f, 0.f, 0.f, 0.f};
; #pragma unroll
;             for (int dc = 0; dc < 4; ++dc) { const bf16x8 kf = *(const LAS bf16x8*)(Ks + (16 * kt + c15) * 272 + (32 * dc + 8 * g) * 2); acc = __builtin_amdgcn_mfma_f32_16x16x32_bf16(kf, qf[dc], acc, 0, 0, 0); }
;             S[kt] = acc;
;             if (kt & 1) asm volatile("" ::: "memory");
;         }
;         float mx = -3.0e38f;
; #pragma unroll
;         for (int kt = 0; kt < 16; ++kt)
; #pragma unroll
;             for (int jj = 0; jj < 4; ++jj) { const float sv = S[kt][jj] * (0.08838834764831845f * 1.4426950408889634f); S[kt][jj] = sv; mx = fmaxf(mx, sv); }
	v_mfma_f32_16x16x32_bf16 v[98:101], v[196:199], v[126:129], v[98:101]
	ds_read_b128 v[196:199], v152 offset:43648
	s_waitcnt lgkmcnt(6)
	v_mfma_f32_16x16x32_bf16 v[102:105], v[200:203], v[138:141], 0
	ds_read_b128 v[200:203], v152 offset:43712
	s_waitcnt lgkmcnt(6)
	v_mfma_f32_16x16x32_bf16 v[102:105], v[204:207], v[134:137], v[102:105]
	ds_read_b128 v[204:207], v152 offset:47872
	s_waitcnt lgkmcnt(6)
	v_mfma_f32_16x16x32_bf16 v[102:105], v[208:211], v[130:133], v[102:105]
	ds_read_b128 v[208:211], v152 offset:47936
	s_waitcnt lgkmcnt(6)
	v_mfma_f32_16x16x32_bf16 v[102:105], v[212:215], v[126:129], v[102:105]
	ds_read_b128 v[212:215], v152 offset:48000
	s_waitcnt lgkmcnt(6)
	v_mfma_f32_16x16x32_bf16 v[106:109], v[216:219], v[138:141], 0
	ds_read_b128 v[216:219], v152 offset:48064
	s_waitcnt lgkmcnt(6)
	v_mfma_f32_16x16x32_bf16 v[106:109], v[220:223], v[134:137], v[106:109]
	ds_read_b128 v[220:223], v152 offset:52224
	s_waitcnt lgkmcnt(6)
	v_mfma_f32_16x16x32_bf16 v[106:109], v[196:199], v[130:133], v[106:109]
	ds_read_b128 v[196:199], v152 offset:52288
	s_waitcnt lgkmcnt(6)
	v_mfma_f32_16x16x32_bf16 v[106:109], v[200:203], v[126:129], v[106:109]
	ds_read_b128 v[200:203], v152 offset:52352
	s_waitcnt lgkmcnt(6)
	v_mfma_f32_16x16x32_bf16 v[110:113], v[204:207], v[138:141], 0
	ds_read_b128 v[204:207], v152 offset:52416
	s_waitcnt lgkmcnt(6)
	v_mfma_f32_16x16x32_bf16 v[110:113], v[208:211], v[134:137], v[110:113]
	ds_read_b128 v[208:211], v152 offset:56576
	s_waitcnt lgkmcnt(6)
	v_mfma_f32_16x16x32_bf16 v[110:113], v[212:215], v[130:133], v[110:113]
	ds_read_b128 v[212:215], v152 offset:56640
	s_waitcnt lgkmcnt(6)
	v_mfma_f32_16x16x32_bf16 v[110:113], v[216:219], v[126:129], v[110:113]
	ds_read_b128 v[216:219], v152 offset:56704
	s_waitcnt lgkmcnt(6)
	v_mfma_f32_16x16x32_bf16 v[114:117], v[220:223], v[138:141], 0
	ds_read_b128 v[220:223], v152 offset:56768
	s_waitcnt lgkmcnt(6)
	v_mfma_f32_16x16x32_bf16 v[114:117], v[196:199], v[134:137], v[114:117]
	ds_read_b128 v[196:199], v152 offset:60928
	s_waitcnt lgkmcnt(6)
	v_mfma_f32_16x16x32_bf16 v[114:117], v[200:203], v[130:133], v[114:117]
	ds_read_b128 v[200:203], v152 offset:60992
	s_waitcnt lgkmcnt(6)
	v_mfma_f32_16x16x32_bf16 v[114:117], v[204:207], v[126:129], v[114:117]
	ds_read_b128 v[204:207], v152 offset:61056
	s_waitcnt lgkmcnt(6)
	v_mfma_f32_16x16x32_bf16 v[118:121], v[208:211], v[138:141], 0
	ds_read_b128 v[208:211], v152 offset:61120
	s_waitcnt lgkmcnt(6)
	v_mfma_f32_16x16x32_bf16 v[118:121], v[212:215], v[134:137], v[118:121]
	ds_read_b128 v[212:215], v152 offset:65280
	s_waitcnt lgkmcnt(6)
	v_mfma_f32_16x16x32_bf16 v[118:121], v[216:219], v[130:133], v[118:121]
	ds_read_b128 v[216:219], v152 offset:65344
	s_waitcnt lgkmcnt(6)
	v_mfma_f32_16x16x32_bf16 v[118:121], v[220:223], v[126:129], v[118:121]
	ds_read_b128 v[220:223], v152 offset:65408
	s_waitcnt lgkmcnt(6)
	v_mfma_f32_16x16x32_bf16 v[122:125], v[196:199], v[138:141], 0
	ds_read_b128 v[196:199], v152 offset:65472
	s_waitcnt lgkmcnt(6)
	v_mfma_f32_16x16x32_bf16 v[122:125], v[200:203], v[134:137], v[122:125]
	s_waitcnt lgkmcnt(5)
	v_mfma_f32_16x16x32_bf16 v[122:125], v[204:207], v[130:133], v[122:125]
	s_waitcnt lgkmcnt(4)
	v_mfma_f32_16x16x32_bf16 v[122:125], v[208:211], v[126:129], v[122:125]
	s_waitcnt lgkmcnt(3)
	v_mfma_f32_16x16x32_bf16 v[224:227], v[212:215], v[138:141], 0
	s_waitcnt lgkmcnt(2)
	v_mfma_f32_16x16x32_bf16 v[224:227], v[216:219], v[134:137], v[224:227]
	s_waitcnt lgkmcnt(1)
	v_mfma_f32_16x16x32_bf16 v[224:227], v[220:223], v[130:133], v[224:227]
	s_waitcnt lgkmcnt(0)
	v_mfma_f32_16x16x32_bf16 v[126:129], v[196:199], v[126:129], v[224:227]
	s_nop 7
	v_mul_f32_e32 v130, 0x3e0293ee, v66
	v_mul_f32_e32 v131, 0x3e0293ee, v67
	v_max3_f32 v130, v130, s90, v131
	v_mul_f32_e32 v131, 0x3e0293ee, v68
	v_mul_f32_e32 v132, 0x3e0293ee, v69
	v_max3_f32 v130, v130, v131, v132
	v_mul_f32_e32 v131, 0x3e0293ee, v70
	v_mul_f32_e32 v132, 0x3e0293ee, v71
	v_max3_f32 v130, v130, v131, v132
	v_mul_f32_e32 v131, 0x3e0293ee, v72
	v_mul_f32_e32 v132, 0x3e0293ee, v73
	v_max3_f32 v130, v130, v131, v132
	v_mul_f32_e32 v131, 0x3e0293ee, v74
	v_mul_f32_e32 v132, 0x3e0293ee, v75
	v_max3_f32 v130, v130, v131, v132
	v_mul_f32_e32 v131, 0x3e0293ee, v76
	v_mul_f32_e32 v132, 0x3e0293ee, v77
	v_max3_f32 v130, v130, v131, v132
	v_mul_f32_e32 v131, 0x3e0293ee, v78
	v_mul_f32_e32 v132, 0x3e0293ee, v79
	v_max3_f32 v130, v130, v131, v132
	v_mul_f32_e32 v131, 0x3e0293ee, v80
	v_mul_f32_e32 v132, 0x3e0293ee, v81
	v_max3_f32 v130, v130, v131, v132
	v_mul_f32_e32 v131, 0x3e0293ee, v82
	v_mul_f32_e32 v132, 0x3e0293ee, v83
	v_max3_f32 v130, v130, v131, v132
	v_mul_f32_e32 v131, 0x3e0293ee, v84
	v_mul_f32_e32 v132, 0x3e0293ee, v85
	v_max3_f32 v130, v130, v131, v132
	v_mul_f32_e32 v131, 0x3e0293ee, v86
	v_mul_f32_e32 v132, 0x3e0293ee, v87
	v_max3_f32 v130, v130, v131, v132
	v_mul_f32_e32 v131, 0x3e0293ee, v88
	v_mul_f32_e32 v132, 0x3e0293ee, v89
	v_max3_f32 v130, v130, v131, v132
	v_mul_f32_e32 v131, 0x3e0293ee, v90
	v_mul_f32_e32 v132, 0x3e0293ee, v91
	v_max3_f32 v130, v130, v131, v132
	v_mul_f32_e32 v131, 0x3e0293ee, v92
	v_mul_f32_e32 v132, 0x3e0293ee, v93
	v_max3_f32 v130, v130, v131, v132
	v_mul_f32_e32 v131, 0x3e0293ee, v94
	v_mul_f32_e32 v132, 0x3e0293ee, v95
	v_max3_f32 v130, v130, v131, v132
	v_mul_f32_e32 v131, 0x3e0293ee, v96
	v_mul_f32_e32 v132, 0x3e0293ee, v97
	v_max3_f32 v130, v130, v131, v132
	v_mul_f32_e32 v131, 0x3e0293ee, v98
	v_mul_f32_e32 v132, 0x3e0293ee, v99
	v_max3_f32 v130, v130, v131, v132
	v_mul_f32_e32 v131, 0x3e0293ee, v100
	v_mul_f32_e32 v132, 0x3e0293ee, v101
	v_max3_f32 v130, v130, v131, v132
	v_mul_f32_e32 v131, 0x3e0293ee, v102
; __device__ __forceinline__ void ca_block(bf16_t* PB, const bf16_t* KV, const bf16_t* VT, int b, int hh, int q256, LAS unsigned char* lds, int tid, u32x4 (&pk)[8], u32x4 (&pv)[8], bool have, int nx) {
;     ...
;         float mx = -3.0e38f;
; #pragma unroll
;         for (int kt = 0; kt < 16; ++kt)
; #pragma unroll
;             for (int jj = 0; jj < 4; ++jj) { const float sv = S[kt][jj] * (0.08838834764831845f * 1.4426950408889634f); S[kt][jj] = sv; mx = fmaxf(mx, sv); }
;         mx = fmaxf(mx, __shfl_xor(mx, 16)); mx = fmaxf(mx, __shfl_xor(mx, 32));
;         float sum = 0.f;
; #pragma unroll
;         for (int kt = 0; kt < 16; ++kt)
; #pragma unroll
;             for (int jj = 0; jj < 4; ++jj) { const float p = __builtin_amdgcn_exp2f(S[kt][jj] - mx); S[kt][jj] = p; sum += p; }
;         sum += __shfl_xor(sum, 16); sum += __shfl_xor(sum, 32);
	v_mul_f32_e32 v132, 0x3e0293ee, v103
	v_max3_f32 v130, v130, v131, v132
	v_mul_f32_e32 v131, 0x3e0293ee, v104
	v_mul_f32_e32 v132, 0x3e0293ee, v105
	v_max3_f32 v130, v130, v131, v132
	v_mul_f32_e32 v131, 0x3e0293ee, v106
	v_mul_f32_e32 v132, 0x3e0293ee, v107
	v_max3_f32 v130, v130, v131, v132
	v_mul_f32_e32 v131, 0x3e0293ee, v108
	v_mul_f32_e32 v132, 0x3e0293ee, v109
	v_max3_f32 v130, v130, v131, v132
	v_mul_f32_e32 v131, 0x3e0293ee, v110
	v_mul_f32_e32 v132, 0x3e0293ee, v111
	v_max3_f32 v130, v130, v131, v132
	v_mul_f32_e32 v131, 0x3e0293ee, v112
	v_mul_f32_e32 v132, 0x3e0293ee, v113
	v_max3_f32 v130, v130, v131, v132
	v_mul_f32_e32 v131, 0x3e0293ee, v114
	v_mul_f32_e32 v132, 0x3e0293ee, v115
	v_max3_f32 v130, v130, v131, v132
	v_mul_f32_e32 v131, 0x3e0293ee, v116
	v_mul_f32_e32 v132, 0x3e0293ee, v117
	v_max3_f32 v130, v130, v131, v132
	v_mul_f32_e32 v131, 0x3e0293ee, v118
	v_mul_f32_e32 v132, 0x3e0293ee, v119
	v_max3_f32 v130, v130, v131, v132
	v_mul_f32_e32 v131, 0x3e0293ee, v120
	v_mul_f32_e32 v132, 0x3e0293ee, v121
	v_max3_f32 v130, v130, v131, v132
	v_mul_f32_e32 v131, 0x3e0293ee, v122
	v_mul_f32_e32 v132, 0x3e0293ee, v123
	v_max3_f32 v130, v130, v131, v132
	v_mul_f32_e32 v131, 0x3e0293ee, v124
	v_mul_f32_e32 v132, 0x3e0293ee, v125
	v_max3_f32 v130, v130, v131, v132
	v_mul_f32_e32 v131, 0x3e0293ee, v126
	v_mul_f32_e32 v132, 0x3e0293ee, v127
	v_max3_f32 v130, v130, v131, v132
	v_mul_f32_e32 v131, 0x3e0293ee, v128
	v_mul_f32_e32 v132, 0x3e0293ee, v129
	v_max3_f32 v130, v130, v131, v132
	v_and_b32_e32 v132, 64, v169
	v_xor_b32_e32 v131, 16, v169
	v_add_u32_e32 v132, 64, v132
	v_cmp_lt_i32_e32 vcc, v131, v132
	s_nop 1
	v_cndmask_b32_e32 v131, v169, v131, vcc
	v_lshlrev_b32_e32 v131, 2, v131
	ds_bpermute_b32 v133, v131, v130
	s_waitcnt lgkmcnt(0)
	v_max_f32_e32 v133, v133, v133
	v_max_f32_e32 v130, v130, v133
	v_xor_b32_e32 v133, 32, v169
	v_cmp_lt_i32_e32 vcc, v133, v132
	s_nop 1
	v_cndmask_b32_e32 v132, v169, v133, vcc
	v_lshlrev_b32_e32 v132, 2, v132
	ds_bpermute_b32 v133, v132, v130
	s_waitcnt lgkmcnt(0)
	v_max_f32_e32 v133, v133, v133
	v_max_f32_e32 v130, v130, v133
	v_fma_f32 v66, v66, s76, -v130
	v_exp_f32_e32 v66, v66
	v_fma_f32 v67, v67, s76, -v130
	v_exp_f32_e32 v67, v67
	v_fma_f32 v68, v68, s76, -v130
	v_exp_f32_e32 v68, v68
	v_fma_f32 v69, v69, s76, -v130
	v_exp_f32_e32 v69, v69
	v_fma_f32 v70, v70, s76, -v130
	v_add_f32_e32 v133, 0, v66
	v_exp_f32_e32 v70, v70
	v_fma_f32 v71, v71, s76, -v130
	v_add_f32_e32 v133, v67, v133
	v_exp_f32_e32 v71, v71
	v_fma_f32 v72, v72, s76, -v130
	v_add_f32_e32 v133, v68, v133
	v_exp_f32_e32 v72, v72
	v_fma_f32 v73, v73, s76, -v130
	v_add_f32_e32 v133, v69, v133
	v_exp_f32_e32 v73, v73
	v_fma_f32 v74, v74, s76, -v130
	v_add_f32_e32 v133, v70, v133
	v_exp_f32_e32 v134, v74
	v_add_f32_e32 v133, v71, v133
	v_add_f32_e32 v133, v72, v133
	v_add_f32_e32 v133, v73, v133
	v_fma_f32 v75, v75, s76, -v130
	v_add_f32_e32 v74, v134, v133
	v_exp_f32_e32 v133, v75
	v_fma_f32 v75, v76, s76, -v130
	v_exp_f32_e32 v135, v75
	v_fma_f32 v75, v77, s76, -v130
	v_exp_f32_e32 v136, v75
	v_fma_f32 v75, v78, s76, -v130
	v_exp_f32_e32 v137, v75
	v_fma_f32 v75, v79, s76, -v130
	v_add_f32_e32 v74, v133, v74
	v_exp_f32_e32 v138, v75
	v_fma_f32 v75, v80, s76, -v130
	v_add_f32_e32 v74, v135, v74
	v_exp_f32_e32 v139, v75
	v_fma_f32 v75, v81, s76, -v130
	v_add_f32_e32 v74, v136, v74
	v_exp_f32_e32 v140, v75
	v_fma_f32 v75, v82, s76, -v130
	v_add_f32_e32 v74, v137, v74
	v_exp_f32_e32 v141, v75
	v_fma_f32 v75, v83, s76, -v130
	v_add_f32_e32 v74, v138, v74
	v_exp_f32_e32 v145, v75
	v_fma_f32 v75, v84, s76, -v130
	v_add_f32_e32 v74, v139, v74
	v_exp_f32_e32 v154, v75
	v_fma_f32 v75, v85, s76, -v130
	v_add_f32_e32 v74, v140, v74
	v_exp_f32_e32 v155, v75
	v_fma_f32 v75, v86, s76, -v130
	v_add_f32_e32 v74, v141, v74
	v_exp_f32_e32 v156, v75
	v_fma_f32 v75, v87, s76, -v130
	v_add_f32_e32 v74, v145, v74
	v_exp_f32_e32 v157, v75
	v_fma_f32 v75, v88, s76, -v130
	v_add_f32_e32 v74, v154, v74
	v_exp_f32_e32 v158, v75
	v_fma_f32 v75, v89, s76, -v130
	v_add_f32_e32 v74, v155, v74
	v_exp_f32_e32 v159, v75
	v_fma_f32 v75, v90, s76, -v130
	v_add_f32_e32 v74, v156, v74
	v_exp_f32_e32 v160, v75
	v_fma_f32 v75, v91, s76, -v130
	v_add_f32_e32 v74, v157, v74
	v_exp_f32_e32 v161, v75
	v_fma_f32 v75, v92, s76, -v130
	v_add_f32_e32 v74, v158, v74
	v_exp_f32_e32 v162, v75
	v_fma_f32 v75, v93, s76, -v130
	v_add_f32_e32 v74, v159, v74
	v_exp_f32_e32 v163, v75
	v_fma_f32 v75, v94, s76, -v130
	v_add_f32_e32 v74, v160, v74
	v_exp_f32_e32 v184, v75
	v_fma_f32 v75, v95, s76, -v130
	v_add_f32_e32 v74, v161, v74
	v_exp_f32_e32 v185, v75
	v_fma_f32 v75, v96, s76, -v130
	v_add_f32_e32 v74, v162, v74
	v_exp_f32_e32 v186, v75
	v_fma_f32 v75, v97, s76, -v130
	v_add_f32_e32 v74, v163, v74
	v_exp_f32_e32 v187, v75
	v_fma_f32 v75, v98, s76, -v130
	v_add_f32_e32 v74, v184, v74
	v_exp_f32_e32 v188, v75
	v_fma_f32 v75, v99, s76, -v130
	v_add_f32_e32 v74, v185, v74
	v_exp_f32_e32 v189, v75
	v_fma_f32 v75, v100, s76, -v130
	v_add_f32_e32 v74, v186, v74
	v_exp_f32_e32 v190, v75
	v_fma_f32 v75, v101, s76, -v130
	v_add_f32_e32 v74, v187, v74
	v_exp_f32_e32 v191, v75
	v_fma_f32 v75, v102, s76, -v130
	v_add_f32_e32 v74, v188, v74
	v_exp_f32_e32 v192, v75
	v_fma_f32 v75, v103, s76, -v130
	v_add_f32_e32 v74, v189, v74
	v_exp_f32_e32 v193, v75
	v_fma_f32 v75, v104, s76, -v130
	v_add_f32_e32 v74, v190, v74
	v_exp_f32_e32 v194, v75
	v_fma_f32 v75, v105, s76, -v130
	v_add_f32_e32 v74, v191, v74
	v_exp_f32_e32 v195, v75
	v_fma_f32 v75, v106, s76, -v130
	v_add_f32_e32 v74, v192, v74
	v_exp_f32_e32 v106, v75
	v_fma_f32 v75, v107, s76, -v130
	v_add_f32_e32 v74, v193, v74
	v_exp_f32_e32 v107, v75
; #define LAS __attribute__((address_space(3)))
; __device__ __forceinline__ unsigned cvt_pk_bf16(float lo, float hi) { const f32x2_t v = {lo, hi}; const bf16x2_t b = __builtin_convertvector(v, bf16x2_t); return __builtin_bit_cast(unsigned, b); }
; __device__ __forceinline__ void ca_block(bf16_t* PB, const bf16_t* KV, const bf16_t* VT, int b, int hh, int q256, LAS unsigned char* lds, int tid, u32x4 (&pk)[8], u32x4 (&pv)[8], bool have, int nx) {
;     ...
;         sum += __shfl_xor(sum, 16); sum += __shfl_xor(sum, 32);
;         const float inv = 1.0f / sum;
;         f32x4 O[8];
; #pragma unroll
;         for (int dt = 0; dt < 8; ++dt) O[dt] = (f32x4){0.f, 0.f, 0.f, 0.f};
; #pragma unroll
;         for (int kc8 = 0; kc8 < 8; ++kc8) {
;             u32x4 pw; pw.x = cvt_pk_bf16(S[2 * kc8][0], S[2 * kc8][1]); pw.y = cvt_pk_bf16(S[2 * kc8][2], S[2 * kc8][3]);
;             pw.z = cvt_pk_bf16(S[2 * kc8 + 1][0], S[2 * kc8 + 1][1]); pw.w = cvt_pk_bf16(S[2 * kc8 + 1][2], S[2 * kc8 + 1][3]);
;             const bf16x8 pb = __builtin_bit_cast(bf16x8, pw);
; #pragma unroll
;             for (int dt = 0; dt < 8; ++dt) { const bf16x8 vf = *(const LAS bf16x8*)(Vs + (16 * dt + c15) * 528 + (32 * kc8 + 8 * g) * 2); O[dt] = __builtin_amdgcn_mfma_f32_16x16x32_bf16(vf, pb, O[dt], 0, 0, 0); }
;             asm volatile("" ::: "memory");
	v_fma_f32 v75, v108, s76, -v130
	v_add_f32_e32 v74, v194, v74
	v_exp_f32_e32 v108, v75
	v_fma_f32 v75, v109, s76, -v130
	v_add_f32_e32 v74, v195, v74
	v_exp_f32_e32 v109, v75
	v_fma_f32 v75, v110, s76, -v130
	v_add_f32_e32 v74, v106, v74
	v_exp_f32_e32 v110, v75
	v_fma_f32 v75, v111, s76, -v130
	v_add_f32_e32 v74, v107, v74
	v_exp_f32_e32 v111, v75
	v_fma_f32 v75, v112, s76, -v130
	v_add_f32_e32 v74, v108, v74
	v_exp_f32_e32 v112, v75
	v_fma_f32 v75, v113, s76, -v130
	v_add_f32_e32 v74, v109, v74
	v_exp_f32_e32 v113, v75
	v_fma_f32 v75, v114, s76, -v130
	v_add_f32_e32 v74, v110, v74
	v_exp_f32_e32 v114, v75
	v_fma_f32 v75, v115, s76, -v130
	v_add_f32_e32 v74, v111, v74
	v_exp_f32_e32 v115, v75
	v_fma_f32 v75, v116, s76, -v130
	v_add_f32_e32 v74, v112, v74
	v_exp_f32_e32 v116, v75
	v_fma_f32 v75, v117, s76, -v130
	v_add_f32_e32 v74, v113, v74
	v_exp_f32_e32 v117, v75
	v_fma_f32 v75, v118, s76, -v130
	v_add_f32_e32 v74, v114, v74
	v_exp_f32_e32 v118, v75
	v_fma_f32 v75, v119, s76, -v130
	v_add_f32_e32 v74, v115, v74
	v_exp_f32_e32 v119, v75
	v_fma_f32 v75, v120, s76, -v130
	v_add_f32_e32 v74, v116, v74
	v_exp_f32_e32 v120, v75
	v_fma_f32 v75, v121, s76, -v130
	v_add_f32_e32 v74, v117, v74
	v_exp_f32_e32 v121, v75
	v_fma_f32 v75, v122, s76, -v130
	v_add_f32_e32 v74, v118, v74
	v_exp_f32_e32 v122, v75
	v_fma_f32 v75, v123, s76, -v130
	v_add_f32_e32 v74, v119, v74
	v_exp_f32_e32 v123, v75
	v_fma_f32 v75, v124, s76, -v130
	v_add_f32_e32 v74, v120, v74
	v_exp_f32_e32 v124, v75
	v_fma_f32 v75, v125, s76, -v130
	v_add_f32_e32 v74, v121, v74
	v_exp_f32_e32 v125, v75
	v_fma_f32 v75, v126, s76, -v130
	v_add_f32_e32 v74, v122, v74
	v_exp_f32_e32 v126, v75
	v_fma_f32 v75, v127, s76, -v130
	v_add_f32_e32 v74, v123, v74
	v_exp_f32_e32 v127, v75
	v_fma_f32 v75, v128, s76, -v130
	v_add_f32_e32 v74, v124, v74
	v_exp_f32_e32 v128, v75
	v_fma_f32 v75, v129, s76, -v130
	v_add_f32_e32 v74, v125, v74
	v_exp_f32_e32 v129, v75
	v_add_f32_e32 v74, v126, v74
	v_add_f32_e32 v74, v127, v74
	v_add_f32_e32 v74, v128, v74
	v_add_f32_e32 v74, v129, v74
	ds_bpermute_b32 v75, v131, v74
	v_cvt_pk_bf16_f32 v98, v66, v67
	v_cvt_pk_bf16_f32 v99, v68, v69
	v_cvt_pk_bf16_f32 v100, v70, v71
	v_cvt_pk_bf16_f32 v101, v72, v73
	s_waitcnt lgkmcnt(0)
	v_add_f32_e32 v74, v74, v75
	ds_bpermute_b32 v75, v132, v74
	ds_read_b128 v[196:199], v153
	ds_read_b128 v[200:203], v153 offset:8448
	ds_read_b128 v[204:207], v153 offset:16896
	ds_read_b128 v[208:211], v153 offset:25344
	ds_read_b128 v[212:215], v153 offset:33792
	ds_read_b128 v[216:219], v153 offset:42240
	ds_read_b128 v[220:223], v153 offset:50688
	s_waitcnt lgkmcnt(7)
	v_add_f32_e32 v130, v74, v75
	s_waitcnt lgkmcnt(6)
	v_mfma_f32_16x16x32_bf16 v[94:97], v[196:199], v[98:101], 0
	ds_read_b128 v[196:199], v153 offset:59136
	s_waitcnt lgkmcnt(6)
	v_mfma_f32_16x16x32_bf16 v[90:93], v[200:203], v[98:101], 0
	ds_read_b128 v[200:203], v153 offset:64
	s_waitcnt lgkmcnt(6)
	v_mfma_f32_16x16x32_bf16 v[86:89], v[204:207], v[98:101], 0
	ds_read_b128 v[204:207], v153 offset:8512
	s_waitcnt lgkmcnt(6)
	v_mfma_f32_16x16x32_bf16 v[82:85], v[208:211], v[98:101], 0
	ds_read_b128 v[208:211], v153 offset:16960
	s_waitcnt lgkmcnt(6)
	v_mfma_f32_16x16x32_bf16 v[78:81], v[212:215], v[98:101], 0
	ds_read_b128 v[212:215], v153 offset:25408
	s_waitcnt lgkmcnt(6)
	v_mfma_f32_16x16x32_bf16 v[74:77], v[216:219], v[98:101], 0
	ds_read_b128 v[216:219], v153 offset:33856
	s_waitcnt lgkmcnt(6)
	v_mfma_f32_16x16x32_bf16 v[70:73], v[220:223], v[98:101], 0
	ds_read_b128 v[220:223], v153 offset:42304
	s_waitcnt lgkmcnt(6)
	v_mfma_f32_16x16x32_bf16 v[66:69], v[196:199], v[98:101], 0
	ds_read_b128 v[196:199], v153 offset:50752
	v_cvt_pk_bf16_f32 v98, v134, v133
	v_cvt_pk_bf16_f32 v99, v135, v136
	v_cvt_pk_bf16_f32 v100, v137, v138
	v_cvt_pk_bf16_f32 v101, v139, v140
	s_nop 1
	s_waitcnt lgkmcnt(6)
	v_mfma_f32_16x16x32_bf16 v[94:97], v[200:203], v[98:101], v[94:97]
	ds_read_b128 v[200:203], v153 offset:59200
	s_waitcnt lgkmcnt(6)
	v_mfma_f32_16x16x32_bf16 v[90:93], v[204:207], v[98:101], v[90:93]
	ds_read_b128 v[204:207], v153 offset:128
	s_waitcnt lgkmcnt(6)
	v_mfma_f32_16x16x32_bf16 v[86:89], v[208:211], v[98:101], v[86:89]
	ds_read_b128 v[208:211], v153 offset:8576
	s_waitcnt lgkmcnt(6)
	v_mfma_f32_16x16x32_bf16 v[82:85], v[212:215], v[98:101], v[82:85]
	ds_read_b128 v[212:215], v153 offset:17024
	s_waitcnt lgkmcnt(6)
	v_mfma_f32_16x16x32_bf16 v[78:81], v[216:219], v[98:101], v[78:81]
	ds_read_b128 v[216:219], v153 offset:25472
	s_waitcnt lgkmcnt(6)
	v_mfma_f32_16x16x32_bf16 v[74:77], v[220:223], v[98:101], v[74:77]
	ds_read_b128 v[220:223], v153 offset:33920
	s_waitcnt lgkmcnt(6)
	v_mfma_f32_16x16x32_bf16 v[70:73], v[196:199], v[98:101], v[70:73]
	ds_read_b128 v[196:199], v153 offset:42368
	s_waitcnt lgkmcnt(6)
	v_mfma_f32_16x16x32_bf16 v[66:69], v[200:203], v[98:101], v[66:69]
	ds_read_b128 v[200:203], v153 offset:50816
	v_cvt_pk_bf16_f32 v98, v141, v145
	v_cvt_pk_bf16_f32 v99, v154, v155
	v_cvt_pk_bf16_f32 v100, v156, v157
	v_cvt_pk_bf16_f32 v101, v158, v159
	s_nop 1
	s_waitcnt lgkmcnt(6)
	v_mfma_f32_16x16x32_bf16 v[94:97], v[204:207], v[98:101], v[94:97]
	ds_read_b128 v[204:207], v153 offset:59264
	s_waitcnt lgkmcnt(6)
	v_mfma_f32_16x16x32_bf16 v[90:93], v[208:211], v[98:101], v[90:93]
	ds_read_b128 v[208:211], v153 offset:192
	s_waitcnt lgkmcnt(6)
	v_mfma_f32_16x16x32_bf16 v[86:89], v[212:215], v[98:101], v[86:89]
	ds_read_b128 v[212:215], v153 offset:8640
	s_waitcnt lgkmcnt(6)
	v_mfma_f32_16x16x32_bf16 v[82:85], v[216:219], v[98:101], v[82:85]
	ds_read_b128 v[216:219], v153 offset:17088
	s_waitcnt lgkmcnt(6)
; #define LAS __attribute__((address_space(3)))
; __device__ __forceinline__ unsigned cvt_pk_bf16(float lo, float hi) { const f32x2_t v = {lo, hi}; const bf16x2_t b = __builtin_convertvector(v, bf16x2_t); return __builtin_bit_cast(unsigned, b); }
; __device__ __forceinline__ void ca_block(bf16_t* PB, const bf16_t* KV, const bf16_t* VT, int b, int hh, int q256, LAS unsigned char* lds, int tid, u32x4 (&pk)[8], u32x4 (&pv)[8], bool have, int nx) {
;     ...
; #pragma unroll
;         for (int kc8 = 0; kc8 < 8; ++kc8) {
;             u32x4 pw; pw.x = cvt_pk_bf16(S[2 * kc8][0], S[2 * kc8][1]); pw.y = cvt_pk_bf16(S[2 * kc8][2], S[2 * kc8][3]);
;             pw.z = cvt_pk_bf16(S[2 * kc8 + 1][0], S[2 * kc8 + 1][1]); pw.w = cvt_pk_bf16(S[2 * kc8 + 1][2], S[2 * kc8 + 1][3]);
;             const bf16x8 pb = __builtin_bit_cast(bf16x8, pw);
; #pragma unroll
;             for (int dt = 0; dt < 8; ++dt) { const bf16x8 vf = *(const LAS bf16x8*)(Vs + (16 * dt + c15) * 528 + (32 * kc8 + 8 * g) * 2); O[dt] = __builtin_amdgcn_mfma_f32_16x16x32_bf16(vf, pb, O[dt], 0, 0, 0); }
;             asm volatile("" ::: "memory");
	v_mfma_f32_16x16x32_bf16 v[78:81], v[220:223], v[98:101], v[78:81]
	ds_read_b128 v[220:223], v153 offset:25536
	s_waitcnt lgkmcnt(6)
	v_mfma_f32_16x16x32_bf16 v[74:77], v[196:199], v[98:101], v[74:77]
	ds_read_b128 v[196:199], v153 offset:33984
	s_waitcnt lgkmcnt(6)
	v_mfma_f32_16x16x32_bf16 v[70:73], v[200:203], v[98:101], v[70:73]
	ds_read_b128 v[200:203], v153 offset:42432
	s_waitcnt lgkmcnt(6)
	v_mfma_f32_16x16x32_bf16 v[66:69], v[204:207], v[98:101], v[66:69]
	ds_read_b128 v[204:207], v153 offset:50880
	v_cvt_pk_bf16_f32 v98, v160, v161
	v_cvt_pk_bf16_f32 v99, v162, v163
	v_cvt_pk_bf16_f32 v100, v184, v185
	v_cvt_pk_bf16_f32 v101, v186, v187
	s_nop 1
	s_waitcnt lgkmcnt(6)
	v_mfma_f32_16x16x32_bf16 v[94:97], v[208:211], v[98:101], v[94:97]
	ds_read_b128 v[208:211], v153 offset:59328
	s_waitcnt lgkmcnt(6)
	v_mfma_f32_16x16x32_bf16 v[90:93], v[212:215], v[98:101], v[90:93]
	ds_read_b128 v[212:215], v153 offset:256
	s_waitcnt lgkmcnt(6)
	v_mfma_f32_16x16x32_bf16 v[86:89], v[216:219], v[98:101], v[86:89]
	ds_read_b128 v[216:219], v153 offset:8704
	s_waitcnt lgkmcnt(6)
	v_mfma_f32_16x16x32_bf16 v[82:85], v[220:223], v[98:101], v[82:85]
	ds_read_b128 v[220:223], v153 offset:17152
	s_waitcnt lgkmcnt(6)
	v_mfma_f32_16x16x32_bf16 v[78:81], v[196:199], v[98:101], v[78:81]
	ds_read_b128 v[196:199], v153 offset:25600
	s_waitcnt lgkmcnt(6)
	v_mfma_f32_16x16x32_bf16 v[74:77], v[200:203], v[98:101], v[74:77]
	ds_read_b128 v[200:203], v153 offset:34048
	s_waitcnt lgkmcnt(6)
	v_mfma_f32_16x16x32_bf16 v[70:73], v[204:207], v[98:101], v[70:73]
	ds_read_b128 v[204:207], v153 offset:42496
	s_waitcnt lgkmcnt(6)
	v_mfma_f32_16x16x32_bf16 v[66:69], v[208:211], v[98:101], v[66:69]
	ds_read_b128 v[208:211], v153 offset:50944
	v_cvt_pk_bf16_f32 v98, v188, v189
	v_cvt_pk_bf16_f32 v99, v190, v191
	v_cvt_pk_bf16_f32 v100, v192, v193
	v_cvt_pk_bf16_f32 v101, v194, v195
	s_nop 1
	s_waitcnt lgkmcnt(6)
	v_mfma_f32_16x16x32_bf16 v[94:97], v[212:215], v[98:101], v[94:97]
	ds_read_b128 v[212:215], v153 offset:59392
	s_waitcnt lgkmcnt(6)
	v_mfma_f32_16x16x32_bf16 v[90:93], v[216:219], v[98:101], v[90:93]
	ds_read_b128 v[216:219], v153 offset:320
	s_waitcnt lgkmcnt(6)
	v_mfma_f32_16x16x32_bf16 v[86:89], v[220:223], v[98:101], v[86:89]
	ds_read_b128 v[220:223], v153 offset:8768
	s_waitcnt lgkmcnt(6)
	v_mfma_f32_16x16x32_bf16 v[82:85], v[196:199], v[98:101], v[82:85]
	ds_read_b128 v[196:199], v153 offset:17216
	s_waitcnt lgkmcnt(6)
	v_mfma_f32_16x16x32_bf16 v[78:81], v[200:203], v[98:101], v[78:81]
	ds_read_b128 v[200:203], v153 offset:25664
	s_waitcnt lgkmcnt(6)
	v_mfma_f32_16x16x32_bf16 v[74:77], v[204:207], v[98:101], v[74:77]
	ds_read_b128 v[204:207], v153 offset:34112
	s_waitcnt lgkmcnt(6)
	v_mfma_f32_16x16x32_bf16 v[70:73], v[208:211], v[98:101], v[70:73]
	ds_read_b128 v[208:211], v153 offset:42560
	s_waitcnt lgkmcnt(6)
	v_mfma_f32_16x16x32_bf16 v[66:69], v[212:215], v[98:101], v[66:69]
	ds_read_b128 v[212:215], v153 offset:51008
	v_cvt_pk_bf16_f32 v98, v106, v107
	v_cvt_pk_bf16_f32 v99, v108, v109
	v_cvt_pk_bf16_f32 v100, v110, v111
	v_cvt_pk_bf16_f32 v101, v112, v113
	s_nop 1
	s_waitcnt lgkmcnt(6)
	v_mfma_f32_16x16x32_bf16 v[94:97], v[216:219], v[98:101], v[94:97]
	ds_read_b128 v[216:219], v153 offset:59456
	s_waitcnt lgkmcnt(6)
	v_mfma_f32_16x16x32_bf16 v[90:93], v[220:223], v[98:101], v[90:93]
	ds_read_b128 v[220:223], v153 offset:384
	s_waitcnt lgkmcnt(6)
	v_mfma_f32_16x16x32_bf16 v[86:89], v[196:199], v[98:101], v[86:89]
	ds_read_b128 v[196:199], v153 offset:8832
	s_waitcnt lgkmcnt(6)
	v_mfma_f32_16x16x32_bf16 v[82:85], v[200:203], v[98:101], v[82:85]
	ds_read_b128 v[200:203], v153 offset:17280
	s_waitcnt lgkmcnt(6)
	v_mfma_f32_16x16x32_bf16 v[78:81], v[204:207], v[98:101], v[78:81]
	ds_read_b128 v[204:207], v153 offset:25728
	s_waitcnt lgkmcnt(6)
	v_mfma_f32_16x16x32_bf16 v[74:77], v[208:211], v[98:101], v[74:77]
	ds_read_b128 v[208:211], v153 offset:34176
	s_waitcnt lgkmcnt(6)
	v_mfma_f32_16x16x32_bf16 v[70:73], v[212:215], v[98:101], v[70:73]
	ds_read_b128 v[212:215], v153 offset:42624
	s_waitcnt lgkmcnt(6)
	v_mfma_f32_16x16x32_bf16 v[66:69], v[216:219], v[98:101], v[66:69]
	ds_read_b128 v[216:219], v153 offset:51072
	v_cvt_pk_bf16_f32 v98, v114, v115
	v_cvt_pk_bf16_f32 v99, v116, v117
	v_cvt_pk_bf16_f32 v100, v118, v119
	v_cvt_pk_bf16_f32 v101, v120, v121
	s_nop 1
	s_waitcnt lgkmcnt(6)
	v_mfma_f32_16x16x32_bf16 v[94:97], v[220:223], v[98:101], v[94:97]
	ds_read_b128 v[220:223], v153 offset:59520
	s_waitcnt lgkmcnt(6)
; #define LAS __attribute__((address_space(3)))
; __device__ __forceinline__ unsigned cvt_pk_bf16(float lo, float hi) { const f32x2_t v = {lo, hi}; const bf16x2_t b = __builtin_convertvector(v, bf16x2_t); return __builtin_bit_cast(unsigned, b); }
; __device__ __forceinline__ void ca_block(bf16_t* PB, const bf16_t* KV, const bf16_t* VT, int b, int hh, int q256, LAS unsigned char* lds, int tid, u32x4 (&pk)[8], u32x4 (&pv)[8], bool have, int nx) {
;     ...
;         for (int kc8 = 0; kc8 < 8; ++kc8) {
;             u32x4 pw; pw.x = cvt_pk_bf16(S[2 * kc8][0], S[2 * kc8][1]); pw.y = cvt_pk_bf16(S[2 * kc8][2], S[2 * kc8][3]);
;             pw.z = cvt_pk_bf16(S[2 * kc8 + 1][0], S[2 * kc8 + 1][1]); pw.w = cvt_pk_bf16(S[2 * kc8 + 1][2], S[2 * kc8 + 1][3]);
;             const bf16x8 pb = __builtin_bit_cast(bf16x8, pw);
; #pragma unroll
;             for (int dt = 0; dt < 8; ++dt) { const bf16x8 vf = *(const LAS bf16x8*)(Vs + (16 * dt + c15) * 528 + (32 * kc8 + 8 * g) * 2); O[dt] = __builtin_amdgcn_mfma_f32_16x16x32_bf16(vf, pb, O[dt], 0, 0, 0); }
;             asm volatile("" ::: "memory");
;         }
; #pragma unroll
;         for (int dt = 0; dt < 8; ++dt) { u32x2 wv; wv.x = cvt_pk_bf16(O[dt][0] * inv, O[dt][1] * inv); wv.y = cvt_pk_bf16(O[dt][2] * inv, O[dt][3] * inv);
;             *(u32x2*)(qp + 16 * dt + 4 * g) = wv; }
;     }
	v_mfma_f32_16x16x32_bf16 v[90:93], v[196:199], v[98:101], v[90:93]
	ds_read_b128 v[196:199], v153 offset:448
	s_waitcnt lgkmcnt(6)
	v_mfma_f32_16x16x32_bf16 v[86:89], v[200:203], v[98:101], v[86:89]
	ds_read_b128 v[200:203], v153 offset:8896
	s_waitcnt lgkmcnt(6)
	v_mfma_f32_16x16x32_bf16 v[82:85], v[204:207], v[98:101], v[82:85]
	ds_read_b128 v[204:207], v153 offset:17344
	s_waitcnt lgkmcnt(6)
	v_mfma_f32_16x16x32_bf16 v[78:81], v[208:211], v[98:101], v[78:81]
	ds_read_b128 v[208:211], v153 offset:25792
	s_waitcnt lgkmcnt(6)
	v_mfma_f32_16x16x32_bf16 v[74:77], v[212:215], v[98:101], v[74:77]
	ds_read_b128 v[212:215], v153 offset:34240
	s_waitcnt lgkmcnt(6)
	v_mfma_f32_16x16x32_bf16 v[70:73], v[216:219], v[98:101], v[70:73]
	ds_read_b128 v[216:219], v153 offset:42688
	s_waitcnt lgkmcnt(6)
	v_mfma_f32_16x16x32_bf16 v[66:69], v[220:223], v[98:101], v[66:69]
	ds_read_b128 v[220:223], v153 offset:51136
	v_cvt_pk_bf16_f32 v98, v122, v123
	v_cvt_pk_bf16_f32 v99, v124, v125
	v_cvt_pk_bf16_f32 v100, v126, v127
	v_cvt_pk_bf16_f32 v101, v128, v129
	s_nop 1
	s_waitcnt lgkmcnt(6)
	v_mfma_f32_16x16x32_bf16 v[94:97], v[196:199], v[98:101], v[94:97]
	ds_read_b128 v[196:199], v153 offset:59584
	s_waitcnt lgkmcnt(6)
	v_mfma_f32_16x16x32_bf16 v[90:93], v[200:203], v[98:101], v[90:93]
	s_waitcnt lgkmcnt(5)
	v_mfma_f32_16x16x32_bf16 v[86:89], v[204:207], v[98:101], v[86:89]
	s_waitcnt lgkmcnt(4)
	v_mfma_f32_16x16x32_bf16 v[82:85], v[208:211], v[98:101], v[82:85]
	s_waitcnt lgkmcnt(3)
	v_mfma_f32_16x16x32_bf16 v[78:81], v[212:215], v[98:101], v[78:81]
	s_waitcnt lgkmcnt(2)
	v_mfma_f32_16x16x32_bf16 v[74:77], v[216:219], v[98:101], v[74:77]
	s_waitcnt lgkmcnt(1)
	v_mfma_f32_16x16x32_bf16 v[70:73], v[220:223], v[98:101], v[70:73]
	s_waitcnt lgkmcnt(0)
	v_mfma_f32_16x16x32_bf16 v[66:69], v[196:199], v[98:101], v[66:69]
	v_mov_b32_e32 v145, v1
	v_div_scale_f32 v98, s[2:3], v130, v130, 1.0
	v_rcp_f32_e32 v99, v98
	s_movk_i32 s2, 0x80
	v_fma_f32 v100, -v98, v99, 1.0
	v_fmac_f32_e32 v99, v100, v99
	v_div_scale_f32 v100, vcc, 1.0, v130, 1.0
	v_mul_f32_e32 v101, v100, v99
	v_fma_f32 v102, -v98, v101, v100
	v_fmac_f32_e32 v101, v102, v99
	v_fma_f32 v98, -v98, v101, v100
	v_div_fmas_f32 v98, v98, v99, v101
	v_div_fixup_f32 v98, v98, v130, 1.0
	v_pk_mul_f32 v[94:95], v[98:99], v[94:95] op_sel_hi:[0,1]
	v_pk_mul_f32 v[96:97], v[98:99], v[96:97] op_sel_hi:[0,1]
	v_pk_mul_f32 v[90:91], v[98:99], v[90:91] op_sel_hi:[0,1]
	v_pk_mul_f32 v[92:93], v[98:99], v[92:93] op_sel_hi:[0,1]
	v_pk_mul_f32 v[86:87], v[98:99], v[86:87] op_sel_hi:[0,1]
	v_pk_mul_f32 v[88:89], v[98:99], v[88:89] op_sel_hi:[0,1]
	v_pk_mul_f32 v[82:83], v[98:99], v[82:83] op_sel_hi:[0,1]
	v_pk_mul_f32 v[84:85], v[98:99], v[84:85] op_sel_hi:[0,1]
	v_pk_mul_f32 v[78:79], v[98:99], v[78:79] op_sel_hi:[0,1]
	v_pk_mul_f32 v[80:81], v[98:99], v[80:81] op_sel_hi:[0,1]
	v_pk_mul_f32 v[74:75], v[98:99], v[74:75] op_sel_hi:[0,1]
	v_pk_mul_f32 v[76:77], v[98:99], v[76:77] op_sel_hi:[0,1]
	v_pk_mul_f32 v[70:71], v[98:99], v[70:71] op_sel_hi:[0,1]
	v_pk_mul_f32 v[72:73], v[98:99], v[72:73] op_sel_hi:[0,1]
	v_pk_mul_f32 v[66:67], v[98:99], v[66:67] op_sel_hi:[0,1]
	v_pk_mul_f32 v[68:69], v[98:99], v[68:69] op_sel_hi:[0,1]
	v_lshl_add_u64 v[100:101], v[150:151], 0, v[144:145]
	v_cvt_pk_bf16_f32 v94, v94, v95
	v_cvt_pk_bf16_f32 v95, v96, v97
	v_cvt_pk_bf16_f32 v90, v90, v91
	v_cvt_pk_bf16_f32 v91, v92, v93
	v_cvt_pk_bf16_f32 v86, v86, v87
	v_cvt_pk_bf16_f32 v87, v88, v89
	v_cvt_pk_bf16_f32 v82, v82, v83
	v_cvt_pk_bf16_f32 v83, v84, v85
	v_cvt_pk_bf16_f32 v78, v78, v79
	v_cvt_pk_bf16_f32 v79, v80, v81
	v_cvt_pk_bf16_f32 v74, v74, v75
	v_cvt_pk_bf16_f32 v75, v76, v77
	v_cvt_pk_bf16_f32 v70, v70, v71
	v_cvt_pk_bf16_f32 v71, v72, v73
	v_cvt_pk_bf16_f32 v66, v66, v67
	v_cvt_pk_bf16_f32 v67, v68, v69
	s_and_b64 vcc, exec, s[42:43]
	s_mov_b64 s[42:43], 0
	global_store_dwordx2 v[100:101], v[94:95], off
	global_store_dwordx2 v[100:101], v[90:91], off offset:32
	global_store_dwordx2 v[100:101], v[86:87], off offset:64
	global_store_dwordx2 v[100:101], v[82:83], off offset:96
	global_store_dwordx2 v[100:101], v[78:79], off offset:128
	global_store_dwordx2 v[100:101], v[74:75], off offset:160
	global_store_dwordx2 v[100:101], v[70:71], off offset:192
	global_store_dwordx2 v[100:101], v[66:67], off offset:224
	s_cbranch_vccnz .LBB0_946
	s_andn2_b64 vcc, exec, s[40:41]
	s_mov_b32 s16, s6
	s_cbranch_vccnz .LBB0_939
